# GEMM K-loops: all 16 LDS-DMA loads per iteration use scalar-base addressing (chained +0x80 addresses via saved scalar bases); no per-iteration VALU address adds; on top of v36
# speedup vs baseline: 1.0117x; 1.0006x over previous
; #define PG8_STAGE(bufoff, gbase, voff) do { _Pragma("unroll") for (int _i = 0; _i < 2; ++_i) \
;         __builtin_amdgcn_global_load_lds((const unsigned*)((const char*)(gbase) + (voff)[_i]), (PG8_LAS unsigned*)(lds + (bufoff) + ldsw + _i * 8192), 16, 0, 0); } while (0)
; #define PG8_LDA(dst, b, h) do { _Pragma("unroll") for (int m = 0; m < 4; ++m) _Pragma("unroll") for (int k = 0; k < 2; ++k) dst[m][k] = *(const PG8_LAS bf16x8*)(lds + PG8_SA(b, h) + aoff + m * 2048 + k * 1024); } while (0)
; #define PG8_LDB(dst, b, h) do { _Pragma("unroll") for (int n = 0; n < 2; ++n) _Pragma("unroll") for (int k = 0; k < 2; ++k) dst[n][k] = *(const PG8_LAS bf16x8*)(lds + PG8_SB(b, h) + boff + n * 2048 + k * 1024); } while (0)
; #define PG8_MMA(ai, bj, At, Bt) do { __builtin_amdgcn_s_setprio(1); _Pragma("unroll") for (int m = 0; m < 4; ++m) _Pragma("unroll") for (int n = 0; n < 2; ++n) _Pragma("unroll") for (int k = 0; k < 2; ++k) \
;         acc[ai][bj][m][n] = __builtin_amdgcn_mfma_f32_16x16x32_bf16(Bt[n][k], At[m][k], acc[ai][bj][m][n], 0, 0, 0); __builtin_amdgcn_s_setprio(0); } while (0)
; #define PG8_WAIT_V(n) asm volatile("s_waitcnt vmcnt(" #n ")" ::: "memory")
; #define PG8_WAIT_L(n) asm volatile("s_waitcnt lgkmcnt(" #n ")" ::: "memory")
; #define PG8_BAR __builtin_amdgcn_s_barrier()
; #define PG8_SCHED __builtin_amdgcn_sched_barrier(0)
; template <class Epi, class Sched, bool ALIGN_EPI = false, bool SP2 = false>
; __device__ __forceinline__ void gemm_phase(PG8_LAS unsigned char* lds, const Gemm g, const Sched& S, const Epi& E) {
;     ...
;         for (int t = 0; t < nt; t += 2) {
;             const bool last = (t == nt - 2);
;             const char* a1 = cA + (size_t)(t + 1) * kstep;
;             const char* a2 = last ? nA : cA + (size_t)(t + 2) * kstep; const char* b2 = last ? nB : cB + (size_t)(t + 2) * kstep;
;             const char* a3 = a2 + kstep; const char* b3 = b2 + kstep;
;             if (last && has_next) S.a_ready(nxt);
;             if constexpr (SP2) {
;             PG8_LDB(B0, 0, 0); PG8_LDB(B1, 0, 1); PG8_SCHED; PG8_LDA(At, 0, 0); PG8_STAGE(PG8_SA(1, 1), a1 + hstepA, voffA);
;             PG8_WAIT_V(8); PG8_WAIT_L(0); PG8_BAR; PG8_MMA(0, 0, At, B0); PG8_MMA(0, 1, At, B1); PG8_BAR; PG8_SCHED;
;             PG8_LDA(At, 0, 1); PG8_STAGE(PG8_SB(0, 0), b2, voffB); PG8_STAGE(PG8_SB(0, 1), b2 + hstepB, voffB); PG8_STAGE(PG8_SA(0, 0), a2, voffA);
.LBB0_254:
	s_add_u32 s28, s26, 0xfffc0080
	s_addc_u32 s29, s27, -1
	s_add_i32 s53, 0, 0x10000
	s_cmp_eq_u32 s52, 12
	s_cselect_b32 s31, s7, s29
	s_cselect_b32 s30, s9, s28
	v_add_u32_e32 v150, s53, v153
	s_cselect_b32 s29, s19, s51
	s_cselect_b32 s28, s21, s50
	s_add_i32 s56, 0, 0x14000
	ds_read_b128 v[142:145], v150
	ds_read_b128 v[146:149], v150 offset:1024
	ds_read_b128 v[158:161], v150 offset:2048
	ds_read_b128 v[162:165], v150 offset:3072
	v_add_u32_e32 v150, s56, v153
	ds_read_b128 v[166:169], v150
	ds_read_b128 v[170:173], v150 offset:1024
	ds_read_b128 v[174:177], v150 offset:2048
	ds_read_b128 v[178:181], v150 offset:3072
	s_add_i32 m0, s40, 0xc000
	ds_read_b128 v[182:185], v156
	ds_read_b128 v[202:205], v156 offset:1024
	ds_read_b128 v[206:209], v156 offset:2048
	ds_read_b128 v[210:213], v156 offset:3072
	ds_read_b128 v[232:235], v156 offset:4096
	ds_read_b128 v[236:239], v156 offset:5120
	ds_read_b128 v[240:243], v156 offset:6144
	ds_read_b128 v[244:247], v156 offset:7168
	global_load_lds_dwordx4 v138, s[26:27]
	s_add_i32 m0, s40, 0xe000
	s_nop 0
	global_load_lds_dwordx4 v140, s[26:27]
	s_waitcnt vmcnt(8)
	s_waitcnt lgkmcnt(0)
	s_barrier
	s_setprio 1
	s_waitcnt lgkmcnt(0)
	v_mfma_f32_16x16x32_bf16 v[126:129], v[142:145], v[182:185], v[126:129]
	v_mfma_f32_16x16x32_bf16 v[122:125], v[158:161], v[182:185], v[122:125]
	v_mfma_f32_16x16x32_bf16 v[110:113], v[142:145], v[206:209], v[110:113]
	v_mfma_f32_16x16x32_bf16 v[106:109], v[158:161], v[206:209], v[106:109]
	v_mfma_f32_16x16x32_bf16 v[94:97], v[142:145], v[232:235], v[94:97]
	v_mfma_f32_16x16x32_bf16 v[90:93], v[158:161], v[232:235], v[90:93]
	v_mfma_f32_16x16x32_bf16 v[78:81], v[142:145], v[240:243], v[78:81]
	v_mfma_f32_16x16x32_bf16 v[74:77], v[158:161], v[240:243], v[74:77]
	v_mfma_f32_16x16x32_bf16 v[126:129], v[146:149], v[202:205], v[126:129]
	v_mfma_f32_16x16x32_bf16 v[122:125], v[162:165], v[202:205], v[122:125]
	v_mfma_f32_16x16x32_bf16 v[110:113], v[146:149], v[210:213], v[110:113]
	v_mfma_f32_16x16x32_bf16 v[106:109], v[162:165], v[210:213], v[106:109]
	v_mfma_f32_16x16x32_bf16 v[94:97], v[146:149], v[236:239], v[94:97]
	v_mfma_f32_16x16x32_bf16 v[90:93], v[162:165], v[236:239], v[90:93]
	v_mfma_f32_16x16x32_bf16 v[78:81], v[146:149], v[244:247], v[78:81]
	v_mfma_f32_16x16x32_bf16 v[74:77], v[162:165], v[244:247], v[74:77]
	s_setprio 0
	s_setprio 1
	v_mfma_f32_16x16x32_bf16 v[118:121], v[166:169], v[182:185], v[118:121]
	v_mfma_f32_16x16x32_bf16 v[114:117], v[174:177], v[182:185], v[114:117]
	v_mfma_f32_16x16x32_bf16 v[102:105], v[166:169], v[206:209], v[102:105]
	v_mfma_f32_16x16x32_bf16 v[98:101], v[174:177], v[206:209], v[98:101]
	v_mfma_f32_16x16x32_bf16 v[86:89], v[166:169], v[232:235], v[86:89]
	v_mfma_f32_16x16x32_bf16 v[82:85], v[174:177], v[232:235], v[82:85]
	v_mfma_f32_16x16x32_bf16 v[70:73], v[166:169], v[240:243], v[70:73]
	v_mfma_f32_16x16x32_bf16 v[66:69], v[174:177], v[240:243], v[66:69]
	v_mfma_f32_16x16x32_bf16 v[118:121], v[170:173], v[202:205], v[118:121]
	v_mfma_f32_16x16x32_bf16 v[114:117], v[178:181], v[202:205], v[114:117]
	v_mfma_f32_16x16x32_bf16 v[102:105], v[170:173], v[210:213], v[102:105]
	v_mfma_f32_16x16x32_bf16 v[98:101], v[178:181], v[210:213], v[98:101]
	v_mfma_f32_16x16x32_bf16 v[86:89], v[170:173], v[236:239], v[86:89]
	v_mfma_f32_16x16x32_bf16 v[82:85], v[178:181], v[236:239], v[82:85]
	v_mfma_f32_16x16x32_bf16 v[70:73], v[170:173], v[244:247], v[70:73]
	v_mfma_f32_16x16x32_bf16 v[66:69], v[178:181], v[244:247], v[66:69]
	s_setprio 0
	s_barrier
	s_add_i32 s53, s53, s39
	s_mov_b32 m0, s53
	ds_read_b128 v[182:185], v156 offset:16384
	ds_read_b128 v[202:205], v156 offset:17408
	ds_read_b128 v[206:209], v156 offset:18432
	ds_read_b128 v[210:213], v156 offset:19456
	ds_read_b128 v[232:235], v156 offset:20480
	ds_read_b128 v[236:239], v156 offset:21504
	ds_read_b128 v[240:243], v156 offset:22528
	ds_read_b128 v[244:247], v156 offset:23552
	s_add_u32 s60, s28, 0x80
	s_addc_u32 s61, s29, 0
	s_add_u32 s62, s30, 0x80
	s_addc_u32 s63, s31, 0
	global_load_lds_dwordx4 v132, s[28:29]
	s_add_i32 m0, s53, 0x2000
	s_add_u32 s54, s28, 0x40000
	s_addc_u32 s55, s29, 0
	s_add_i32 s53, s56, s39
	global_load_lds_dwordx4 v136, s[28:29]
	s_mov_b32 m0, s53
	s_nop 0
	global_load_lds_dwordx4 v132, s[54:55]
	s_add_i32 m0, s53, 0x2000
	s_nop 0
	global_load_lds_dwordx4 v136, s[54:55]
	s_mov_b32 m0, s40
	s_nop 0
	global_load_lds_dwordx4 v130, s[30:31]
	s_mov_b32 m0, s41
	s_nop 0
	global_load_lds_dwordx4 v134, s[30:31]
	s_waitcnt vmcnt(8)
	s_waitcnt lgkmcnt(0)
	s_barrier
; #define PG8_STAGE(bufoff, gbase, voff) do { _Pragma("unroll") for (int _i = 0; _i < 2; ++_i) \
;         __builtin_amdgcn_global_load_lds((const unsigned*)((const char*)(gbase) + (voff)[_i]), (PG8_LAS unsigned*)(lds + (bufoff) + ldsw + _i * 8192), 16, 0, 0); } while (0)
; #define PG8_LDA(dst, b, h) do { _Pragma("unroll") for (int m = 0; m < 4; ++m) _Pragma("unroll") for (int k = 0; k < 2; ++k) dst[m][k] = *(const PG8_LAS bf16x8*)(lds + PG8_SA(b, h) + aoff + m * 2048 + k * 1024); } while (0)
; #define PG8_LDB(dst, b, h) do { _Pragma("unroll") for (int n = 0; n < 2; ++n) _Pragma("unroll") for (int k = 0; k < 2; ++k) dst[n][k] = *(const PG8_LAS bf16x8*)(lds + PG8_SB(b, h) + boff + n * 2048 + k * 1024); } while (0)
; #define PG8_MMA(ai, bj, At, Bt) do { __builtin_amdgcn_s_setprio(1); _Pragma("unroll") for (int m = 0; m < 4; ++m) _Pragma("unroll") for (int n = 0; n < 2; ++n) _Pragma("unroll") for (int k = 0; k < 2; ++k) \
;         acc[ai][bj][m][n] = __builtin_amdgcn_mfma_f32_16x16x32_bf16(Bt[n][k], At[m][k], acc[ai][bj][m][n], 0, 0, 0); __builtin_amdgcn_s_setprio(0); } while (0)
; #define PG8_WAIT_V(n) asm volatile("s_waitcnt vmcnt(" #n ")" ::: "memory")
; #define PG8_WAIT_L(n) asm volatile("s_waitcnt lgkmcnt(" #n ")" ::: "memory")
; #define PG8_BAR __builtin_amdgcn_s_barrier()
; #define PG8_SCHED __builtin_amdgcn_sched_barrier(0)
; template <class Epi, class Sched, bool ALIGN_EPI = false, bool SP2 = false>
; __device__ __forceinline__ void gemm_phase(PG8_LAS unsigned char* lds, const Gemm g, const Sched& S, const Epi& E) {
;     ...
;             PG8_WAIT_V(8); PG8_WAIT_L(0); PG8_BAR; PG8_MMA(1, 0, At, B0); PG8_MMA(1, 1, At, B1); PG8_BAR; PG8_SCHED;
;             PG8_LDB(B0, 1, 0); PG8_LDB(B1, 1, 1); PG8_SCHED; PG8_LDA(At, 1, 0); PG8_STAGE(PG8_SA(0, 1), a2 + hstepA, voffA);
;             PG8_WAIT_V(8); PG8_WAIT_L(0); PG8_BAR; PG8_MMA(0, 0, At, B0); PG8_MMA(0, 1, At, B1); PG8_BAR; PG8_SCHED;
	s_setprio 1
	s_waitcnt lgkmcnt(0)
	v_mfma_f32_16x16x32_bf16 v[62:65], v[142:145], v[182:185], v[62:65]
	v_mfma_f32_16x16x32_bf16 v[58:61], v[158:161], v[182:185], v[58:61]
	v_mfma_f32_16x16x32_bf16 v[46:49], v[142:145], v[206:209], v[46:49]
	v_mfma_f32_16x16x32_bf16 v[42:45], v[158:161], v[206:209], v[42:45]
	v_mfma_f32_16x16x32_bf16 v[30:33], v[142:145], v[232:235], v[30:33]
	v_mfma_f32_16x16x32_bf16 v[26:29], v[158:161], v[232:235], v[26:29]
	v_mfma_f32_16x16x32_bf16 v[14:17], v[142:145], v[240:243], v[14:17]
	v_mfma_f32_16x16x32_bf16 v[10:13], v[158:161], v[240:243], v[10:13]
	v_mfma_f32_16x16x32_bf16 v[62:65], v[146:149], v[202:205], v[62:65]
	v_mfma_f32_16x16x32_bf16 v[58:61], v[162:165], v[202:205], v[58:61]
	v_mfma_f32_16x16x32_bf16 v[46:49], v[146:149], v[210:213], v[46:49]
	v_mfma_f32_16x16x32_bf16 v[42:45], v[162:165], v[210:213], v[42:45]
	v_mfma_f32_16x16x32_bf16 v[30:33], v[146:149], v[236:239], v[30:33]
	v_mfma_f32_16x16x32_bf16 v[26:29], v[162:165], v[236:239], v[26:29]
	v_mfma_f32_16x16x32_bf16 v[14:17], v[146:149], v[244:247], v[14:17]
	v_mfma_f32_16x16x32_bf16 v[10:13], v[162:165], v[244:247], v[10:13]
	s_setprio 0
	s_setprio 1
	v_mfma_f32_16x16x32_bf16 v[54:57], v[166:169], v[182:185], v[54:57]
	v_mfma_f32_16x16x32_bf16 v[50:53], v[174:177], v[182:185], v[50:53]
	v_mfma_f32_16x16x32_bf16 v[38:41], v[166:169], v[206:209], v[38:41]
	v_mfma_f32_16x16x32_bf16 v[34:37], v[174:177], v[206:209], v[34:37]
	v_mfma_f32_16x16x32_bf16 v[22:25], v[166:169], v[232:235], v[22:25]
	v_mfma_f32_16x16x32_bf16 v[18:21], v[174:177], v[232:235], v[18:21]
	v_mfma_f32_16x16x32_bf16 v[6:9], v[166:169], v[240:243], v[6:9]
	v_mfma_f32_16x16x32_bf16 v[2:5], v[174:177], v[240:243], v[2:5]
	v_mfma_f32_16x16x32_bf16 v[54:57], v[170:173], v[202:205], v[54:57]
	v_mfma_f32_16x16x32_bf16 v[50:53], v[178:181], v[202:205], v[50:53]
	v_mfma_f32_16x16x32_bf16 v[38:41], v[170:173], v[210:213], v[38:41]
	v_mfma_f32_16x16x32_bf16 v[34:37], v[178:181], v[210:213], v[34:37]
	v_mfma_f32_16x16x32_bf16 v[22:25], v[170:173], v[236:239], v[22:25]
	v_mfma_f32_16x16x32_bf16 v[18:21], v[178:181], v[236:239], v[18:21]
	v_mfma_f32_16x16x32_bf16 v[6:9], v[170:173], v[244:247], v[6:9]
	v_mfma_f32_16x16x32_bf16 v[2:5], v[178:181], v[244:247], v[2:5]
	s_setprio 0
	s_barrier
	s_add_i32 s53, 0, 0x18000
	v_add_u32_e32 v157, s53, v153
	s_add_i32 s54, 0, 0x1c000
	ds_read_b128 v[142:145], v157
	ds_read_b128 v[146:149], v157 offset:1024
	ds_read_b128 v[158:161], v157 offset:2048
	ds_read_b128 v[162:165], v157 offset:3072
	v_add_u32_e32 v157, s54, v153
	ds_read_b128 v[166:169], v157
	ds_read_b128 v[170:173], v157 offset:1024
	ds_read_b128 v[174:177], v157 offset:2048
	ds_read_b128 v[178:181], v157 offset:3072
	s_add_u32 s30, s30, 0x40000
	s_addc_u32 s31, s31, 0
	s_mov_b32 m0, s42
	ds_read_b128 v[182:185], v156 offset:32768
	ds_read_b128 v[202:205], v156 offset:33792
	ds_read_b128 v[206:209], v156 offset:34816
	ds_read_b128 v[210:213], v156 offset:35840
	ds_read_b128 v[232:235], v156 offset:36864
	ds_read_b128 v[236:239], v156 offset:37888
	ds_read_b128 v[240:243], v156 offset:38912
	ds_read_b128 v[244:247], v156 offset:39936
	global_load_lds_dwordx4 v130, s[30:31]
	s_mov_b32 m0, s43
	s_nop 0
	global_load_lds_dwordx4 v134, s[30:31]
	s_waitcnt vmcnt(8)
	s_waitcnt lgkmcnt(0)
	s_barrier
	s_setprio 1
	s_waitcnt lgkmcnt(0)
	v_mfma_f32_16x16x32_bf16 v[126:129], v[142:145], v[182:185], v[126:129]
	v_mfma_f32_16x16x32_bf16 v[122:125], v[158:161], v[182:185], v[122:125]
	v_mfma_f32_16x16x32_bf16 v[110:113], v[142:145], v[206:209], v[110:113]
	v_mfma_f32_16x16x32_bf16 v[106:109], v[158:161], v[206:209], v[106:109]
	v_mfma_f32_16x16x32_bf16 v[94:97], v[142:145], v[232:235], v[94:97]
	v_mfma_f32_16x16x32_bf16 v[90:93], v[158:161], v[232:235], v[90:93]
	v_mfma_f32_16x16x32_bf16 v[78:81], v[142:145], v[240:243], v[78:81]
	v_mfma_f32_16x16x32_bf16 v[74:77], v[158:161], v[240:243], v[74:77]
	v_mfma_f32_16x16x32_bf16 v[126:129], v[146:149], v[202:205], v[126:129]
	v_mfma_f32_16x16x32_bf16 v[122:125], v[162:165], v[202:205], v[122:125]
	v_mfma_f32_16x16x32_bf16 v[110:113], v[146:149], v[210:213], v[110:113]
	v_mfma_f32_16x16x32_bf16 v[106:109], v[162:165], v[210:213], v[106:109]
	v_mfma_f32_16x16x32_bf16 v[94:97], v[146:149], v[236:239], v[94:97]
	v_mfma_f32_16x16x32_bf16 v[90:93], v[162:165], v[236:239], v[90:93]
	v_mfma_f32_16x16x32_bf16 v[78:81], v[146:149], v[244:247], v[78:81]
	v_mfma_f32_16x16x32_bf16 v[74:77], v[162:165], v[244:247], v[74:77]
	s_setprio 0
	s_setprio 1
	v_mfma_f32_16x16x32_bf16 v[118:121], v[166:169], v[182:185], v[118:121]
	v_mfma_f32_16x16x32_bf16 v[114:117], v[174:177], v[182:185], v[114:117]
	v_mfma_f32_16x16x32_bf16 v[102:105], v[166:169], v[206:209], v[102:105]
	v_mfma_f32_16x16x32_bf16 v[98:101], v[174:177], v[206:209], v[98:101]
	v_mfma_f32_16x16x32_bf16 v[86:89], v[166:169], v[232:235], v[86:89]
	v_mfma_f32_16x16x32_bf16 v[82:85], v[174:177], v[232:235], v[82:85]
	v_mfma_f32_16x16x32_bf16 v[70:73], v[166:169], v[240:243], v[70:73]
	v_mfma_f32_16x16x32_bf16 v[66:69], v[174:177], v[240:243], v[66:69]
	v_mfma_f32_16x16x32_bf16 v[118:121], v[170:173], v[202:205], v[118:121]
	v_mfma_f32_16x16x32_bf16 v[114:117], v[178:181], v[202:205], v[114:117]
	v_mfma_f32_16x16x32_bf16 v[102:105], v[170:173], v[210:213], v[102:105]
	v_mfma_f32_16x16x32_bf16 v[98:101], v[178:181], v[210:213], v[98:101]
	v_mfma_f32_16x16x32_bf16 v[86:89], v[170:173], v[236:239], v[86:89]
	v_mfma_f32_16x16x32_bf16 v[82:85], v[178:181], v[236:239], v[82:85]
	v_mfma_f32_16x16x32_bf16 v[70:73], v[170:173], v[244:247], v[70:73]
	v_mfma_f32_16x16x32_bf16 v[66:69], v[178:181], v[244:247], v[66:69]
	s_setprio 0
	s_barrier
; #define PG8_STAGE(bufoff, gbase, voff) do { _Pragma("unroll") for (int _i = 0; _i < 2; ++_i) \
;         __builtin_amdgcn_global_load_lds((const unsigned*)((const char*)(gbase) + (voff)[_i]), (PG8_LAS unsigned*)(lds + (bufoff) + ldsw + _i * 8192), 16, 0, 0); } while (0)
; #define PG8_LDA(dst, b, h) do { _Pragma("unroll") for (int m = 0; m < 4; ++m) _Pragma("unroll") for (int k = 0; k < 2; ++k) dst[m][k] = *(const PG8_LAS bf16x8*)(lds + PG8_SA(b, h) + aoff + m * 2048 + k * 1024); } while (0)
; #define PG8_MMA(ai, bj, At, Bt) do { __builtin_amdgcn_s_setprio(1); _Pragma("unroll") for (int m = 0; m < 4; ++m) _Pragma("unroll") for (int n = 0; n < 2; ++n) _Pragma("unroll") for (int k = 0; k < 2; ++k) \
;         acc[ai][bj][m][n] = __builtin_amdgcn_mfma_f32_16x16x32_bf16(Bt[n][k], At[m][k], acc[ai][bj][m][n], 0, 0, 0); __builtin_amdgcn_s_setprio(0); } while (0)
; #define PG8_WAIT_V(n) asm volatile("s_waitcnt vmcnt(" #n ")" ::: "memory")
; #define PG8_WAIT_L(n) asm volatile("s_waitcnt lgkmcnt(" #n ")" ::: "memory")
; #define PG8_BAR __builtin_amdgcn_s_barrier()
; #define PG8_SCHED __builtin_amdgcn_sched_barrier(0)
; template <class Epi, class Sched, bool ALIGN_EPI = false, bool SP2 = false>
; __device__ __forceinline__ void gemm_phase(PG8_LAS unsigned char* lds, const Gemm g, const Sched& S, const Epi& E) {
;     ...
;             PG8_LDA(At, 1, 1); PG8_STAGE(PG8_SB(1, 0), b3, voffB); PG8_STAGE(PG8_SB(1, 1), b3 + hstepB, voffB); PG8_STAGE(PG8_SA(1, 0), a3, voffA);
;             PG8_WAIT_V(8); PG8_WAIT_L(0); PG8_BAR; PG8_MMA(1, 0, At, B0); PG8_MMA(1, 1, At, B1); PG8_BAR; PG8_SCHED;
	s_add_i32 s30, s53, s39
	s_mov_b32 m0, s30
	ds_read_b128 v[182:185], v156 offset:49152
	ds_read_b128 v[202:205], v156 offset:50176
	ds_read_b128 v[206:209], v156 offset:51200
	ds_read_b128 v[210:213], v156 offset:52224
	ds_read_b128 v[232:235], v156 offset:53248
	ds_read_b128 v[236:239], v156 offset:54272
	ds_read_b128 v[240:243], v156 offset:55296
	ds_read_b128 v[244:247], v156 offset:56320
	global_load_lds_dwordx4 v132, s[60:61]
	s_add_i32 m0, s30, 0x2000
	s_add_u32 s28, s28, 0x40080
	s_addc_u32 s29, s29, 0
	s_add_i32 s30, s54, s39
	global_load_lds_dwordx4 v136, s[60:61]
	s_mov_b32 m0, s30
	s_nop 0
	global_load_lds_dwordx4 v132, s[28:29]
	s_add_i32 m0, s30, 0x2000
	s_nop 0
	global_load_lds_dwordx4 v136, s[28:29]
	s_mov_b32 m0, s45
	s_nop 0
	global_load_lds_dwordx4 v130, s[62:63]
	s_mov_b32 m0, s46
	s_nop 0
	global_load_lds_dwordx4 v134, s[62:63]
	s_waitcnt vmcnt(8)
	s_waitcnt lgkmcnt(0)
	s_barrier
	s_setprio 1
	s_waitcnt lgkmcnt(0)
	v_mfma_f32_16x16x32_bf16 v[62:65], v[142:145], v[182:185], v[62:65]
	v_mfma_f32_16x16x32_bf16 v[58:61], v[158:161], v[182:185], v[58:61]
	v_mfma_f32_16x16x32_bf16 v[46:49], v[142:145], v[206:209], v[46:49]
	v_mfma_f32_16x16x32_bf16 v[42:45], v[158:161], v[206:209], v[42:45]
	v_mfma_f32_16x16x32_bf16 v[30:33], v[142:145], v[232:235], v[30:33]
	v_mfma_f32_16x16x32_bf16 v[26:29], v[158:161], v[232:235], v[26:29]
	v_mfma_f32_16x16x32_bf16 v[14:17], v[142:145], v[240:243], v[14:17]
	v_mfma_f32_16x16x32_bf16 v[10:13], v[158:161], v[240:243], v[10:13]
	v_mfma_f32_16x16x32_bf16 v[62:65], v[146:149], v[202:205], v[62:65]
	v_mfma_f32_16x16x32_bf16 v[58:61], v[162:165], v[202:205], v[58:61]
	v_mfma_f32_16x16x32_bf16 v[46:49], v[146:149], v[210:213], v[46:49]
	v_mfma_f32_16x16x32_bf16 v[42:45], v[162:165], v[210:213], v[42:45]
	v_mfma_f32_16x16x32_bf16 v[30:33], v[146:149], v[236:239], v[30:33]
	v_mfma_f32_16x16x32_bf16 v[26:29], v[162:165], v[236:239], v[26:29]
	v_mfma_f32_16x16x32_bf16 v[14:17], v[146:149], v[244:247], v[14:17]
	v_mfma_f32_16x16x32_bf16 v[10:13], v[162:165], v[244:247], v[10:13]
	s_setprio 0
	s_setprio 1
	v_mfma_f32_16x16x32_bf16 v[54:57], v[166:169], v[182:185], v[54:57]
	v_mfma_f32_16x16x32_bf16 v[50:53], v[174:177], v[182:185], v[50:53]
	v_mfma_f32_16x16x32_bf16 v[38:41], v[166:169], v[206:209], v[38:41]
	v_mfma_f32_16x16x32_bf16 v[34:37], v[174:177], v[206:209], v[34:37]
	v_mfma_f32_16x16x32_bf16 v[22:25], v[166:169], v[232:235], v[22:25]
	v_mfma_f32_16x16x32_bf16 v[18:21], v[174:177], v[232:235], v[18:21]
	v_mfma_f32_16x16x32_bf16 v[6:9], v[166:169], v[240:243], v[6:9]
	v_mfma_f32_16x16x32_bf16 v[2:5], v[174:177], v[240:243], v[2:5]
	v_mfma_f32_16x16x32_bf16 v[54:57], v[170:173], v[202:205], v[54:57]
	v_mfma_f32_16x16x32_bf16 v[50:53], v[178:181], v[202:205], v[50:53]
	v_mfma_f32_16x16x32_bf16 v[38:41], v[170:173], v[210:213], v[38:41]
	v_mfma_f32_16x16x32_bf16 v[34:37], v[178:181], v[210:213], v[34:37]
	v_mfma_f32_16x16x32_bf16 v[22:25], v[170:173], v[236:239], v[22:25]
	v_mfma_f32_16x16x32_bf16 v[18:21], v[178:181], v[236:239], v[18:21]
	v_mfma_f32_16x16x32_bf16 v[6:9], v[170:173], v[244:247], v[6:9]
	v_mfma_f32_16x16x32_bf16 v[2:5], v[178:181], v[244:247], v[2:5]
	s_setprio 0
	s_barrier
	s_add_i32 s52, s52, 2
	s_add_u32 s26, s26, 0x100
	s_addc_u32 s27, s27, 0
	s_add_u32 s50, s50, 0x100
	s_addc_u32 s51, s51, 0
	s_cmp_gt_u32 s52, 13
	s_cbranch_scc0 .LBB0_254
	s_and_b64 vcc, exec, s[16:17]
	s_cbranch_vccz .LBB0_257
	s_barrier

; #define PG8_STAGE(bufoff, gbase, voff) do { _Pragma("unroll") for (int _i = 0; _i < 2; ++_i) \
;         __builtin_amdgcn_global_load_lds((const unsigned*)((const char*)(gbase) + (voff)[_i]), (PG8_LAS unsigned*)(lds + (bufoff) + ldsw + _i * 8192), 16, 0, 0); } while (0)
; #define PG8_LDA(dst, b, h) do { _Pragma("unroll") for (int m = 0; m < 4; ++m) _Pragma("unroll") for (int k = 0; k < 2; ++k) dst[m][k] = *(const PG8_LAS bf16x8*)(lds + PG8_SA(b, h) + aoff + m * 2048 + k * 1024); } while (0)
; #define PG8_LDB(dst, b, h) do { _Pragma("unroll") for (int n = 0; n < 2; ++n) _Pragma("unroll") for (int k = 0; k < 2; ++k) dst[n][k] = *(const PG8_LAS bf16x8*)(lds + PG8_SB(b, h) + boff + n * 2048 + k * 1024); } while (0)
; #define PG8_MMA(ai, bj, At, Bt) do { __builtin_amdgcn_s_setprio(1); _Pragma("unroll") for (int m = 0; m < 4; ++m) _Pragma("unroll") for (int n = 0; n < 2; ++n) _Pragma("unroll") for (int k = 0; k < 2; ++k) \
;         acc[ai][bj][m][n] = __builtin_amdgcn_mfma_f32_16x16x32_bf16(Bt[n][k], At[m][k], acc[ai][bj][m][n], 0, 0, 0); __builtin_amdgcn_s_setprio(0); } while (0)
; #define PG8_WAIT_V(n) asm volatile("s_waitcnt vmcnt(" #n ")" ::: "memory")
; #define PG8_WAIT_L(n) asm volatile("s_waitcnt lgkmcnt(" #n ")" ::: "memory")
; #define PG8_BAR __builtin_amdgcn_s_barrier()
; #define PG8_SCHED __builtin_amdgcn_sched_barrier(0)
; template <class Epi, class Sched, bool ALIGN_EPI = false, bool SP2 = false>
; __device__ __forceinline__ void gemm_phase(PG8_LAS unsigned char* lds, const Gemm g, const Sched& S, const Epi& E) {
;     ...
;         for (int t = 0; t < nt; t += 2) {
;             const bool last = (t == nt - 2);
;             const char* a1 = cA + (size_t)(t + 1) * kstep;
;             const char* a2 = last ? nA : cA + (size_t)(t + 2) * kstep; const char* b2 = last ? nB : cB + (size_t)(t + 2) * kstep;
;             const char* a3 = a2 + kstep; const char* b3 = b2 + kstep;
;             if (last && has_next) S.a_ready(nxt);
;             if constexpr (SP2) {
;             PG8_LDB(B0, 0, 0); PG8_LDB(B1, 0, 1); PG8_SCHED; PG8_LDA(At, 0, 0); PG8_STAGE(PG8_SA(1, 1), a1 + hstepA, voffA);
;             PG8_WAIT_V(8); PG8_WAIT_L(0); PG8_BAR; PG8_MMA(0, 0, At, B0); PG8_MMA(0, 1, At, B1); PG8_BAR; PG8_SCHED;
;             PG8_LDA(At, 0, 1); PG8_STAGE(PG8_SB(0, 0), b2, voffB); PG8_STAGE(PG8_SB(0, 1), b2 + hstepB, voffB); PG8_STAGE(PG8_SA(0, 0), a2, voffA);
.LBB0_530:
	s_add_u32 s12, s1, s8
	s_addc_u32 s13, s28, s9
	s_add_u32 s12, s12, 0xfe00100
	s_addc_u32 s13, s13, 0
	s_add_u32 s34, s29, s8
	s_addc_u32 s35, s30, s9
	s_add_i32 s36, 0, 0x10000
	s_cmpk_eq_i32 s8, 0x700
	s_cselect_b32 s15, s7, s13
	s_cselect_b32 s14, s6, s12
	v_add_u32_e32 v145, s36, v143
	s_cselect_b32 s13, s5, s35
	s_cselect_b32 s12, s4, s34
	s_add_i32 s37, 0, 0x14000
	ds_read_b128 v[146:149], v145
	ds_read_b128 v[150:153], v145 offset:1024
	ds_read_b128 v[154:157], v145 offset:2048
	ds_read_b128 v[158:161], v145 offset:3072
	v_add_u32_e32 v145, s37, v143
	ds_read_b128 v[162:165], v145
	ds_read_b128 v[166:169], v145 offset:1024
	ds_read_b128 v[170:173], v145 offset:2048
	ds_read_b128 v[174:177], v145 offset:3072
	v_lshl_add_u64 v[186:187], v[138:139], 0, s[8:9]
	s_add_i32 m0, s21, 0xc000
	ds_read_b128 v[178:181], v144
	ds_read_b128 v[182:185], v144 offset:1024
	ds_read_b128 v[202:205], v144 offset:2048
	ds_read_b128 v[206:209], v144 offset:3072
	ds_read_b128 v[210:213], v144 offset:4096
	ds_read_b128 v[232:235], v144 offset:5120
	ds_read_b128 v[236:239], v144 offset:6144
	ds_read_b128 v[240:243], v144 offset:7168
	global_load_lds_dwordx4 v[186:187], off
	v_lshl_add_u64 v[186:187], v[140:141], 0, s[8:9]
	s_add_i32 m0, s21, 0xe000
	s_nop 0
	global_load_lds_dwordx4 v[186:187], off
	s_waitcnt vmcnt(8)
	s_waitcnt lgkmcnt(0)
	s_barrier
	s_setprio 1
	s_waitcnt lgkmcnt(0)
	v_mfma_f32_16x16x32_bf16 v[126:129], v[146:149], v[178:181], v[126:129]
	v_mfma_f32_16x16x32_bf16 v[122:125], v[154:157], v[178:181], v[122:125]
	v_mfma_f32_16x16x32_bf16 v[118:121], v[146:149], v[202:205], v[118:121]
	v_mfma_f32_16x16x32_bf16 v[114:117], v[154:157], v[202:205], v[114:117]
	v_mfma_f32_16x16x32_bf16 v[110:113], v[146:149], v[210:213], v[110:113]
	v_mfma_f32_16x16x32_bf16 v[106:109], v[154:157], v[210:213], v[106:109]
	v_mfma_f32_16x16x32_bf16 v[102:105], v[146:149], v[236:239], v[102:105]
	v_mfma_f32_16x16x32_bf16 v[98:101], v[154:157], v[236:239], v[98:101]
	v_mfma_f32_16x16x32_bf16 v[126:129], v[150:153], v[182:185], v[126:129]
	v_mfma_f32_16x16x32_bf16 v[122:125], v[158:161], v[182:185], v[122:125]
	v_mfma_f32_16x16x32_bf16 v[118:121], v[150:153], v[206:209], v[118:121]
	v_mfma_f32_16x16x32_bf16 v[114:117], v[158:161], v[206:209], v[114:117]
	v_mfma_f32_16x16x32_bf16 v[110:113], v[150:153], v[232:235], v[110:113]
	v_mfma_f32_16x16x32_bf16 v[106:109], v[158:161], v[232:235], v[106:109]
	v_mfma_f32_16x16x32_bf16 v[102:105], v[150:153], v[240:243], v[102:105]
	v_mfma_f32_16x16x32_bf16 v[98:101], v[158:161], v[240:243], v[98:101]
	s_setprio 0
	s_setprio 1
	v_mfma_f32_16x16x32_bf16 v[94:97], v[162:165], v[178:181], v[94:97]
	v_mfma_f32_16x16x32_bf16 v[86:89], v[170:173], v[178:181], v[86:89]
	v_mfma_f32_16x16x32_bf16 v[78:81], v[162:165], v[202:205], v[78:81]
	v_mfma_f32_16x16x32_bf16 v[74:77], v[170:173], v[202:205], v[74:77]
	v_mfma_f32_16x16x32_bf16 v[70:73], v[162:165], v[210:213], v[70:73]
	v_mfma_f32_16x16x32_bf16 v[62:65], v[170:173], v[210:213], v[62:65]
	v_mfma_f32_16x16x32_bf16 v[54:57], v[162:165], v[236:239], v[54:57]
	v_mfma_f32_16x16x32_bf16 v[50:53], v[170:173], v[236:239], v[50:53]
	v_mfma_f32_16x16x32_bf16 v[94:97], v[166:169], v[182:185], v[94:97]
	v_mfma_f32_16x16x32_bf16 v[86:89], v[174:177], v[182:185], v[86:89]
	v_mfma_f32_16x16x32_bf16 v[78:81], v[166:169], v[206:209], v[78:81]
	v_mfma_f32_16x16x32_bf16 v[74:77], v[174:177], v[206:209], v[74:77]
	v_mfma_f32_16x16x32_bf16 v[70:73], v[166:169], v[232:235], v[70:73]
	v_mfma_f32_16x16x32_bf16 v[62:65], v[174:177], v[232:235], v[62:65]
	v_mfma_f32_16x16x32_bf16 v[54:57], v[166:169], v[240:243], v[54:57]
	v_mfma_f32_16x16x32_bf16 v[50:53], v[174:177], v[240:243], v[50:53]
	s_setprio 0
	s_barrier
	s_add_i32 s34, s36, s20
	s_mov_b32 m0, s34
	ds_read_b128 v[178:181], v144 offset:16384
	ds_read_b128 v[182:185], v144 offset:17408
	ds_read_b128 v[202:205], v144 offset:18432
	ds_read_b128 v[206:209], v144 offset:19456
	ds_read_b128 v[210:213], v144 offset:20480
	ds_read_b128 v[232:235], v144 offset:21504
	ds_read_b128 v[236:239], v144 offset:22528
	ds_read_b128 v[240:243], v144 offset:23552
	s_add_u32 s60, s12, 0x80
	s_addc_u32 s61, s13, 0
	s_add_u32 s62, s14, 0x80
	s_addc_u32 s63, s15, 0
	global_load_lds_dwordx4 v134, s[12:13]
	s_add_i32 m0, s34, 0x2000
	s_add_u32 s34, s12, 0x80000
	s_addc_u32 s35, s13, 0
	s_add_i32 s36, s37, s20
	global_load_lds_dwordx4 v130, s[12:13]
	s_mov_b32 m0, s36
	s_nop 0
	global_load_lds_dwordx4 v134, s[34:35]
	s_add_i32 m0, s36, 0x2000
	s_nop 0
	global_load_lds_dwordx4 v130, s[34:35]
	s_mov_b32 m0, s21
	s_nop 0
	global_load_lds_dwordx4 v136, s[14:15]
	s_mov_b32 m0, s22
	s_nop 0
	global_load_lds_dwordx4 v132, s[14:15]
	s_waitcnt vmcnt(8)
	s_waitcnt lgkmcnt(0)
	s_barrier
; #define PG8_STAGE(bufoff, gbase, voff) do { _Pragma("unroll") for (int _i = 0; _i < 2; ++_i) \
;         __builtin_amdgcn_global_load_lds((const unsigned*)((const char*)(gbase) + (voff)[_i]), (PG8_LAS unsigned*)(lds + (bufoff) + ldsw + _i * 8192), 16, 0, 0); } while (0)
; #define PG8_LDA(dst, b, h) do { _Pragma("unroll") for (int m = 0; m < 4; ++m) _Pragma("unroll") for (int k = 0; k < 2; ++k) dst[m][k] = *(const PG8_LAS bf16x8*)(lds + PG8_SA(b, h) + aoff + m * 2048 + k * 1024); } while (0)
; #define PG8_LDB(dst, b, h) do { _Pragma("unroll") for (int n = 0; n < 2; ++n) _Pragma("unroll") for (int k = 0; k < 2; ++k) dst[n][k] = *(const PG8_LAS bf16x8*)(lds + PG8_SB(b, h) + boff + n * 2048 + k * 1024); } while (0)
; #define PG8_MMA(ai, bj, At, Bt) do { __builtin_amdgcn_s_setprio(1); _Pragma("unroll") for (int m = 0; m < 4; ++m) _Pragma("unroll") for (int n = 0; n < 2; ++n) _Pragma("unroll") for (int k = 0; k < 2; ++k) \
;         acc[ai][bj][m][n] = __builtin_amdgcn_mfma_f32_16x16x32_bf16(Bt[n][k], At[m][k], acc[ai][bj][m][n], 0, 0, 0); __builtin_amdgcn_s_setprio(0); } while (0)
; #define PG8_WAIT_V(n) asm volatile("s_waitcnt vmcnt(" #n ")" ::: "memory")
; #define PG8_WAIT_L(n) asm volatile("s_waitcnt lgkmcnt(" #n ")" ::: "memory")
; #define PG8_BAR __builtin_amdgcn_s_barrier()
; #define PG8_SCHED __builtin_amdgcn_sched_barrier(0)
; template <class Epi, class Sched, bool ALIGN_EPI = false, bool SP2 = false>
; __device__ __forceinline__ void gemm_phase(PG8_LAS unsigned char* lds, const Gemm g, const Sched& S, const Epi& E) {
;     ...
;             PG8_WAIT_V(8); PG8_WAIT_L(0); PG8_BAR; PG8_MMA(1, 0, At, B0); PG8_MMA(1, 1, At, B1); PG8_BAR; PG8_SCHED;
;             PG8_LDB(B0, 1, 0); PG8_LDB(B1, 1, 1); PG8_SCHED; PG8_LDA(At, 1, 0); PG8_STAGE(PG8_SA(0, 1), a2 + hstepA, voffA);
;             PG8_WAIT_V(8); PG8_WAIT_L(0); PG8_BAR; PG8_MMA(0, 0, At, B0); PG8_MMA(0, 1, At, B1); PG8_BAR; PG8_SCHED;
	s_setprio 1
	s_waitcnt lgkmcnt(0)
	v_mfma_f32_16x16x32_bf16 v[90:93], v[146:149], v[178:181], v[90:93]
	v_mfma_f32_16x16x32_bf16 v[82:85], v[154:157], v[178:181], v[82:85]
	v_mfma_f32_16x16x32_bf16 v[66:69], v[146:149], v[202:205], v[66:69]
	v_mfma_f32_16x16x32_bf16 v[58:61], v[154:157], v[202:205], v[58:61]
	v_mfma_f32_16x16x32_bf16 v[46:49], v[146:149], v[210:213], v[46:49]
	v_mfma_f32_16x16x32_bf16 v[42:45], v[154:157], v[210:213], v[42:45]
	v_mfma_f32_16x16x32_bf16 v[38:41], v[146:149], v[236:239], v[38:41]
	v_mfma_f32_16x16x32_bf16 v[34:37], v[154:157], v[236:239], v[34:37]
	v_mfma_f32_16x16x32_bf16 v[90:93], v[150:153], v[182:185], v[90:93]
	v_mfma_f32_16x16x32_bf16 v[82:85], v[158:161], v[182:185], v[82:85]
	v_mfma_f32_16x16x32_bf16 v[66:69], v[150:153], v[206:209], v[66:69]
	v_mfma_f32_16x16x32_bf16 v[58:61], v[158:161], v[206:209], v[58:61]
	v_mfma_f32_16x16x32_bf16 v[46:49], v[150:153], v[232:235], v[46:49]
	v_mfma_f32_16x16x32_bf16 v[42:45], v[158:161], v[232:235], v[42:45]
	v_mfma_f32_16x16x32_bf16 v[38:41], v[150:153], v[240:243], v[38:41]
	v_mfma_f32_16x16x32_bf16 v[34:37], v[158:161], v[240:243], v[34:37]
	s_setprio 0
	s_setprio 1
	v_mfma_f32_16x16x32_bf16 v[30:33], v[162:165], v[178:181], v[30:33]
	v_mfma_f32_16x16x32_bf16 v[26:29], v[170:173], v[178:181], v[26:29]
	v_mfma_f32_16x16x32_bf16 v[22:25], v[162:165], v[202:205], v[22:25]
	v_mfma_f32_16x16x32_bf16 v[18:21], v[170:173], v[202:205], v[18:21]
	v_mfma_f32_16x16x32_bf16 v[14:17], v[162:165], v[210:213], v[14:17]
	v_mfma_f32_16x16x32_bf16 v[10:13], v[170:173], v[210:213], v[10:13]
	v_mfma_f32_16x16x32_bf16 v[6:9], v[162:165], v[236:239], v[6:9]
	v_mfma_f32_16x16x32_bf16 v[2:5], v[170:173], v[236:239], v[2:5]
	v_mfma_f32_16x16x32_bf16 v[30:33], v[166:169], v[182:185], v[30:33]
	v_mfma_f32_16x16x32_bf16 v[26:29], v[174:177], v[182:185], v[26:29]
	v_mfma_f32_16x16x32_bf16 v[22:25], v[166:169], v[206:209], v[22:25]
	v_mfma_f32_16x16x32_bf16 v[18:21], v[174:177], v[206:209], v[18:21]
	v_mfma_f32_16x16x32_bf16 v[14:17], v[166:169], v[232:235], v[14:17]
	v_mfma_f32_16x16x32_bf16 v[10:13], v[174:177], v[232:235], v[10:13]
	v_mfma_f32_16x16x32_bf16 v[6:9], v[166:169], v[240:243], v[6:9]
	v_mfma_f32_16x16x32_bf16 v[2:5], v[174:177], v[240:243], v[2:5]
	s_setprio 0
	s_barrier
	s_add_i32 s34, 0, 0x18000
	v_add_u32_e32 v145, s34, v143
	s_add_i32 s35, 0, 0x1c000
	ds_read_b128 v[146:149], v145
	ds_read_b128 v[150:153], v145 offset:1024
	ds_read_b128 v[154:157], v145 offset:2048
	ds_read_b128 v[158:161], v145 offset:3072
	v_add_u32_e32 v145, s35, v143
	ds_read_b128 v[162:165], v145
	ds_read_b128 v[166:169], v145 offset:1024
	ds_read_b128 v[170:173], v145 offset:2048
	ds_read_b128 v[174:177], v145 offset:3072
	s_add_u32 s14, s14, 0x40000
	s_addc_u32 s15, s15, 0
	s_mov_b32 m0, s23
	ds_read_b128 v[178:181], v144 offset:32768
	ds_read_b128 v[182:185], v144 offset:33792
	ds_read_b128 v[202:205], v144 offset:34816
	ds_read_b128 v[206:209], v144 offset:35840
	ds_read_b128 v[210:213], v144 offset:36864
	ds_read_b128 v[232:235], v144 offset:37888
	ds_read_b128 v[236:239], v144 offset:38912
	ds_read_b128 v[240:243], v144 offset:39936
	global_load_lds_dwordx4 v136, s[14:15]
	s_mov_b32 m0, s24
	s_nop 0
	global_load_lds_dwordx4 v132, s[14:15]
	s_waitcnt vmcnt(8)
	s_waitcnt lgkmcnt(0)
	s_barrier
	s_setprio 1
	s_waitcnt lgkmcnt(0)
	v_mfma_f32_16x16x32_bf16 v[126:129], v[146:149], v[178:181], v[126:129]
	v_mfma_f32_16x16x32_bf16 v[122:125], v[154:157], v[178:181], v[122:125]
	v_mfma_f32_16x16x32_bf16 v[118:121], v[146:149], v[202:205], v[118:121]
	v_mfma_f32_16x16x32_bf16 v[114:117], v[154:157], v[202:205], v[114:117]
	v_mfma_f32_16x16x32_bf16 v[110:113], v[146:149], v[210:213], v[110:113]
	v_mfma_f32_16x16x32_bf16 v[106:109], v[154:157], v[210:213], v[106:109]
	v_mfma_f32_16x16x32_bf16 v[102:105], v[146:149], v[236:239], v[102:105]
	v_mfma_f32_16x16x32_bf16 v[98:101], v[154:157], v[236:239], v[98:101]
	v_mfma_f32_16x16x32_bf16 v[126:129], v[150:153], v[182:185], v[126:129]
	v_mfma_f32_16x16x32_bf16 v[122:125], v[158:161], v[182:185], v[122:125]
	v_mfma_f32_16x16x32_bf16 v[118:121], v[150:153], v[206:209], v[118:121]
	v_mfma_f32_16x16x32_bf16 v[114:117], v[158:161], v[206:209], v[114:117]
	v_mfma_f32_16x16x32_bf16 v[110:113], v[150:153], v[232:235], v[110:113]
	v_mfma_f32_16x16x32_bf16 v[106:109], v[158:161], v[232:235], v[106:109]
	v_mfma_f32_16x16x32_bf16 v[102:105], v[150:153], v[240:243], v[102:105]
	v_mfma_f32_16x16x32_bf16 v[98:101], v[158:161], v[240:243], v[98:101]
	s_setprio 0
	s_setprio 1
	v_mfma_f32_16x16x32_bf16 v[94:97], v[162:165], v[178:181], v[94:97]
	v_mfma_f32_16x16x32_bf16 v[86:89], v[170:173], v[178:181], v[86:89]
	v_mfma_f32_16x16x32_bf16 v[78:81], v[162:165], v[202:205], v[78:81]
	v_mfma_f32_16x16x32_bf16 v[74:77], v[170:173], v[202:205], v[74:77]
	v_mfma_f32_16x16x32_bf16 v[70:73], v[162:165], v[210:213], v[70:73]
	v_mfma_f32_16x16x32_bf16 v[62:65], v[170:173], v[210:213], v[62:65]
	v_mfma_f32_16x16x32_bf16 v[54:57], v[162:165], v[236:239], v[54:57]
	v_mfma_f32_16x16x32_bf16 v[50:53], v[170:173], v[236:239], v[50:53]
	v_mfma_f32_16x16x32_bf16 v[94:97], v[166:169], v[182:185], v[94:97]
	v_mfma_f32_16x16x32_bf16 v[86:89], v[174:177], v[182:185], v[86:89]
	v_mfma_f32_16x16x32_bf16 v[78:81], v[166:169], v[206:209], v[78:81]
	v_mfma_f32_16x16x32_bf16 v[74:77], v[174:177], v[206:209], v[74:77]
	v_mfma_f32_16x16x32_bf16 v[70:73], v[166:169], v[232:235], v[70:73]
	v_mfma_f32_16x16x32_bf16 v[62:65], v[174:177], v[232:235], v[62:65]
	v_mfma_f32_16x16x32_bf16 v[54:57], v[166:169], v[240:243], v[54:57]
	v_mfma_f32_16x16x32_bf16 v[50:53], v[174:177], v[240:243], v[50:53]
	s_setprio 0
	s_barrier
; #define PG8_STAGE(bufoff, gbase, voff) do { _Pragma("unroll") for (int _i = 0; _i < 2; ++_i) \
;         __builtin_amdgcn_global_load_lds((const unsigned*)((const char*)(gbase) + (voff)[_i]), (PG8_LAS unsigned*)(lds + (bufoff) + ldsw + _i * 8192), 16, 0, 0); } while (0)
; #define PG8_LDA(dst, b, h) do { _Pragma("unroll") for (int m = 0; m < 4; ++m) _Pragma("unroll") for (int k = 0; k < 2; ++k) dst[m][k] = *(const PG8_LAS bf16x8*)(lds + PG8_SA(b, h) + aoff + m * 2048 + k * 1024); } while (0)
; #define PG8_MMA(ai, bj, At, Bt) do { __builtin_amdgcn_s_setprio(1); _Pragma("unroll") for (int m = 0; m < 4; ++m) _Pragma("unroll") for (int n = 0; n < 2; ++n) _Pragma("unroll") for (int k = 0; k < 2; ++k) \
;         acc[ai][bj][m][n] = __builtin_amdgcn_mfma_f32_16x16x32_bf16(Bt[n][k], At[m][k], acc[ai][bj][m][n], 0, 0, 0); __builtin_amdgcn_s_setprio(0); } while (0)
; #define PG8_WAIT_V(n) asm volatile("s_waitcnt vmcnt(" #n ")" ::: "memory")
; #define PG8_WAIT_L(n) asm volatile("s_waitcnt lgkmcnt(" #n ")" ::: "memory")
; #define PG8_BAR __builtin_amdgcn_s_barrier()
; #define PG8_SCHED __builtin_amdgcn_sched_barrier(0)
; template <class Epi, class Sched, bool ALIGN_EPI = false, bool SP2 = false>
; __device__ __forceinline__ void gemm_phase(PG8_LAS unsigned char* lds, const Gemm g, const Sched& S, const Epi& E) {
;     ...
;             PG8_LDA(At, 1, 1); PG8_STAGE(PG8_SB(1, 0), b3, voffB); PG8_STAGE(PG8_SB(1, 1), b3 + hstepB, voffB); PG8_STAGE(PG8_SA(1, 0), a3, voffA);
;             PG8_WAIT_V(8); PG8_WAIT_L(0); PG8_BAR; PG8_MMA(1, 0, At, B0); PG8_MMA(1, 1, At, B1); PG8_BAR; PG8_SCHED;
	s_add_i32 s14, s34, s20
	s_mov_b32 m0, s14
	ds_read_b128 v[178:181], v144 offset:49152
	ds_read_b128 v[182:185], v144 offset:50176
	ds_read_b128 v[202:205], v144 offset:51200
	ds_read_b128 v[206:209], v144 offset:52224
	ds_read_b128 v[210:213], v144 offset:53248
	ds_read_b128 v[232:235], v144 offset:54272
	ds_read_b128 v[236:239], v144 offset:55296
	ds_read_b128 v[240:243], v144 offset:56320
	global_load_lds_dwordx4 v134, s[60:61]
	s_add_i32 m0, s14, 0x2000
	s_add_u32 s12, s12, 0x80080
	s_addc_u32 s13, s13, 0
	s_add_i32 s14, s35, s20
	global_load_lds_dwordx4 v130, s[60:61]
	s_mov_b32 m0, s14
	s_nop 0
	global_load_lds_dwordx4 v134, s[12:13]
	s_add_i32 m0, s14, 0x2000
	s_nop 0
	global_load_lds_dwordx4 v130, s[12:13]
	s_mov_b32 m0, s26
	s_nop 0
	global_load_lds_dwordx4 v136, s[62:63]
	s_mov_b32 m0, s27
	s_nop 0
	global_load_lds_dwordx4 v132, s[62:63]
	s_waitcnt vmcnt(8)
	s_waitcnt lgkmcnt(0)
	s_barrier
	s_setprio 1
	s_waitcnt lgkmcnt(0)
	v_mfma_f32_16x16x32_bf16 v[90:93], v[146:149], v[178:181], v[90:93]
	v_mfma_f32_16x16x32_bf16 v[82:85], v[154:157], v[178:181], v[82:85]
	v_mfma_f32_16x16x32_bf16 v[66:69], v[146:149], v[202:205], v[66:69]
	v_mfma_f32_16x16x32_bf16 v[58:61], v[154:157], v[202:205], v[58:61]
	v_mfma_f32_16x16x32_bf16 v[46:49], v[146:149], v[210:213], v[46:49]
	v_mfma_f32_16x16x32_bf16 v[42:45], v[154:157], v[210:213], v[42:45]
	v_mfma_f32_16x16x32_bf16 v[38:41], v[146:149], v[236:239], v[38:41]
	v_mfma_f32_16x16x32_bf16 v[34:37], v[154:157], v[236:239], v[34:37]
	v_mfma_f32_16x16x32_bf16 v[90:93], v[150:153], v[182:185], v[90:93]
	v_mfma_f32_16x16x32_bf16 v[82:85], v[158:161], v[182:185], v[82:85]
	v_mfma_f32_16x16x32_bf16 v[66:69], v[150:153], v[206:209], v[66:69]
	v_mfma_f32_16x16x32_bf16 v[58:61], v[158:161], v[206:209], v[58:61]
	v_mfma_f32_16x16x32_bf16 v[46:49], v[150:153], v[232:235], v[46:49]
	v_mfma_f32_16x16x32_bf16 v[42:45], v[158:161], v[232:235], v[42:45]
	v_mfma_f32_16x16x32_bf16 v[38:41], v[150:153], v[240:243], v[38:41]
	v_mfma_f32_16x16x32_bf16 v[34:37], v[158:161], v[240:243], v[34:37]
	s_setprio 0
	s_setprio 1
	v_mfma_f32_16x16x32_bf16 v[30:33], v[162:165], v[178:181], v[30:33]
	v_mfma_f32_16x16x32_bf16 v[26:29], v[170:173], v[178:181], v[26:29]
	v_mfma_f32_16x16x32_bf16 v[22:25], v[162:165], v[202:205], v[22:25]
	v_mfma_f32_16x16x32_bf16 v[18:21], v[170:173], v[202:205], v[18:21]
	v_mfma_f32_16x16x32_bf16 v[14:17], v[162:165], v[210:213], v[14:17]
	v_mfma_f32_16x16x32_bf16 v[10:13], v[170:173], v[210:213], v[10:13]
	v_mfma_f32_16x16x32_bf16 v[6:9], v[162:165], v[236:239], v[6:9]
	v_mfma_f32_16x16x32_bf16 v[2:5], v[170:173], v[236:239], v[2:5]
	v_mfma_f32_16x16x32_bf16 v[30:33], v[166:169], v[182:185], v[30:33]
	v_mfma_f32_16x16x32_bf16 v[26:29], v[174:177], v[182:185], v[26:29]
	v_mfma_f32_16x16x32_bf16 v[22:25], v[166:169], v[206:209], v[22:25]
	v_mfma_f32_16x16x32_bf16 v[18:21], v[174:177], v[206:209], v[18:21]
	v_mfma_f32_16x16x32_bf16 v[14:17], v[166:169], v[232:235], v[14:17]
	v_mfma_f32_16x16x32_bf16 v[10:13], v[174:177], v[232:235], v[10:13]
	v_mfma_f32_16x16x32_bf16 v[6:9], v[166:169], v[240:243], v[6:9]
	v_mfma_f32_16x16x32_bf16 v[2:5], v[174:177], v[240:243], v[2:5]
	s_setprio 0
	s_barrier
	s_add_i32 s31, s31, 2
	s_add_u32 s8, s8, 0x100
	s_addc_u32 s9, s9, 0
	s_cmp_gt_u32 s31, 13
	s_cbranch_scc0 .LBB0_530
	s_cmpk_lt_u32 s19, 0x100
	s_cbranch_scc0 .LBB0_533
	s_barrier

; #define PG8_STAGE(bufoff, gbase, voff) do { _Pragma("unroll") for (int _i = 0; _i < 2; ++_i) \
;         __builtin_amdgcn_global_load_lds((const unsigned*)((const char*)(gbase) + (voff)[_i]), (PG8_LAS unsigned*)(lds + (bufoff) + ldsw + _i * 8192), 16, 0, 0); } while (0)
; #define PG8_LDA(dst, b, h) do { _Pragma("unroll") for (int m = 0; m < 4; ++m) _Pragma("unroll") for (int k = 0; k < 2; ++k) dst[m][k] = *(const PG8_LAS bf16x8*)(lds + PG8_SA(b, h) + aoff + m * 2048 + k * 1024); } while (0)
; #define PG8_LDB(dst, b, h) do { _Pragma("unroll") for (int n = 0; n < 2; ++n) _Pragma("unroll") for (int k = 0; k < 2; ++k) dst[n][k] = *(const PG8_LAS bf16x8*)(lds + PG8_SB(b, h) + boff + n * 2048 + k * 1024); } while (0)
; #define PG8_MMA(ai, bj, At, Bt) do { __builtin_amdgcn_s_setprio(1); _Pragma("unroll") for (int m = 0; m < 4; ++m) _Pragma("unroll") for (int n = 0; n < 2; ++n) _Pragma("unroll") for (int k = 0; k < 2; ++k) \
;         acc[ai][bj][m][n] = __builtin_amdgcn_mfma_f32_16x16x32_bf16(Bt[n][k], At[m][k], acc[ai][bj][m][n], 0, 0, 0); __builtin_amdgcn_s_setprio(0); } while (0)
; #define PG8_WAIT_V(n) asm volatile("s_waitcnt vmcnt(" #n ")" ::: "memory")
; #define PG8_WAIT_L(n) asm volatile("s_waitcnt lgkmcnt(" #n ")" ::: "memory")
; #define PG8_BAR __builtin_amdgcn_s_barrier()
; #define PG8_SCHED __builtin_amdgcn_sched_barrier(0)
; template <class Epi, class Sched, bool ALIGN_EPI = false, bool SP2 = false>
; __device__ __forceinline__ void gemm_phase(PG8_LAS unsigned char* lds, const Gemm g, const Sched& S, const Epi& E) {
;     ...
;         for (int t = 0; t < nt; t += 2) {
;             const bool last = (t == nt - 2);
;             const char* a1 = cA + (size_t)(t + 1) * kstep;
;             const char* a2 = last ? nA : cA + (size_t)(t + 2) * kstep; const char* b2 = last ? nB : cB + (size_t)(t + 2) * kstep;
;             const char* a3 = a2 + kstep; const char* b3 = b2 + kstep;
;             if (last && has_next) S.a_ready(nxt);
;             if constexpr (SP2) {
;             PG8_LDB(B0, 0, 0); PG8_LDB(B1, 0, 1); PG8_SCHED; PG8_LDA(At, 0, 0); PG8_STAGE(PG8_SA(1, 1), a1 + hstepA, voffA);
;             PG8_WAIT_V(8); PG8_WAIT_L(0); PG8_BAR; PG8_MMA(0, 0, At, B0); PG8_MMA(0, 1, At, B1); PG8_BAR; PG8_SCHED;
;             PG8_LDA(At, 0, 1); PG8_STAGE(PG8_SB(0, 0), b2, voffB); PG8_STAGE(PG8_SB(0, 1), b2 + hstepB, voffB); PG8_STAGE(PG8_SA(0, 0), a2, voffA);
.LBB0_1160:
	s_add_u32 s24, s22, 0x100
	s_addc_u32 s25, s23, 0
	s_add_i32 s57, 0, 0x10000
	s_cmp_eq_u32 s56, 4
	s_cselect_b32 s29, s17, s25
	s_cselect_b32 s28, s16, s24
	v_add_u32_e32 v145, s57, v142
	s_cselect_b32 s27, s52, s55
	s_cselect_b32 s26, s53, s54
	s_add_i32 s58, 0, 0x14000
	ds_read_b128 v[146:149], v145
	ds_read_b128 v[150:153], v145 offset:1024
	ds_read_b128 v[154:157], v145 offset:2048
	ds_read_b128 v[158:161], v145 offset:3072
	v_add_u32_e32 v145, s58, v142
	ds_read_b128 v[162:165], v145
	ds_read_b128 v[166:169], v145 offset:1024
	ds_read_b128 v[170:173], v145 offset:2048
	ds_read_b128 v[174:177], v145 offset:3072
	s_add_i32 m0, s39, 0xc000
	ds_read_b128 v[178:181], v143
	ds_read_b128 v[182:185], v143 offset:1024
	ds_read_b128 v[202:205], v143 offset:2048
	ds_read_b128 v[206:209], v143 offset:3072
	ds_read_b128 v[210:213], v143 offset:4096
	ds_read_b128 v[232:235], v143 offset:5120
	ds_read_b128 v[236:239], v143 offset:6144
	ds_read_b128 v[240:243], v143 offset:7168
	global_load_lds_dwordx4 v138, s[22:23]
	s_add_i32 m0, s39, 0xe000
	s_nop 0
	global_load_lds_dwordx4 v140, s[22:23]
	s_waitcnt vmcnt(8)
	s_waitcnt lgkmcnt(0)
	s_barrier
	s_setprio 1
	s_waitcnt lgkmcnt(0)
	v_mfma_f32_16x16x32_bf16 v[126:129], v[146:149], v[178:181], v[126:129]
	v_mfma_f32_16x16x32_bf16 v[122:125], v[154:157], v[178:181], v[122:125]
	v_mfma_f32_16x16x32_bf16 v[118:121], v[146:149], v[202:205], v[118:121]
	v_mfma_f32_16x16x32_bf16 v[114:117], v[154:157], v[202:205], v[114:117]
	v_mfma_f32_16x16x32_bf16 v[110:113], v[146:149], v[210:213], v[110:113]
	v_mfma_f32_16x16x32_bf16 v[106:109], v[154:157], v[210:213], v[106:109]
	v_mfma_f32_16x16x32_bf16 v[102:105], v[146:149], v[236:239], v[102:105]
	v_mfma_f32_16x16x32_bf16 v[98:101], v[154:157], v[236:239], v[98:101]
	v_mfma_f32_16x16x32_bf16 v[126:129], v[150:153], v[182:185], v[126:129]
	v_mfma_f32_16x16x32_bf16 v[122:125], v[158:161], v[182:185], v[122:125]
	v_mfma_f32_16x16x32_bf16 v[118:121], v[150:153], v[206:209], v[118:121]
	v_mfma_f32_16x16x32_bf16 v[114:117], v[158:161], v[206:209], v[114:117]
	v_mfma_f32_16x16x32_bf16 v[110:113], v[150:153], v[232:235], v[110:113]
	v_mfma_f32_16x16x32_bf16 v[106:109], v[158:161], v[232:235], v[106:109]
	v_mfma_f32_16x16x32_bf16 v[102:105], v[150:153], v[240:243], v[102:105]
	v_mfma_f32_16x16x32_bf16 v[98:101], v[158:161], v[240:243], v[98:101]
	s_setprio 0
	s_setprio 1
	v_mfma_f32_16x16x32_bf16 v[78:81], v[162:165], v[178:181], v[78:81]
	v_mfma_f32_16x16x32_bf16 v[70:73], v[170:173], v[178:181], v[70:73]
	v_mfma_f32_16x16x32_bf16 v[62:65], v[162:165], v[202:205], v[62:65]
	v_mfma_f32_16x16x32_bf16 v[54:57], v[170:173], v[202:205], v[54:57]
	v_mfma_f32_16x16x32_bf16 v[46:49], v[162:165], v[210:213], v[46:49]
	v_mfma_f32_16x16x32_bf16 v[42:45], v[170:173], v[210:213], v[42:45]
	v_mfma_f32_16x16x32_bf16 v[38:41], v[162:165], v[236:239], v[38:41]
	v_mfma_f32_16x16x32_bf16 v[34:37], v[170:173], v[236:239], v[34:37]
	v_mfma_f32_16x16x32_bf16 v[78:81], v[166:169], v[182:185], v[78:81]
	v_mfma_f32_16x16x32_bf16 v[70:73], v[174:177], v[182:185], v[70:73]
	v_mfma_f32_16x16x32_bf16 v[62:65], v[166:169], v[206:209], v[62:65]
	v_mfma_f32_16x16x32_bf16 v[54:57], v[174:177], v[206:209], v[54:57]
	v_mfma_f32_16x16x32_bf16 v[46:49], v[166:169], v[232:235], v[46:49]
	v_mfma_f32_16x16x32_bf16 v[42:45], v[174:177], v[232:235], v[42:45]
	v_mfma_f32_16x16x32_bf16 v[38:41], v[166:169], v[240:243], v[38:41]
	v_mfma_f32_16x16x32_bf16 v[34:37], v[174:177], v[240:243], v[34:37]
	s_setprio 0
	s_barrier
	s_add_i32 s22, s57, s38
	s_mov_b32 m0, s22
	ds_read_b128 v[178:181], v143 offset:16384
	ds_read_b128 v[182:185], v143 offset:17408
	ds_read_b128 v[202:205], v143 offset:18432
	ds_read_b128 v[206:209], v143 offset:19456
	ds_read_b128 v[210:213], v143 offset:20480
	ds_read_b128 v[232:235], v143 offset:21504
	ds_read_b128 v[236:239], v143 offset:22528
	ds_read_b128 v[240:243], v143 offset:23552
	s_add_u32 s60, s26, 0x80
	s_addc_u32 s61, s27, 0
	s_add_u32 s62, s28, 0x80
	s_addc_u32 s63, s29, 0
	global_load_lds_dwordx4 v134, s[26:27]
	s_add_i32 m0, s22, 0x2000
	s_add_u32 s22, s26, 0x20000
	s_addc_u32 s23, s27, 0
	s_add_i32 s57, s58, s38
	global_load_lds_dwordx4 v130, s[26:27]
	s_mov_b32 m0, s57
	s_nop 0
	global_load_lds_dwordx4 v134, s[22:23]
	s_add_i32 m0, s57, 0x2000
	s_nop 0
	global_load_lds_dwordx4 v130, s[22:23]
	s_mov_b32 m0, s39
	s_nop 0
	global_load_lds_dwordx4 v136, s[28:29]
	s_mov_b32 m0, s40
	s_nop 0
	global_load_lds_dwordx4 v132, s[28:29]
	s_waitcnt vmcnt(8)
	s_waitcnt lgkmcnt(0)
	s_barrier
; #define PG8_STAGE(bufoff, gbase, voff) do { _Pragma("unroll") for (int _i = 0; _i < 2; ++_i) \
;         __builtin_amdgcn_global_load_lds((const unsigned*)((const char*)(gbase) + (voff)[_i]), (PG8_LAS unsigned*)(lds + (bufoff) + ldsw + _i * 8192), 16, 0, 0); } while (0)
; #define PG8_LDA(dst, b, h) do { _Pragma("unroll") for (int m = 0; m < 4; ++m) _Pragma("unroll") for (int k = 0; k < 2; ++k) dst[m][k] = *(const PG8_LAS bf16x8*)(lds + PG8_SA(b, h) + aoff + m * 2048 + k * 1024); } while (0)
; #define PG8_LDB(dst, b, h) do { _Pragma("unroll") for (int n = 0; n < 2; ++n) _Pragma("unroll") for (int k = 0; k < 2; ++k) dst[n][k] = *(const PG8_LAS bf16x8*)(lds + PG8_SB(b, h) + boff + n * 2048 + k * 1024); } while (0)
; #define PG8_MMA(ai, bj, At, Bt) do { __builtin_amdgcn_s_setprio(1); _Pragma("unroll") for (int m = 0; m < 4; ++m) _Pragma("unroll") for (int n = 0; n < 2; ++n) _Pragma("unroll") for (int k = 0; k < 2; ++k) \
;         acc[ai][bj][m][n] = __builtin_amdgcn_mfma_f32_16x16x32_bf16(Bt[n][k], At[m][k], acc[ai][bj][m][n], 0, 0, 0); __builtin_amdgcn_s_setprio(0); } while (0)
; #define PG8_WAIT_V(n) asm volatile("s_waitcnt vmcnt(" #n ")" ::: "memory")
; #define PG8_WAIT_L(n) asm volatile("s_waitcnt lgkmcnt(" #n ")" ::: "memory")
; #define PG8_BAR __builtin_amdgcn_s_barrier()
; #define PG8_SCHED __builtin_amdgcn_sched_barrier(0)
; template <class Epi, class Sched, bool ALIGN_EPI = false, bool SP2 = false>
; __device__ __forceinline__ void gemm_phase(PG8_LAS unsigned char* lds, const Gemm g, const Sched& S, const Epi& E) {
;     ...
;             PG8_WAIT_V(8); PG8_WAIT_L(0); PG8_BAR; PG8_MMA(1, 0, At, B0); PG8_MMA(1, 1, At, B1); PG8_BAR; PG8_SCHED;
;             PG8_LDB(B0, 1, 0); PG8_LDB(B1, 1, 1); PG8_SCHED; PG8_LDA(At, 1, 0); PG8_STAGE(PG8_SA(0, 1), a2 + hstepA, voffA);
;             PG8_WAIT_V(8); PG8_WAIT_L(0); PG8_BAR; PG8_MMA(0, 0, At, B0); PG8_MMA(0, 1, At, B1); PG8_BAR; PG8_SCHED;
	s_setprio 1
	s_waitcnt lgkmcnt(0)
	v_mfma_f32_16x16x32_bf16 v[94:97], v[146:149], v[178:181], v[94:97]
	v_mfma_f32_16x16x32_bf16 v[90:93], v[154:157], v[178:181], v[90:93]
	v_mfma_f32_16x16x32_bf16 v[86:89], v[146:149], v[202:205], v[86:89]
	v_mfma_f32_16x16x32_bf16 v[82:85], v[154:157], v[202:205], v[82:85]
	v_mfma_f32_16x16x32_bf16 v[74:77], v[146:149], v[210:213], v[74:77]
	v_mfma_f32_16x16x32_bf16 v[66:69], v[154:157], v[210:213], v[66:69]
	v_mfma_f32_16x16x32_bf16 v[58:61], v[146:149], v[236:239], v[58:61]
	v_mfma_f32_16x16x32_bf16 v[50:53], v[154:157], v[236:239], v[50:53]
	v_mfma_f32_16x16x32_bf16 v[94:97], v[150:153], v[182:185], v[94:97]
	v_mfma_f32_16x16x32_bf16 v[90:93], v[158:161], v[182:185], v[90:93]
	v_mfma_f32_16x16x32_bf16 v[86:89], v[150:153], v[206:209], v[86:89]
	v_mfma_f32_16x16x32_bf16 v[82:85], v[158:161], v[206:209], v[82:85]
	v_mfma_f32_16x16x32_bf16 v[74:77], v[150:153], v[232:235], v[74:77]
	v_mfma_f32_16x16x32_bf16 v[66:69], v[158:161], v[232:235], v[66:69]
	v_mfma_f32_16x16x32_bf16 v[58:61], v[150:153], v[240:243], v[58:61]
	v_mfma_f32_16x16x32_bf16 v[50:53], v[158:161], v[240:243], v[50:53]
	s_setprio 0
	s_setprio 1
	v_mfma_f32_16x16x32_bf16 v[30:33], v[162:165], v[178:181], v[30:33]
	v_mfma_f32_16x16x32_bf16 v[26:29], v[170:173], v[178:181], v[26:29]
	v_mfma_f32_16x16x32_bf16 v[22:25], v[162:165], v[202:205], v[22:25]
	v_mfma_f32_16x16x32_bf16 v[18:21], v[170:173], v[202:205], v[18:21]
	v_mfma_f32_16x16x32_bf16 v[14:17], v[162:165], v[210:213], v[14:17]
	v_mfma_f32_16x16x32_bf16 v[10:13], v[170:173], v[210:213], v[10:13]
	v_mfma_f32_16x16x32_bf16 v[6:9], v[162:165], v[236:239], v[6:9]
	v_mfma_f32_16x16x32_bf16 v[2:5], v[170:173], v[236:239], v[2:5]
	v_mfma_f32_16x16x32_bf16 v[30:33], v[166:169], v[182:185], v[30:33]
	v_mfma_f32_16x16x32_bf16 v[26:29], v[174:177], v[182:185], v[26:29]
	v_mfma_f32_16x16x32_bf16 v[22:25], v[166:169], v[206:209], v[22:25]
	v_mfma_f32_16x16x32_bf16 v[18:21], v[174:177], v[206:209], v[18:21]
	v_mfma_f32_16x16x32_bf16 v[14:17], v[166:169], v[232:235], v[14:17]
	v_mfma_f32_16x16x32_bf16 v[10:13], v[174:177], v[232:235], v[10:13]
	v_mfma_f32_16x16x32_bf16 v[6:9], v[166:169], v[240:243], v[6:9]
	v_mfma_f32_16x16x32_bf16 v[2:5], v[174:177], v[240:243], v[2:5]
	s_setprio 0
	s_barrier
	s_add_i32 s57, 0, 0x18000
	v_add_u32_e32 v145, s57, v142
	s_add_i32 s58, 0, 0x1c000
	ds_read_b128 v[146:149], v145
	ds_read_b128 v[150:153], v145 offset:1024
	ds_read_b128 v[154:157], v145 offset:2048
	ds_read_b128 v[158:161], v145 offset:3072
	v_add_u32_e32 v145, s58, v142
	ds_read_b128 v[162:165], v145
	ds_read_b128 v[166:169], v145 offset:1024
	ds_read_b128 v[170:173], v145 offset:2048
	ds_read_b128 v[174:177], v145 offset:3072
	s_add_u32 s22, s28, 0x30000
	s_addc_u32 s23, s29, 0
	s_mov_b32 m0, s41
	ds_read_b128 v[178:181], v143 offset:32768
	ds_read_b128 v[182:185], v143 offset:33792
	ds_read_b128 v[202:205], v143 offset:34816
	ds_read_b128 v[206:209], v143 offset:35840
	ds_read_b128 v[210:213], v143 offset:36864
	ds_read_b128 v[232:235], v143 offset:37888
	ds_read_b128 v[236:239], v143 offset:38912
	ds_read_b128 v[240:243], v143 offset:39936
	global_load_lds_dwordx4 v136, s[22:23]
	s_mov_b32 m0, s42
	s_nop 0
	global_load_lds_dwordx4 v132, s[22:23]
	s_waitcnt vmcnt(8)
	s_waitcnt lgkmcnt(0)
	s_barrier
	s_setprio 1
	s_waitcnt lgkmcnt(0)
	v_mfma_f32_16x16x32_bf16 v[126:129], v[146:149], v[178:181], v[126:129]
	v_mfma_f32_16x16x32_bf16 v[122:125], v[154:157], v[178:181], v[122:125]
	v_mfma_f32_16x16x32_bf16 v[118:121], v[146:149], v[202:205], v[118:121]
	v_mfma_f32_16x16x32_bf16 v[114:117], v[154:157], v[202:205], v[114:117]
	v_mfma_f32_16x16x32_bf16 v[110:113], v[146:149], v[210:213], v[110:113]
	v_mfma_f32_16x16x32_bf16 v[106:109], v[154:157], v[210:213], v[106:109]
	v_mfma_f32_16x16x32_bf16 v[102:105], v[146:149], v[236:239], v[102:105]
	v_mfma_f32_16x16x32_bf16 v[98:101], v[154:157], v[236:239], v[98:101]
	v_mfma_f32_16x16x32_bf16 v[126:129], v[150:153], v[182:185], v[126:129]
	v_mfma_f32_16x16x32_bf16 v[122:125], v[158:161], v[182:185], v[122:125]
	v_mfma_f32_16x16x32_bf16 v[118:121], v[150:153], v[206:209], v[118:121]
	v_mfma_f32_16x16x32_bf16 v[114:117], v[158:161], v[206:209], v[114:117]
	v_mfma_f32_16x16x32_bf16 v[110:113], v[150:153], v[232:235], v[110:113]
	v_mfma_f32_16x16x32_bf16 v[106:109], v[158:161], v[232:235], v[106:109]
	v_mfma_f32_16x16x32_bf16 v[102:105], v[150:153], v[240:243], v[102:105]
	v_mfma_f32_16x16x32_bf16 v[98:101], v[158:161], v[240:243], v[98:101]
	s_setprio 0
	s_setprio 1
	v_mfma_f32_16x16x32_bf16 v[78:81], v[162:165], v[178:181], v[78:81]
	v_mfma_f32_16x16x32_bf16 v[70:73], v[170:173], v[178:181], v[70:73]
	v_mfma_f32_16x16x32_bf16 v[62:65], v[162:165], v[202:205], v[62:65]
	v_mfma_f32_16x16x32_bf16 v[54:57], v[170:173], v[202:205], v[54:57]
	v_mfma_f32_16x16x32_bf16 v[46:49], v[162:165], v[210:213], v[46:49]
	v_mfma_f32_16x16x32_bf16 v[42:45], v[170:173], v[210:213], v[42:45]
	v_mfma_f32_16x16x32_bf16 v[38:41], v[162:165], v[236:239], v[38:41]
	v_mfma_f32_16x16x32_bf16 v[34:37], v[170:173], v[236:239], v[34:37]
	v_mfma_f32_16x16x32_bf16 v[78:81], v[166:169], v[182:185], v[78:81]
	v_mfma_f32_16x16x32_bf16 v[70:73], v[174:177], v[182:185], v[70:73]
	v_mfma_f32_16x16x32_bf16 v[62:65], v[166:169], v[206:209], v[62:65]
	v_mfma_f32_16x16x32_bf16 v[54:57], v[174:177], v[206:209], v[54:57]
	v_mfma_f32_16x16x32_bf16 v[46:49], v[166:169], v[232:235], v[46:49]
	v_mfma_f32_16x16x32_bf16 v[42:45], v[174:177], v[232:235], v[42:45]
	v_mfma_f32_16x16x32_bf16 v[38:41], v[166:169], v[240:243], v[38:41]
	v_mfma_f32_16x16x32_bf16 v[34:37], v[174:177], v[240:243], v[34:37]
	s_setprio 0
	s_barrier
; #define PG8_STAGE(bufoff, gbase, voff) do { _Pragma("unroll") for (int _i = 0; _i < 2; ++_i) \
;         __builtin_amdgcn_global_load_lds((const unsigned*)((const char*)(gbase) + (voff)[_i]), (PG8_LAS unsigned*)(lds + (bufoff) + ldsw + _i * 8192), 16, 0, 0); } while (0)
; #define PG8_LDA(dst, b, h) do { _Pragma("unroll") for (int m = 0; m < 4; ++m) _Pragma("unroll") for (int k = 0; k < 2; ++k) dst[m][k] = *(const PG8_LAS bf16x8*)(lds + PG8_SA(b, h) + aoff + m * 2048 + k * 1024); } while (0)
; #define PG8_MMA(ai, bj, At, Bt) do { __builtin_amdgcn_s_setprio(1); _Pragma("unroll") for (int m = 0; m < 4; ++m) _Pragma("unroll") for (int n = 0; n < 2; ++n) _Pragma("unroll") for (int k = 0; k < 2; ++k) \
;         acc[ai][bj][m][n] = __builtin_amdgcn_mfma_f32_16x16x32_bf16(Bt[n][k], At[m][k], acc[ai][bj][m][n], 0, 0, 0); __builtin_amdgcn_s_setprio(0); } while (0)
; #define PG8_WAIT_V(n) asm volatile("s_waitcnt vmcnt(" #n ")" ::: "memory")
; #define PG8_WAIT_L(n) asm volatile("s_waitcnt lgkmcnt(" #n ")" ::: "memory")
; #define PG8_BAR __builtin_amdgcn_s_barrier()
; #define PG8_SCHED __builtin_amdgcn_sched_barrier(0)
; template <class Epi, class Sched, bool ALIGN_EPI = false, bool SP2 = false>
; __device__ __forceinline__ void gemm_phase(PG8_LAS unsigned char* lds, const Gemm g, const Sched& S, const Epi& E) {
;     ...
;             PG8_LDA(At, 1, 1); PG8_STAGE(PG8_SB(1, 0), b3, voffB); PG8_STAGE(PG8_SB(1, 1), b3 + hstepB, voffB); PG8_STAGE(PG8_SA(1, 0), a3, voffA);
;             PG8_WAIT_V(8); PG8_WAIT_L(0); PG8_BAR; PG8_MMA(1, 0, At, B0); PG8_MMA(1, 1, At, B1); PG8_BAR; PG8_SCHED;
	s_add_i32 s22, s57, s38
	s_mov_b32 m0, s22
	ds_read_b128 v[178:181], v143 offset:49152
	ds_read_b128 v[182:185], v143 offset:50176
	ds_read_b128 v[202:205], v143 offset:51200
	ds_read_b128 v[206:209], v143 offset:52224
	ds_read_b128 v[210:213], v143 offset:53248
	ds_read_b128 v[232:235], v143 offset:54272
	ds_read_b128 v[236:239], v143 offset:55296
	ds_read_b128 v[240:243], v143 offset:56320
	global_load_lds_dwordx4 v134, s[60:61]
	s_add_i32 m0, s22, 0x2000
	s_add_u32 s22, s26, 0x20080
	s_addc_u32 s23, s27, 0
	s_add_i32 s26, s58, s38
	global_load_lds_dwordx4 v130, s[60:61]
	s_mov_b32 m0, s26
	s_nop 0
	global_load_lds_dwordx4 v134, s[22:23]
	s_add_i32 m0, s26, 0x2000
	s_nop 0
	global_load_lds_dwordx4 v130, s[22:23]
	s_mov_b32 m0, s43
	s_nop 0
	global_load_lds_dwordx4 v136, s[62:63]
	s_mov_b32 m0, s46
	s_nop 0
	global_load_lds_dwordx4 v132, s[62:63]
	s_waitcnt vmcnt(8)
	s_waitcnt lgkmcnt(0)
	s_barrier
	s_setprio 1
	s_waitcnt lgkmcnt(0)
	v_mfma_f32_16x16x32_bf16 v[94:97], v[146:149], v[178:181], v[94:97]
	v_mfma_f32_16x16x32_bf16 v[90:93], v[154:157], v[178:181], v[90:93]
	v_mfma_f32_16x16x32_bf16 v[86:89], v[146:149], v[202:205], v[86:89]
	v_mfma_f32_16x16x32_bf16 v[82:85], v[154:157], v[202:205], v[82:85]
	v_mfma_f32_16x16x32_bf16 v[74:77], v[146:149], v[210:213], v[74:77]
	v_mfma_f32_16x16x32_bf16 v[66:69], v[154:157], v[210:213], v[66:69]
	v_mfma_f32_16x16x32_bf16 v[58:61], v[146:149], v[236:239], v[58:61]
	v_mfma_f32_16x16x32_bf16 v[50:53], v[154:157], v[236:239], v[50:53]
	v_mfma_f32_16x16x32_bf16 v[94:97], v[150:153], v[182:185], v[94:97]
	v_mfma_f32_16x16x32_bf16 v[90:93], v[158:161], v[182:185], v[90:93]
	v_mfma_f32_16x16x32_bf16 v[86:89], v[150:153], v[206:209], v[86:89]
	v_mfma_f32_16x16x32_bf16 v[82:85], v[158:161], v[206:209], v[82:85]
	v_mfma_f32_16x16x32_bf16 v[74:77], v[150:153], v[232:235], v[74:77]
	v_mfma_f32_16x16x32_bf16 v[66:69], v[158:161], v[232:235], v[66:69]
	v_mfma_f32_16x16x32_bf16 v[58:61], v[150:153], v[240:243], v[58:61]
	v_mfma_f32_16x16x32_bf16 v[50:53], v[158:161], v[240:243], v[50:53]
	s_setprio 0
	s_setprio 1
	v_mfma_f32_16x16x32_bf16 v[30:33], v[162:165], v[178:181], v[30:33]
	v_mfma_f32_16x16x32_bf16 v[26:29], v[170:173], v[178:181], v[26:29]
	v_mfma_f32_16x16x32_bf16 v[22:25], v[162:165], v[202:205], v[22:25]
	v_mfma_f32_16x16x32_bf16 v[18:21], v[170:173], v[202:205], v[18:21]
	v_mfma_f32_16x16x32_bf16 v[14:17], v[162:165], v[210:213], v[14:17]
	v_mfma_f32_16x16x32_bf16 v[10:13], v[170:173], v[210:213], v[10:13]
	v_mfma_f32_16x16x32_bf16 v[6:9], v[162:165], v[236:239], v[6:9]
	v_mfma_f32_16x16x32_bf16 v[2:5], v[170:173], v[236:239], v[2:5]
	v_mfma_f32_16x16x32_bf16 v[30:33], v[166:169], v[182:185], v[30:33]
	v_mfma_f32_16x16x32_bf16 v[26:29], v[174:177], v[182:185], v[26:29]
	v_mfma_f32_16x16x32_bf16 v[22:25], v[166:169], v[206:209], v[22:25]
	v_mfma_f32_16x16x32_bf16 v[18:21], v[174:177], v[206:209], v[18:21]
	v_mfma_f32_16x16x32_bf16 v[14:17], v[166:169], v[232:235], v[14:17]
	v_mfma_f32_16x16x32_bf16 v[10:13], v[174:177], v[232:235], v[10:13]
	v_mfma_f32_16x16x32_bf16 v[6:9], v[166:169], v[240:243], v[6:9]
	v_mfma_f32_16x16x32_bf16 v[2:5], v[174:177], v[240:243], v[2:5]
	s_setprio 0
	s_barrier
	s_add_i32 s56, s56, 2
	s_add_u32 s54, s54, 0x100
	s_addc_u32 s55, s55, 0
	s_cmp_gt_u32 s56, 5
	s_mov_b64 s[22:23], s[24:25]
	s_cbranch_scc0 .LBB0_1160
	s_and_b64 vcc, exec, s[8:9]
	s_cbranch_vccz .LBB0_1163
	s_barrier

; #define PG8_STAGE(bufoff, gbase, voff) do { _Pragma("unroll") for (int _i = 0; _i < 2; ++_i) \
;         __builtin_amdgcn_global_load_lds((const unsigned*)((const char*)(gbase) + (voff)[_i]), (PG8_LAS unsigned*)(lds + (bufoff) + ldsw + _i * 8192), 16, 0, 0); } while (0)
; #define PG8_LDA(dst, b, h) do { _Pragma("unroll") for (int m = 0; m < 4; ++m) _Pragma("unroll") for (int k = 0; k < 2; ++k) dst[m][k] = *(const PG8_LAS bf16x8*)(lds + PG8_SA(b, h) + aoff + m * 2048 + k * 1024); } while (0)
; #define PG8_LDB(dst, b, h) do { _Pragma("unroll") for (int n = 0; n < 2; ++n) _Pragma("unroll") for (int k = 0; k < 2; ++k) dst[n][k] = *(const PG8_LAS bf16x8*)(lds + PG8_SB(b, h) + boff + n * 2048 + k * 1024); } while (0)
; #define PG8_MMA(ai, bj, At, Bt) do { __builtin_amdgcn_s_setprio(1); _Pragma("unroll") for (int m = 0; m < 4; ++m) _Pragma("unroll") for (int n = 0; n < 2; ++n) _Pragma("unroll") for (int k = 0; k < 2; ++k) \
;         acc[ai][bj][m][n] = __builtin_amdgcn_mfma_f32_16x16x32_bf16(Bt[n][k], At[m][k], acc[ai][bj][m][n], 0, 0, 0); __builtin_amdgcn_s_setprio(0); } while (0)
; #define PG8_WAIT_V(n) asm volatile("s_waitcnt vmcnt(" #n ")" ::: "memory")
; #define PG8_WAIT_L(n) asm volatile("s_waitcnt lgkmcnt(" #n ")" ::: "memory")
; #define PG8_BAR __builtin_amdgcn_s_barrier()
; #define PG8_SCHED __builtin_amdgcn_sched_barrier(0)
; template <class Epi, class Sched, bool ALIGN_EPI = false, bool SP2 = false>
; __device__ __forceinline__ void gemm_phase(PG8_LAS unsigned char* lds, const Gemm g, const Sched& S, const Epi& E) {
;     ...
;         for (int t = 0; t < nt; t += 2) {
;             const bool last = (t == nt - 2);
;             const char* a1 = cA + (size_t)(t + 1) * kstep;
;             const char* a2 = last ? nA : cA + (size_t)(t + 2) * kstep; const char* b2 = last ? nB : cB + (size_t)(t + 2) * kstep;
;             const char* a3 = a2 + kstep; const char* b3 = b2 + kstep;
;             if (last && has_next) S.a_ready(nxt);
;             if constexpr (SP2) {
;             PG8_LDB(B0, 0, 0); PG8_LDB(B1, 0, 1); PG8_SCHED; PG8_LDA(At, 0, 0); PG8_STAGE(PG8_SA(1, 1), a1 + hstepA, voffA);
;             PG8_WAIT_V(8); PG8_WAIT_L(0); PG8_BAR; PG8_MMA(0, 0, At, B0); PG8_MMA(0, 1, At, B1); PG8_BAR; PG8_SCHED;
;             PG8_LDA(At, 0, 1); PG8_STAGE(PG8_SB(0, 0), b2, voffB); PG8_STAGE(PG8_SB(0, 1), b2 + hstepB, voffB); PG8_STAGE(PG8_SA(0, 0), a2, voffA);
.LBB0_1190:
	s_add_u32 s24, s22, 0xfffc0080
	s_addc_u32 s25, s23, -1
	s_add_i32 s51, 0, 0x10000
	s_cmp_eq_u32 s50, 12
	s_cselect_b32 s27, s44, s25
	s_cselect_b32 s26, s45, s24
	s_cselect_b32 s25, s46, s49
	s_cselect_b32 s24, s47, s48
	s_add_i32 s54, 0, 0x14000
	v_add_u32_e32 v142, s51, v168
	v_add_u32_e32 v166, s54, v168
	ds_read_b128 v[130:133], v142
	ds_read_b128 v[134:137], v142 offset:1024
	ds_read_b128 v[138:141], v142 offset:2048
	ds_read_b128 v[142:145], v142 offset:3072
	ds_read_b128 v[158:161], v166
	ds_read_b128 v[162:165], v166 offset:1024
	ds_read_b128 v[172:175], v166 offset:2048
	ds_read_b128 v[176:179], v166 offset:3072
	s_add_i32 m0, s7, 0xc000
	ds_read_b128 v[180:183], v171
	ds_read_b128 v[184:187], v171 offset:1024
	ds_read_b128 v[202:205], v171 offset:2048
	ds_read_b128 v[206:209], v171 offset:3072
	ds_read_b128 v[210:213], v171 offset:4096
	ds_read_b128 v[232:235], v171 offset:5120
	ds_read_b128 v[236:239], v171 offset:6144
	ds_read_b128 v[240:243], v171 offset:7168
	global_load_lds_dwordx4 v154, s[22:23]
	s_add_i32 m0, s7, 0xe000
	s_nop 0
	global_load_lds_dwordx4 v156, s[22:23]
	s_waitcnt vmcnt(8)
	s_waitcnt lgkmcnt(0)
	s_barrier
	s_setprio 1
	s_waitcnt lgkmcnt(0)
	v_mfma_f32_16x16x32_bf16 v[126:129], v[130:133], v[180:183], v[126:129]
	v_mfma_f32_16x16x32_bf16 v[118:121], v[138:141], v[180:183], v[118:121]
	v_mfma_f32_16x16x32_bf16 v[110:113], v[130:133], v[202:205], v[110:113]
	v_mfma_f32_16x16x32_bf16 v[102:105], v[138:141], v[202:205], v[102:105]
	v_mfma_f32_16x16x32_bf16 v[94:97], v[130:133], v[210:213], v[94:97]
	v_mfma_f32_16x16x32_bf16 v[86:89], v[138:141], v[210:213], v[86:89]
	v_mfma_f32_16x16x32_bf16 v[78:81], v[130:133], v[236:239], v[78:81]
	v_mfma_f32_16x16x32_bf16 v[70:73], v[138:141], v[236:239], v[70:73]
	v_mfma_f32_16x16x32_bf16 v[126:129], v[134:137], v[184:187], v[126:129]
	v_mfma_f32_16x16x32_bf16 v[118:121], v[142:145], v[184:187], v[118:121]
	v_mfma_f32_16x16x32_bf16 v[110:113], v[134:137], v[206:209], v[110:113]
	v_mfma_f32_16x16x32_bf16 v[102:105], v[142:145], v[206:209], v[102:105]
	v_mfma_f32_16x16x32_bf16 v[94:97], v[134:137], v[232:235], v[94:97]
	v_mfma_f32_16x16x32_bf16 v[86:89], v[142:145], v[232:235], v[86:89]
	v_mfma_f32_16x16x32_bf16 v[78:81], v[134:137], v[240:243], v[78:81]
	v_mfma_f32_16x16x32_bf16 v[70:73], v[142:145], v[240:243], v[70:73]
	s_setprio 0
	s_setprio 1
	v_mfma_f32_16x16x32_bf16 v[122:125], v[158:161], v[180:183], v[122:125]
	v_mfma_f32_16x16x32_bf16 v[114:117], v[172:175], v[180:183], v[114:117]
	v_mfma_f32_16x16x32_bf16 v[106:109], v[158:161], v[202:205], v[106:109]
	v_mfma_f32_16x16x32_bf16 v[98:101], v[172:175], v[202:205], v[98:101]
	v_mfma_f32_16x16x32_bf16 v[90:93], v[158:161], v[210:213], v[90:93]
	v_mfma_f32_16x16x32_bf16 v[82:85], v[172:175], v[210:213], v[82:85]
	v_mfma_f32_16x16x32_bf16 v[74:77], v[158:161], v[236:239], v[74:77]
	v_mfma_f32_16x16x32_bf16 v[66:69], v[172:175], v[236:239], v[66:69]
	v_mfma_f32_16x16x32_bf16 v[122:125], v[162:165], v[184:187], v[122:125]
	v_mfma_f32_16x16x32_bf16 v[114:117], v[176:179], v[184:187], v[114:117]
	v_mfma_f32_16x16x32_bf16 v[106:109], v[162:165], v[206:209], v[106:109]
	v_mfma_f32_16x16x32_bf16 v[98:101], v[176:179], v[206:209], v[98:101]
	v_mfma_f32_16x16x32_bf16 v[90:93], v[162:165], v[232:235], v[90:93]
	v_mfma_f32_16x16x32_bf16 v[82:85], v[176:179], v[232:235], v[82:85]
	v_mfma_f32_16x16x32_bf16 v[74:77], v[162:165], v[240:243], v[74:77]
	v_mfma_f32_16x16x32_bf16 v[66:69], v[176:179], v[240:243], v[66:69]
	s_setprio 0
	s_barrier
	s_add_i32 s51, s51, s30
	s_mov_b32 m0, s51
	ds_read_b128 v[180:183], v171 offset:16384
	ds_read_b128 v[184:187], v171 offset:17408
	ds_read_b128 v[202:205], v171 offset:18432
	ds_read_b128 v[206:209], v171 offset:19456
	ds_read_b128 v[210:213], v171 offset:20480
	ds_read_b128 v[232:235], v171 offset:21504
	ds_read_b128 v[236:239], v171 offset:22528
	ds_read_b128 v[240:243], v171 offset:23552
	s_add_u32 s60, s24, 0x80
	s_addc_u32 s61, s25, 0
	s_add_u32 s62, s26, 0x80
	s_addc_u32 s63, s27, 0
	global_load_lds_dwordx4 v150, s[24:25]
	s_add_i32 m0, s51, 0x2000
	s_add_u32 s52, s24, 0x40000
	s_addc_u32 s53, s25, 0
	s_add_i32 s51, s54, s30
	global_load_lds_dwordx4 v146, s[24:25]
	s_mov_b32 m0, s51
	s_nop 0
	global_load_lds_dwordx4 v150, s[52:53]
	s_add_i32 m0, s51, 0x2000
	s_nop 0
	global_load_lds_dwordx4 v146, s[52:53]
	s_mov_b32 m0, s7
	s_nop 0
	global_load_lds_dwordx4 v152, s[26:27]
	s_mov_b32 m0, s36
	s_nop 0
	global_load_lds_dwordx4 v148, s[26:27]
	s_waitcnt vmcnt(8)
	s_waitcnt lgkmcnt(0)
	s_barrier
; #define PG8_STAGE(bufoff, gbase, voff) do { _Pragma("unroll") for (int _i = 0; _i < 2; ++_i) \
;         __builtin_amdgcn_global_load_lds((const unsigned*)((const char*)(gbase) + (voff)[_i]), (PG8_LAS unsigned*)(lds + (bufoff) + ldsw + _i * 8192), 16, 0, 0); } while (0)
; #define PG8_LDA(dst, b, h) do { _Pragma("unroll") for (int m = 0; m < 4; ++m) _Pragma("unroll") for (int k = 0; k < 2; ++k) dst[m][k] = *(const PG8_LAS bf16x8*)(lds + PG8_SA(b, h) + aoff + m * 2048 + k * 1024); } while (0)
; #define PG8_LDB(dst, b, h) do { _Pragma("unroll") for (int n = 0; n < 2; ++n) _Pragma("unroll") for (int k = 0; k < 2; ++k) dst[n][k] = *(const PG8_LAS bf16x8*)(lds + PG8_SB(b, h) + boff + n * 2048 + k * 1024); } while (0)
; #define PG8_MMA(ai, bj, At, Bt) do { __builtin_amdgcn_s_setprio(1); _Pragma("unroll") for (int m = 0; m < 4; ++m) _Pragma("unroll") for (int n = 0; n < 2; ++n) _Pragma("unroll") for (int k = 0; k < 2; ++k) \
;         acc[ai][bj][m][n] = __builtin_amdgcn_mfma_f32_16x16x32_bf16(Bt[n][k], At[m][k], acc[ai][bj][m][n], 0, 0, 0); __builtin_amdgcn_s_setprio(0); } while (0)
; #define PG8_WAIT_V(n) asm volatile("s_waitcnt vmcnt(" #n ")" ::: "memory")
; #define PG8_WAIT_L(n) asm volatile("s_waitcnt lgkmcnt(" #n ")" ::: "memory")
; #define PG8_BAR __builtin_amdgcn_s_barrier()
; #define PG8_SCHED __builtin_amdgcn_sched_barrier(0)
; template <class Epi, class Sched, bool ALIGN_EPI = false, bool SP2 = false>
; __device__ __forceinline__ void gemm_phase(PG8_LAS unsigned char* lds, const Gemm g, const Sched& S, const Epi& E) {
;     ...
;             PG8_WAIT_V(8); PG8_WAIT_L(0); PG8_BAR; PG8_MMA(1, 0, At, B0); PG8_MMA(1, 1, At, B1); PG8_BAR; PG8_SCHED;
;             PG8_LDB(B0, 1, 0); PG8_LDB(B1, 1, 1); PG8_SCHED; PG8_LDA(At, 1, 0); PG8_STAGE(PG8_SA(0, 1), a2 + hstepA, voffA);
;             PG8_WAIT_V(8); PG8_WAIT_L(0); PG8_BAR; PG8_MMA(0, 0, At, B0); PG8_MMA(0, 1, At, B1); PG8_BAR; PG8_SCHED;
	s_setprio 1
	s_waitcnt lgkmcnt(0)
	v_mfma_f32_16x16x32_bf16 v[62:65], v[130:133], v[180:183], v[62:65]
	v_mfma_f32_16x16x32_bf16 v[54:57], v[138:141], v[180:183], v[54:57]
	v_mfma_f32_16x16x32_bf16 v[46:49], v[130:133], v[202:205], v[46:49]
	v_mfma_f32_16x16x32_bf16 v[38:41], v[138:141], v[202:205], v[38:41]
	v_mfma_f32_16x16x32_bf16 v[30:33], v[130:133], v[210:213], v[30:33]
	v_mfma_f32_16x16x32_bf16 v[22:25], v[138:141], v[210:213], v[22:25]
	v_mfma_f32_16x16x32_bf16 v[14:17], v[130:133], v[236:239], v[14:17]
	v_mfma_f32_16x16x32_bf16 v[6:9], v[138:141], v[236:239], v[6:9]
	v_mfma_f32_16x16x32_bf16 v[62:65], v[134:137], v[184:187], v[62:65]
	v_mfma_f32_16x16x32_bf16 v[54:57], v[142:145], v[184:187], v[54:57]
	v_mfma_f32_16x16x32_bf16 v[46:49], v[134:137], v[206:209], v[46:49]
	v_mfma_f32_16x16x32_bf16 v[38:41], v[142:145], v[206:209], v[38:41]
	v_mfma_f32_16x16x32_bf16 v[30:33], v[134:137], v[232:235], v[30:33]
	v_mfma_f32_16x16x32_bf16 v[22:25], v[142:145], v[232:235], v[22:25]
	v_mfma_f32_16x16x32_bf16 v[14:17], v[134:137], v[240:243], v[14:17]
	v_mfma_f32_16x16x32_bf16 v[6:9], v[142:145], v[240:243], v[6:9]
	s_setprio 0
	s_setprio 1
	v_mfma_f32_16x16x32_bf16 v[58:61], v[158:161], v[180:183], v[58:61]
	v_mfma_f32_16x16x32_bf16 v[50:53], v[172:175], v[180:183], v[50:53]
	v_mfma_f32_16x16x32_bf16 v[42:45], v[158:161], v[202:205], v[42:45]
	v_mfma_f32_16x16x32_bf16 v[34:37], v[172:175], v[202:205], v[34:37]
	v_mfma_f32_16x16x32_bf16 v[26:29], v[158:161], v[210:213], v[26:29]
	v_mfma_f32_16x16x32_bf16 v[18:21], v[172:175], v[210:213], v[18:21]
	v_mfma_f32_16x16x32_bf16 v[10:13], v[158:161], v[236:239], v[10:13]
	v_mfma_f32_16x16x32_bf16 v[2:5], v[172:175], v[236:239], v[2:5]
	v_mfma_f32_16x16x32_bf16 v[58:61], v[162:165], v[184:187], v[58:61]
	v_mfma_f32_16x16x32_bf16 v[50:53], v[176:179], v[184:187], v[50:53]
	v_mfma_f32_16x16x32_bf16 v[42:45], v[162:165], v[206:209], v[42:45]
	v_mfma_f32_16x16x32_bf16 v[34:37], v[176:179], v[206:209], v[34:37]
	v_mfma_f32_16x16x32_bf16 v[26:29], v[162:165], v[232:235], v[26:29]
	v_mfma_f32_16x16x32_bf16 v[18:21], v[176:179], v[232:235], v[18:21]
	v_mfma_f32_16x16x32_bf16 v[10:13], v[162:165], v[240:243], v[10:13]
	v_mfma_f32_16x16x32_bf16 v[2:5], v[176:179], v[240:243], v[2:5]
	s_setprio 0
	s_barrier
	s_add_i32 s51, 0, 0x18000
	s_add_i32 s52, 0, 0x1c000
	v_add_u32_e32 v142, s51, v168
	v_add_u32_e32 v176, s52, v168
	ds_read_b128 v[130:133], v142
	ds_read_b128 v[134:137], v142 offset:1024
	ds_read_b128 v[138:141], v142 offset:2048
	ds_read_b128 v[142:145], v142 offset:3072
	ds_read_b128 v[158:161], v176
	ds_read_b128 v[162:165], v176 offset:1024
	ds_read_b128 v[172:175], v176 offset:2048
	ds_read_b128 v[176:179], v176 offset:3072
	s_add_u32 s26, s26, 0x40000
	s_addc_u32 s27, s27, 0
	s_mov_b32 m0, s37
	ds_read_b128 v[180:183], v171 offset:32768
	ds_read_b128 v[184:187], v171 offset:33792
	ds_read_b128 v[202:205], v171 offset:34816
	ds_read_b128 v[206:209], v171 offset:35840
	ds_read_b128 v[210:213], v171 offset:36864
	ds_read_b128 v[232:235], v171 offset:37888
	ds_read_b128 v[236:239], v171 offset:38912
	ds_read_b128 v[240:243], v171 offset:39936
	global_load_lds_dwordx4 v152, s[26:27]
	s_mov_b32 m0, s38
	s_nop 0
	global_load_lds_dwordx4 v148, s[26:27]
	s_waitcnt vmcnt(8)
	s_waitcnt lgkmcnt(0)
	s_barrier
	s_setprio 1
	s_waitcnt lgkmcnt(0)
	v_mfma_f32_16x16x32_bf16 v[126:129], v[130:133], v[180:183], v[126:129]
	v_mfma_f32_16x16x32_bf16 v[118:121], v[138:141], v[180:183], v[118:121]
	v_mfma_f32_16x16x32_bf16 v[110:113], v[130:133], v[202:205], v[110:113]
	v_mfma_f32_16x16x32_bf16 v[102:105], v[138:141], v[202:205], v[102:105]
	v_mfma_f32_16x16x32_bf16 v[94:97], v[130:133], v[210:213], v[94:97]
	v_mfma_f32_16x16x32_bf16 v[86:89], v[138:141], v[210:213], v[86:89]
	v_mfma_f32_16x16x32_bf16 v[78:81], v[130:133], v[236:239], v[78:81]
	v_mfma_f32_16x16x32_bf16 v[70:73], v[138:141], v[236:239], v[70:73]
	v_mfma_f32_16x16x32_bf16 v[126:129], v[134:137], v[184:187], v[126:129]
	v_mfma_f32_16x16x32_bf16 v[118:121], v[142:145], v[184:187], v[118:121]
	v_mfma_f32_16x16x32_bf16 v[110:113], v[134:137], v[206:209], v[110:113]
	v_mfma_f32_16x16x32_bf16 v[102:105], v[142:145], v[206:209], v[102:105]
	v_mfma_f32_16x16x32_bf16 v[94:97], v[134:137], v[232:235], v[94:97]
	v_mfma_f32_16x16x32_bf16 v[86:89], v[142:145], v[232:235], v[86:89]
	v_mfma_f32_16x16x32_bf16 v[78:81], v[134:137], v[240:243], v[78:81]
	v_mfma_f32_16x16x32_bf16 v[70:73], v[142:145], v[240:243], v[70:73]
	s_setprio 0
	s_setprio 1
	v_mfma_f32_16x16x32_bf16 v[122:125], v[158:161], v[180:183], v[122:125]
	v_mfma_f32_16x16x32_bf16 v[114:117], v[172:175], v[180:183], v[114:117]
	v_mfma_f32_16x16x32_bf16 v[106:109], v[158:161], v[202:205], v[106:109]
	v_mfma_f32_16x16x32_bf16 v[98:101], v[172:175], v[202:205], v[98:101]
	v_mfma_f32_16x16x32_bf16 v[90:93], v[158:161], v[210:213], v[90:93]
	v_mfma_f32_16x16x32_bf16 v[82:85], v[172:175], v[210:213], v[82:85]
	v_mfma_f32_16x16x32_bf16 v[74:77], v[158:161], v[236:239], v[74:77]
	v_mfma_f32_16x16x32_bf16 v[66:69], v[172:175], v[236:239], v[66:69]
	v_mfma_f32_16x16x32_bf16 v[122:125], v[162:165], v[184:187], v[122:125]
	v_mfma_f32_16x16x32_bf16 v[114:117], v[176:179], v[184:187], v[114:117]
	v_mfma_f32_16x16x32_bf16 v[106:109], v[162:165], v[206:209], v[106:109]
	v_mfma_f32_16x16x32_bf16 v[98:101], v[176:179], v[206:209], v[98:101]
	v_mfma_f32_16x16x32_bf16 v[90:93], v[162:165], v[232:235], v[90:93]
	v_mfma_f32_16x16x32_bf16 v[82:85], v[176:179], v[232:235], v[82:85]
	v_mfma_f32_16x16x32_bf16 v[74:77], v[162:165], v[240:243], v[74:77]
	v_mfma_f32_16x16x32_bf16 v[66:69], v[176:179], v[240:243], v[66:69]
	s_setprio 0
	s_barrier
; #define PG8_STAGE(bufoff, gbase, voff) do { _Pragma("unroll") for (int _i = 0; _i < 2; ++_i) \
;         __builtin_amdgcn_global_load_lds((const unsigned*)((const char*)(gbase) + (voff)[_i]), (PG8_LAS unsigned*)(lds + (bufoff) + ldsw + _i * 8192), 16, 0, 0); } while (0)
; #define PG8_LDA(dst, b, h) do { _Pragma("unroll") for (int m = 0; m < 4; ++m) _Pragma("unroll") for (int k = 0; k < 2; ++k) dst[m][k] = *(const PG8_LAS bf16x8*)(lds + PG8_SA(b, h) + aoff + m * 2048 + k * 1024); } while (0)
; #define PG8_MMA(ai, bj, At, Bt) do { __builtin_amdgcn_s_setprio(1); _Pragma("unroll") for (int m = 0; m < 4; ++m) _Pragma("unroll") for (int n = 0; n < 2; ++n) _Pragma("unroll") for (int k = 0; k < 2; ++k) \
;         acc[ai][bj][m][n] = __builtin_amdgcn_mfma_f32_16x16x32_bf16(Bt[n][k], At[m][k], acc[ai][bj][m][n], 0, 0, 0); __builtin_amdgcn_s_setprio(0); } while (0)
; #define PG8_WAIT_V(n) asm volatile("s_waitcnt vmcnt(" #n ")" ::: "memory")
; #define PG8_WAIT_L(n) asm volatile("s_waitcnt lgkmcnt(" #n ")" ::: "memory")
; #define PG8_BAR __builtin_amdgcn_s_barrier()
; #define PG8_SCHED __builtin_amdgcn_sched_barrier(0)
; template <class Epi, class Sched, bool ALIGN_EPI = false, bool SP2 = false>
; __device__ __forceinline__ void gemm_phase(PG8_LAS unsigned char* lds, const Gemm g, const Sched& S, const Epi& E) {
;     ...
;             PG8_LDA(At, 1, 1); PG8_STAGE(PG8_SB(1, 0), b3, voffB); PG8_STAGE(PG8_SB(1, 1), b3 + hstepB, voffB); PG8_STAGE(PG8_SA(1, 0), a3, voffA);
;             PG8_WAIT_V(8); PG8_WAIT_L(0); PG8_BAR; PG8_MMA(1, 0, At, B0); PG8_MMA(1, 1, At, B1); PG8_BAR; PG8_SCHED;
	s_add_i32 s26, s51, s30
	s_mov_b32 m0, s26
	ds_read_b128 v[180:183], v171 offset:49152
	ds_read_b128 v[184:187], v171 offset:50176
	ds_read_b128 v[202:205], v171 offset:51200
	ds_read_b128 v[206:209], v171 offset:52224
	ds_read_b128 v[210:213], v171 offset:53248
	ds_read_b128 v[232:235], v171 offset:54272
	ds_read_b128 v[236:239], v171 offset:55296
	ds_read_b128 v[240:243], v171 offset:56320
	global_load_lds_dwordx4 v150, s[60:61]
	s_add_i32 m0, s26, 0x2000
	s_add_u32 s24, s24, 0x40080
	s_addc_u32 s25, s25, 0
	s_add_i32 s26, s52, s30
	global_load_lds_dwordx4 v146, s[60:61]
	s_mov_b32 m0, s26
	s_nop 0
	global_load_lds_dwordx4 v150, s[24:25]
	s_add_i32 m0, s26, 0x2000
	s_nop 0
	global_load_lds_dwordx4 v146, s[24:25]
	s_mov_b32 m0, s39
	s_nop 0
	global_load_lds_dwordx4 v152, s[62:63]
	s_mov_b32 m0, s40
	s_nop 0
	global_load_lds_dwordx4 v148, s[62:63]
	s_waitcnt vmcnt(8)
	s_waitcnt lgkmcnt(0)
	s_barrier
	s_setprio 1
	s_waitcnt lgkmcnt(0)
	v_mfma_f32_16x16x32_bf16 v[62:65], v[130:133], v[180:183], v[62:65]
	v_mfma_f32_16x16x32_bf16 v[54:57], v[138:141], v[180:183], v[54:57]
	v_mfma_f32_16x16x32_bf16 v[46:49], v[130:133], v[202:205], v[46:49]
	v_mfma_f32_16x16x32_bf16 v[38:41], v[138:141], v[202:205], v[38:41]
	v_mfma_f32_16x16x32_bf16 v[30:33], v[130:133], v[210:213], v[30:33]
	v_mfma_f32_16x16x32_bf16 v[22:25], v[138:141], v[210:213], v[22:25]
	v_mfma_f32_16x16x32_bf16 v[14:17], v[130:133], v[236:239], v[14:17]
	v_mfma_f32_16x16x32_bf16 v[6:9], v[138:141], v[236:239], v[6:9]
	v_mfma_f32_16x16x32_bf16 v[62:65], v[134:137], v[184:187], v[62:65]
	v_mfma_f32_16x16x32_bf16 v[54:57], v[142:145], v[184:187], v[54:57]
	v_mfma_f32_16x16x32_bf16 v[46:49], v[134:137], v[206:209], v[46:49]
	v_mfma_f32_16x16x32_bf16 v[38:41], v[142:145], v[206:209], v[38:41]
	v_mfma_f32_16x16x32_bf16 v[30:33], v[134:137], v[232:235], v[30:33]
	v_mfma_f32_16x16x32_bf16 v[22:25], v[142:145], v[232:235], v[22:25]
	v_mfma_f32_16x16x32_bf16 v[14:17], v[134:137], v[240:243], v[14:17]
	v_mfma_f32_16x16x32_bf16 v[6:9], v[142:145], v[240:243], v[6:9]
	s_setprio 0
	s_setprio 1
	v_mfma_f32_16x16x32_bf16 v[58:61], v[158:161], v[180:183], v[58:61]
	v_mfma_f32_16x16x32_bf16 v[50:53], v[172:175], v[180:183], v[50:53]
	v_mfma_f32_16x16x32_bf16 v[42:45], v[158:161], v[202:205], v[42:45]
	v_mfma_f32_16x16x32_bf16 v[34:37], v[172:175], v[202:205], v[34:37]
	v_mfma_f32_16x16x32_bf16 v[26:29], v[158:161], v[210:213], v[26:29]
	v_mfma_f32_16x16x32_bf16 v[18:21], v[172:175], v[210:213], v[18:21]
	v_mfma_f32_16x16x32_bf16 v[10:13], v[158:161], v[236:239], v[10:13]
	v_mfma_f32_16x16x32_bf16 v[2:5], v[172:175], v[236:239], v[2:5]
	v_mfma_f32_16x16x32_bf16 v[58:61], v[162:165], v[184:187], v[58:61]
	v_mfma_f32_16x16x32_bf16 v[50:53], v[176:179], v[184:187], v[50:53]
	v_mfma_f32_16x16x32_bf16 v[42:45], v[162:165], v[206:209], v[42:45]
	v_mfma_f32_16x16x32_bf16 v[34:37], v[176:179], v[206:209], v[34:37]
	v_mfma_f32_16x16x32_bf16 v[26:29], v[162:165], v[232:235], v[26:29]
	v_mfma_f32_16x16x32_bf16 v[18:21], v[176:179], v[232:235], v[18:21]
	v_mfma_f32_16x16x32_bf16 v[10:13], v[162:165], v[240:243], v[10:13]
	v_mfma_f32_16x16x32_bf16 v[2:5], v[176:179], v[240:243], v[2:5]
	s_setprio 0
	s_barrier
	s_add_i32 s50, s50, 2
	s_add_u32 s22, s22, 0x100
	s_addc_u32 s23, s23, 0
	s_add_u32 s48, s48, 0x100
	s_addc_u32 s49, s49, 0
	s_cmp_gt_u32 s50, 13
	s_cbranch_scc0 .LBB0_1190
	s_and_b64 vcc, exec, s[18:19]
	s_cbranch_vccz .LBB0_1193
	s_barrier

; #define PG8_STAGE(bufoff, gbase, voff) do { _Pragma("unroll") for (int _i = 0; _i < 2; ++_i) \
;         __builtin_amdgcn_global_load_lds((const unsigned*)((const char*)(gbase) + (voff)[_i]), (PG8_LAS unsigned*)(lds + (bufoff) + ldsw + _i * 8192), 16, 0, 0); } while (0)
; #define PG8_LDA(dst, b, h) do { _Pragma("unroll") for (int m = 0; m < 4; ++m) _Pragma("unroll") for (int k = 0; k < 2; ++k) dst[m][k] = *(const PG8_LAS bf16x8*)(lds + PG8_SA(b, h) + aoff + m * 2048 + k * 1024); } while (0)
; #define PG8_LDB(dst, b, h) do { _Pragma("unroll") for (int n = 0; n < 2; ++n) _Pragma("unroll") for (int k = 0; k < 2; ++k) dst[n][k] = *(const PG8_LAS bf16x8*)(lds + PG8_SB(b, h) + boff + n * 2048 + k * 1024); } while (0)
; #define PG8_MMA(ai, bj, At, Bt) do { __builtin_amdgcn_s_setprio(1); _Pragma("unroll") for (int m = 0; m < 4; ++m) _Pragma("unroll") for (int n = 0; n < 2; ++n) _Pragma("unroll") for (int k = 0; k < 2; ++k) \
;         acc[ai][bj][m][n] = __builtin_amdgcn_mfma_f32_16x16x32_bf16(Bt[n][k], At[m][k], acc[ai][bj][m][n], 0, 0, 0); __builtin_amdgcn_s_setprio(0); } while (0)
; #define PG8_WAIT_V(n) asm volatile("s_waitcnt vmcnt(" #n ")" ::: "memory")
; #define PG8_WAIT_L(n) asm volatile("s_waitcnt lgkmcnt(" #n ")" ::: "memory")
; #define PG8_BAR __builtin_amdgcn_s_barrier()
; #define PG8_SCHED __builtin_amdgcn_sched_barrier(0)
; template <class Epi, class Sched, bool ALIGN_EPI = false, bool SP2 = false>
; __device__ __forceinline__ void gemm_phase(PG8_LAS unsigned char* lds, const Gemm g, const Sched& S, const Epi& E) {
;     ...
;         for (int t = 0; t < nt; t += 2) {
;             const bool last = (t == nt - 2);
;             const char* a1 = cA + (size_t)(t + 1) * kstep;
;             const char* a2 = last ? nA : cA + (size_t)(t + 2) * kstep; const char* b2 = last ? nB : cB + (size_t)(t + 2) * kstep;
;             const char* a3 = a2 + kstep; const char* b3 = b2 + kstep;
;             if (last && has_next) S.a_ready(nxt);
;             if constexpr (SP2) {
;             PG8_LDB(B0, 0, 0); PG8_LDB(B1, 0, 1); PG8_SCHED; PG8_LDA(At, 0, 0); PG8_STAGE(PG8_SA(1, 1), a1 + hstepA, voffA);
;             PG8_WAIT_V(8); PG8_WAIT_L(0); PG8_BAR; PG8_MMA(0, 0, At, B0); PG8_MMA(0, 1, At, B1); PG8_BAR; PG8_SCHED;
;             PG8_LDA(At, 0, 1); PG8_STAGE(PG8_SB(0, 0), b2, voffB); PG8_STAGE(PG8_SB(0, 1), b2 + hstepB, voffB); PG8_STAGE(PG8_SA(0, 0), a2, voffA);
.LBB0_1270:
	s_add_u32 s28, s26, 0xfffc0080
	s_addc_u32 s29, s27, -1
	s_add_i32 s52, 0, 0x10000
	s_cmp_eq_u32 s51, 12
	s_cselect_b32 s31, s17, s29
	s_cselect_b32 s30, s23, s28
	s_cselect_b32 s29, s15, s50
	s_cselect_b32 s28, s25, s49
	s_add_i32 s54, 0, 0x14000
	v_add_u32_e32 v142, s52, v186
	v_add_u32_e32 v172, s54, v186
	ds_read_b128 v[130:133], v142
	ds_read_b128 v[134:137], v142 offset:1024
	ds_read_b128 v[138:141], v142 offset:2048
	ds_read_b128 v[142:145], v142 offset:3072
	ds_read_b128 v[146:149], v172
	ds_read_b128 v[150:153], v172 offset:1024
	ds_read_b128 v[168:171], v172 offset:2048
	ds_read_b128 v[172:175], v172 offset:3072
	s_add_i32 m0, s39, 0xc000
	ds_read_b128 v[176:179], v200
	ds_read_b128 v[180:183], v200 offset:1024
	ds_read_b128 v[202:205], v200 offset:2048
	ds_read_b128 v[206:209], v200 offset:3072
	ds_read_b128 v[210:213], v200 offset:4096
	ds_read_b128 v[232:235], v200 offset:5120
	ds_read_b128 v[236:239], v200 offset:6144
	ds_read_b128 v[240:243], v200 offset:7168
	global_load_lds_dwordx4 v164, s[26:27]
	s_add_i32 m0, s39, 0xe000
	s_nop 0
	global_load_lds_dwordx4 v166, s[26:27]
	s_waitcnt vmcnt(8)
	s_waitcnt lgkmcnt(0)
	s_barrier
	s_setprio 1
	s_waitcnt lgkmcnt(0)
	v_mfma_f32_16x16x32_bf16 v[126:129], v[130:133], v[176:179], v[126:129]
	v_mfma_f32_16x16x32_bf16 v[122:125], v[138:141], v[176:179], v[122:125]
	v_mfma_f32_16x16x32_bf16 v[110:113], v[130:133], v[202:205], v[110:113]
	v_mfma_f32_16x16x32_bf16 v[106:109], v[138:141], v[202:205], v[106:109]
	v_mfma_f32_16x16x32_bf16 v[94:97], v[130:133], v[210:213], v[94:97]
	v_mfma_f32_16x16x32_bf16 v[90:93], v[138:141], v[210:213], v[90:93]
	v_mfma_f32_16x16x32_bf16 v[78:81], v[130:133], v[236:239], v[78:81]
	v_mfma_f32_16x16x32_bf16 v[74:77], v[138:141], v[236:239], v[74:77]
	v_mfma_f32_16x16x32_bf16 v[126:129], v[134:137], v[180:183], v[126:129]
	v_mfma_f32_16x16x32_bf16 v[122:125], v[142:145], v[180:183], v[122:125]
	v_mfma_f32_16x16x32_bf16 v[110:113], v[134:137], v[206:209], v[110:113]
	v_mfma_f32_16x16x32_bf16 v[106:109], v[142:145], v[206:209], v[106:109]
	v_mfma_f32_16x16x32_bf16 v[94:97], v[134:137], v[232:235], v[94:97]
	v_mfma_f32_16x16x32_bf16 v[90:93], v[142:145], v[232:235], v[90:93]
	v_mfma_f32_16x16x32_bf16 v[78:81], v[134:137], v[240:243], v[78:81]
	v_mfma_f32_16x16x32_bf16 v[74:77], v[142:145], v[240:243], v[74:77]
	s_setprio 0
	s_setprio 1
	v_mfma_f32_16x16x32_bf16 v[118:121], v[146:149], v[176:179], v[118:121]
	v_mfma_f32_16x16x32_bf16 v[114:117], v[168:171], v[176:179], v[114:117]
	v_mfma_f32_16x16x32_bf16 v[102:105], v[146:149], v[202:205], v[102:105]
	v_mfma_f32_16x16x32_bf16 v[98:101], v[168:171], v[202:205], v[98:101]
	v_mfma_f32_16x16x32_bf16 v[86:89], v[146:149], v[210:213], v[86:89]
	v_mfma_f32_16x16x32_bf16 v[82:85], v[168:171], v[210:213], v[82:85]
	v_mfma_f32_16x16x32_bf16 v[70:73], v[146:149], v[236:239], v[70:73]
	v_mfma_f32_16x16x32_bf16 v[66:69], v[168:171], v[236:239], v[66:69]
	v_mfma_f32_16x16x32_bf16 v[118:121], v[150:153], v[180:183], v[118:121]
	v_mfma_f32_16x16x32_bf16 v[114:117], v[172:175], v[180:183], v[114:117]
	v_mfma_f32_16x16x32_bf16 v[102:105], v[150:153], v[206:209], v[102:105]
	v_mfma_f32_16x16x32_bf16 v[98:101], v[172:175], v[206:209], v[98:101]
	v_mfma_f32_16x16x32_bf16 v[86:89], v[150:153], v[232:235], v[86:89]
	v_mfma_f32_16x16x32_bf16 v[82:85], v[172:175], v[232:235], v[82:85]
	v_mfma_f32_16x16x32_bf16 v[70:73], v[150:153], v[240:243], v[70:73]
	v_mfma_f32_16x16x32_bf16 v[66:69], v[172:175], v[240:243], v[66:69]
	s_setprio 0
	s_barrier
	s_add_i32 s52, s52, s38
	s_mov_b32 m0, s52
	ds_read_b128 v[176:179], v200 offset:16384
	ds_read_b128 v[180:183], v200 offset:17408
	ds_read_b128 v[202:205], v200 offset:18432
	ds_read_b128 v[206:209], v200 offset:19456
	ds_read_b128 v[210:213], v200 offset:20480
	ds_read_b128 v[232:235], v200 offset:21504
	ds_read_b128 v[236:239], v200 offset:22528
	ds_read_b128 v[240:243], v200 offset:23552
	s_add_u32 s60, s28, 0x80
	s_addc_u32 s61, s29, 0
	s_add_u32 s62, s30, 0x80
	s_addc_u32 s63, s31, 0
	global_load_lds_dwordx4 v156, s[28:29]
	s_add_i32 m0, s52, 0x2000
	s_add_u32 s52, s28, 0x40000
	s_addc_u32 s53, s29, 0
	s_add_i32 s54, s54, s38
	global_load_lds_dwordx4 v160, s[28:29]
	s_mov_b32 m0, s54
	s_nop 0
	global_load_lds_dwordx4 v156, s[52:53]
	s_add_i32 m0, s54, 0x2000
	s_nop 0
	global_load_lds_dwordx4 v160, s[52:53]
	s_mov_b32 m0, s39
	s_nop 0
	global_load_lds_dwordx4 v154, s[30:31]
	s_mov_b32 m0, s40
	s_nop 0
	global_load_lds_dwordx4 v158, s[30:31]
	s_waitcnt vmcnt(8)
	s_waitcnt lgkmcnt(0)
	s_barrier
; #define PG8_STAGE(bufoff, gbase, voff) do { _Pragma("unroll") for (int _i = 0; _i < 2; ++_i) \
;         __builtin_amdgcn_global_load_lds((const unsigned*)((const char*)(gbase) + (voff)[_i]), (PG8_LAS unsigned*)(lds + (bufoff) + ldsw + _i * 8192), 16, 0, 0); } while (0)
; #define PG8_LDA(dst, b, h) do { _Pragma("unroll") for (int m = 0; m < 4; ++m) _Pragma("unroll") for (int k = 0; k < 2; ++k) dst[m][k] = *(const PG8_LAS bf16x8*)(lds + PG8_SA(b, h) + aoff + m * 2048 + k * 1024); } while (0)
; #define PG8_LDB(dst, b, h) do { _Pragma("unroll") for (int n = 0; n < 2; ++n) _Pragma("unroll") for (int k = 0; k < 2; ++k) dst[n][k] = *(const PG8_LAS bf16x8*)(lds + PG8_SB(b, h) + boff + n * 2048 + k * 1024); } while (0)
; #define PG8_MMA(ai, bj, At, Bt) do { __builtin_amdgcn_s_setprio(1); _Pragma("unroll") for (int m = 0; m < 4; ++m) _Pragma("unroll") for (int n = 0; n < 2; ++n) _Pragma("unroll") for (int k = 0; k < 2; ++k) \
;         acc[ai][bj][m][n] = __builtin_amdgcn_mfma_f32_16x16x32_bf16(Bt[n][k], At[m][k], acc[ai][bj][m][n], 0, 0, 0); __builtin_amdgcn_s_setprio(0); } while (0)
; #define PG8_WAIT_V(n) asm volatile("s_waitcnt vmcnt(" #n ")" ::: "memory")
; #define PG8_WAIT_L(n) asm volatile("s_waitcnt lgkmcnt(" #n ")" ::: "memory")
; #define PG8_BAR __builtin_amdgcn_s_barrier()
; #define PG8_SCHED __builtin_amdgcn_sched_barrier(0)
; template <class Epi, class Sched, bool ALIGN_EPI = false, bool SP2 = false>
; __device__ __forceinline__ void gemm_phase(PG8_LAS unsigned char* lds, const Gemm g, const Sched& S, const Epi& E) {
;     ...
;             PG8_WAIT_V(8); PG8_WAIT_L(0); PG8_BAR; PG8_MMA(1, 0, At, B0); PG8_MMA(1, 1, At, B1); PG8_BAR; PG8_SCHED;
;             PG8_LDB(B0, 1, 0); PG8_LDB(B1, 1, 1); PG8_SCHED; PG8_LDA(At, 1, 0); PG8_STAGE(PG8_SA(0, 1), a2 + hstepA, voffA);
;             PG8_WAIT_V(8); PG8_WAIT_L(0); PG8_BAR; PG8_MMA(0, 0, At, B0); PG8_MMA(0, 1, At, B1); PG8_BAR; PG8_SCHED;
	s_setprio 1
	s_waitcnt lgkmcnt(0)
	v_mfma_f32_16x16x32_bf16 v[62:65], v[130:133], v[176:179], v[62:65]
	v_mfma_f32_16x16x32_bf16 v[58:61], v[138:141], v[176:179], v[58:61]
	v_mfma_f32_16x16x32_bf16 v[46:49], v[130:133], v[202:205], v[46:49]
	v_mfma_f32_16x16x32_bf16 v[42:45], v[138:141], v[202:205], v[42:45]
	v_mfma_f32_16x16x32_bf16 v[30:33], v[130:133], v[210:213], v[30:33]
	v_mfma_f32_16x16x32_bf16 v[26:29], v[138:141], v[210:213], v[26:29]
	v_mfma_f32_16x16x32_bf16 v[14:17], v[130:133], v[236:239], v[14:17]
	v_mfma_f32_16x16x32_bf16 v[10:13], v[138:141], v[236:239], v[10:13]
	v_mfma_f32_16x16x32_bf16 v[62:65], v[134:137], v[180:183], v[62:65]
	v_mfma_f32_16x16x32_bf16 v[58:61], v[142:145], v[180:183], v[58:61]
	v_mfma_f32_16x16x32_bf16 v[46:49], v[134:137], v[206:209], v[46:49]
	v_mfma_f32_16x16x32_bf16 v[42:45], v[142:145], v[206:209], v[42:45]
	v_mfma_f32_16x16x32_bf16 v[30:33], v[134:137], v[232:235], v[30:33]
	v_mfma_f32_16x16x32_bf16 v[26:29], v[142:145], v[232:235], v[26:29]
	v_mfma_f32_16x16x32_bf16 v[14:17], v[134:137], v[240:243], v[14:17]
	v_mfma_f32_16x16x32_bf16 v[10:13], v[142:145], v[240:243], v[10:13]
	s_setprio 0
	s_setprio 1
	v_mfma_f32_16x16x32_bf16 v[54:57], v[146:149], v[176:179], v[54:57]
	v_mfma_f32_16x16x32_bf16 v[50:53], v[168:171], v[176:179], v[50:53]
	v_mfma_f32_16x16x32_bf16 v[38:41], v[146:149], v[202:205], v[38:41]
	v_mfma_f32_16x16x32_bf16 v[34:37], v[168:171], v[202:205], v[34:37]
	v_mfma_f32_16x16x32_bf16 v[22:25], v[146:149], v[210:213], v[22:25]
	v_mfma_f32_16x16x32_bf16 v[18:21], v[168:171], v[210:213], v[18:21]
	v_mfma_f32_16x16x32_bf16 v[6:9], v[146:149], v[236:239], v[6:9]
	v_mfma_f32_16x16x32_bf16 v[2:5], v[168:171], v[236:239], v[2:5]
	v_mfma_f32_16x16x32_bf16 v[54:57], v[150:153], v[180:183], v[54:57]
	v_mfma_f32_16x16x32_bf16 v[50:53], v[172:175], v[180:183], v[50:53]
	v_mfma_f32_16x16x32_bf16 v[38:41], v[150:153], v[206:209], v[38:41]
	v_mfma_f32_16x16x32_bf16 v[34:37], v[172:175], v[206:209], v[34:37]
	v_mfma_f32_16x16x32_bf16 v[22:25], v[150:153], v[232:235], v[22:25]
	v_mfma_f32_16x16x32_bf16 v[18:21], v[172:175], v[232:235], v[18:21]
	v_mfma_f32_16x16x32_bf16 v[6:9], v[150:153], v[240:243], v[6:9]
	v_mfma_f32_16x16x32_bf16 v[2:5], v[172:175], v[240:243], v[2:5]
	s_setprio 0
	s_barrier
	s_add_i32 s52, 0, 0x18000
	s_add_i32 s53, 0, 0x1c000
	v_add_u32_e32 v142, s52, v186
	v_add_u32_e32 v172, s53, v186
	ds_read_b128 v[130:133], v142
	ds_read_b128 v[134:137], v142 offset:1024
	ds_read_b128 v[138:141], v142 offset:2048
	ds_read_b128 v[142:145], v142 offset:3072
	ds_read_b128 v[146:149], v172
	ds_read_b128 v[150:153], v172 offset:1024
	ds_read_b128 v[168:171], v172 offset:2048
	ds_read_b128 v[172:175], v172 offset:3072
	s_add_u32 s30, s30, 0x40000
	s_addc_u32 s31, s31, 0
	s_mov_b32 m0, s41
	ds_read_b128 v[176:179], v200 offset:32768
	ds_read_b128 v[180:183], v200 offset:33792
	ds_read_b128 v[202:205], v200 offset:34816
	ds_read_b128 v[206:209], v200 offset:35840
	ds_read_b128 v[210:213], v200 offset:36864
	ds_read_b128 v[232:235], v200 offset:37888
	ds_read_b128 v[236:239], v200 offset:38912
	ds_read_b128 v[240:243], v200 offset:39936
	global_load_lds_dwordx4 v154, s[30:31]
	s_mov_b32 m0, s42
	s_nop 0
	global_load_lds_dwordx4 v158, s[30:31]
	s_waitcnt vmcnt(8)
	s_waitcnt lgkmcnt(0)
	s_barrier
	s_setprio 1
	s_waitcnt lgkmcnt(0)
	v_mfma_f32_16x16x32_bf16 v[126:129], v[130:133], v[176:179], v[126:129]
	v_mfma_f32_16x16x32_bf16 v[122:125], v[138:141], v[176:179], v[122:125]
	v_mfma_f32_16x16x32_bf16 v[110:113], v[130:133], v[202:205], v[110:113]
	v_mfma_f32_16x16x32_bf16 v[106:109], v[138:141], v[202:205], v[106:109]
	v_mfma_f32_16x16x32_bf16 v[94:97], v[130:133], v[210:213], v[94:97]
	v_mfma_f32_16x16x32_bf16 v[90:93], v[138:141], v[210:213], v[90:93]
	v_mfma_f32_16x16x32_bf16 v[78:81], v[130:133], v[236:239], v[78:81]
	v_mfma_f32_16x16x32_bf16 v[74:77], v[138:141], v[236:239], v[74:77]
	v_mfma_f32_16x16x32_bf16 v[126:129], v[134:137], v[180:183], v[126:129]
	v_mfma_f32_16x16x32_bf16 v[122:125], v[142:145], v[180:183], v[122:125]
	v_mfma_f32_16x16x32_bf16 v[110:113], v[134:137], v[206:209], v[110:113]
	v_mfma_f32_16x16x32_bf16 v[106:109], v[142:145], v[206:209], v[106:109]
	v_mfma_f32_16x16x32_bf16 v[94:97], v[134:137], v[232:235], v[94:97]
	v_mfma_f32_16x16x32_bf16 v[90:93], v[142:145], v[232:235], v[90:93]
	v_mfma_f32_16x16x32_bf16 v[78:81], v[134:137], v[240:243], v[78:81]
	v_mfma_f32_16x16x32_bf16 v[74:77], v[142:145], v[240:243], v[74:77]
	s_setprio 0
	s_setprio 1
	v_mfma_f32_16x16x32_bf16 v[118:121], v[146:149], v[176:179], v[118:121]
	v_mfma_f32_16x16x32_bf16 v[114:117], v[168:171], v[176:179], v[114:117]
	v_mfma_f32_16x16x32_bf16 v[102:105], v[146:149], v[202:205], v[102:105]
	v_mfma_f32_16x16x32_bf16 v[98:101], v[168:171], v[202:205], v[98:101]
	v_mfma_f32_16x16x32_bf16 v[86:89], v[146:149], v[210:213], v[86:89]
	v_mfma_f32_16x16x32_bf16 v[82:85], v[168:171], v[210:213], v[82:85]
	v_mfma_f32_16x16x32_bf16 v[70:73], v[146:149], v[236:239], v[70:73]
	v_mfma_f32_16x16x32_bf16 v[66:69], v[168:171], v[236:239], v[66:69]
	v_mfma_f32_16x16x32_bf16 v[118:121], v[150:153], v[180:183], v[118:121]
	v_mfma_f32_16x16x32_bf16 v[114:117], v[172:175], v[180:183], v[114:117]
	v_mfma_f32_16x16x32_bf16 v[102:105], v[150:153], v[206:209], v[102:105]
	v_mfma_f32_16x16x32_bf16 v[98:101], v[172:175], v[206:209], v[98:101]
	v_mfma_f32_16x16x32_bf16 v[86:89], v[150:153], v[232:235], v[86:89]
	v_mfma_f32_16x16x32_bf16 v[82:85], v[172:175], v[232:235], v[82:85]
	v_mfma_f32_16x16x32_bf16 v[70:73], v[150:153], v[240:243], v[70:73]
	v_mfma_f32_16x16x32_bf16 v[66:69], v[172:175], v[240:243], v[66:69]
	s_setprio 0
	s_barrier
; #define PG8_STAGE(bufoff, gbase, voff) do { _Pragma("unroll") for (int _i = 0; _i < 2; ++_i) \
;         __builtin_amdgcn_global_load_lds((const unsigned*)((const char*)(gbase) + (voff)[_i]), (PG8_LAS unsigned*)(lds + (bufoff) + ldsw + _i * 8192), 16, 0, 0); } while (0)
; #define PG8_LDA(dst, b, h) do { _Pragma("unroll") for (int m = 0; m < 4; ++m) _Pragma("unroll") for (int k = 0; k < 2; ++k) dst[m][k] = *(const PG8_LAS bf16x8*)(lds + PG8_SA(b, h) + aoff + m * 2048 + k * 1024); } while (0)
; #define PG8_MMA(ai, bj, At, Bt) do { __builtin_amdgcn_s_setprio(1); _Pragma("unroll") for (int m = 0; m < 4; ++m) _Pragma("unroll") for (int n = 0; n < 2; ++n) _Pragma("unroll") for (int k = 0; k < 2; ++k) \
;         acc[ai][bj][m][n] = __builtin_amdgcn_mfma_f32_16x16x32_bf16(Bt[n][k], At[m][k], acc[ai][bj][m][n], 0, 0, 0); __builtin_amdgcn_s_setprio(0); } while (0)
; #define PG8_WAIT_V(n) asm volatile("s_waitcnt vmcnt(" #n ")" ::: "memory")
; #define PG8_WAIT_L(n) asm volatile("s_waitcnt lgkmcnt(" #n ")" ::: "memory")
; #define PG8_BAR __builtin_amdgcn_s_barrier()
; #define PG8_SCHED __builtin_amdgcn_sched_barrier(0)
; template <class Epi, class Sched, bool ALIGN_EPI = false, bool SP2 = false>
; __device__ __forceinline__ void gemm_phase(PG8_LAS unsigned char* lds, const Gemm g, const Sched& S, const Epi& E) {
;     ...
;             PG8_LDA(At, 1, 1); PG8_STAGE(PG8_SB(1, 0), b3, voffB); PG8_STAGE(PG8_SB(1, 1), b3 + hstepB, voffB); PG8_STAGE(PG8_SA(1, 0), a3, voffA);
;             PG8_WAIT_V(8); PG8_WAIT_L(0); PG8_BAR; PG8_MMA(1, 0, At, B0); PG8_MMA(1, 1, At, B1); PG8_BAR; PG8_SCHED;
	s_add_i32 s30, s52, s38
	s_mov_b32 m0, s30
	ds_read_b128 v[176:179], v200 offset:49152
	ds_read_b128 v[180:183], v200 offset:50176
	ds_read_b128 v[202:205], v200 offset:51200
	ds_read_b128 v[206:209], v200 offset:52224
	ds_read_b128 v[210:213], v200 offset:53248
	ds_read_b128 v[232:235], v200 offset:54272
	ds_read_b128 v[236:239], v200 offset:55296
	ds_read_b128 v[240:243], v200 offset:56320
	global_load_lds_dwordx4 v156, s[60:61]
	s_add_i32 m0, s30, 0x2000
	s_add_u32 s28, s28, 0x40080
	s_addc_u32 s29, s29, 0
	s_add_i32 s30, s53, s38
	global_load_lds_dwordx4 v160, s[60:61]
	s_mov_b32 m0, s30
	s_nop 0
	global_load_lds_dwordx4 v156, s[28:29]
	s_add_i32 m0, s30, 0x2000
	s_nop 0
	global_load_lds_dwordx4 v160, s[28:29]
	s_mov_b32 m0, s44
	s_nop 0
	global_load_lds_dwordx4 v154, s[62:63]
	s_mov_b32 m0, s45
	s_nop 0
	global_load_lds_dwordx4 v158, s[62:63]
	s_waitcnt vmcnt(8)
	s_waitcnt lgkmcnt(0)
	s_barrier
	s_setprio 1
	s_waitcnt lgkmcnt(0)
	v_mfma_f32_16x16x32_bf16 v[62:65], v[130:133], v[176:179], v[62:65]
	v_mfma_f32_16x16x32_bf16 v[58:61], v[138:141], v[176:179], v[58:61]
	v_mfma_f32_16x16x32_bf16 v[46:49], v[130:133], v[202:205], v[46:49]
	v_mfma_f32_16x16x32_bf16 v[42:45], v[138:141], v[202:205], v[42:45]
	v_mfma_f32_16x16x32_bf16 v[30:33], v[130:133], v[210:213], v[30:33]
	v_mfma_f32_16x16x32_bf16 v[26:29], v[138:141], v[210:213], v[26:29]
	v_mfma_f32_16x16x32_bf16 v[14:17], v[130:133], v[236:239], v[14:17]
	v_mfma_f32_16x16x32_bf16 v[10:13], v[138:141], v[236:239], v[10:13]
	v_mfma_f32_16x16x32_bf16 v[62:65], v[134:137], v[180:183], v[62:65]
	v_mfma_f32_16x16x32_bf16 v[58:61], v[142:145], v[180:183], v[58:61]
	v_mfma_f32_16x16x32_bf16 v[46:49], v[134:137], v[206:209], v[46:49]
	v_mfma_f32_16x16x32_bf16 v[42:45], v[142:145], v[206:209], v[42:45]
	v_mfma_f32_16x16x32_bf16 v[30:33], v[134:137], v[232:235], v[30:33]
	v_mfma_f32_16x16x32_bf16 v[26:29], v[142:145], v[232:235], v[26:29]
	v_mfma_f32_16x16x32_bf16 v[14:17], v[134:137], v[240:243], v[14:17]
	v_mfma_f32_16x16x32_bf16 v[10:13], v[142:145], v[240:243], v[10:13]
	s_setprio 0
	s_setprio 1
	v_mfma_f32_16x16x32_bf16 v[54:57], v[146:149], v[176:179], v[54:57]
	v_mfma_f32_16x16x32_bf16 v[50:53], v[168:171], v[176:179], v[50:53]
	v_mfma_f32_16x16x32_bf16 v[38:41], v[146:149], v[202:205], v[38:41]
	v_mfma_f32_16x16x32_bf16 v[34:37], v[168:171], v[202:205], v[34:37]
	v_mfma_f32_16x16x32_bf16 v[22:25], v[146:149], v[210:213], v[22:25]
	v_mfma_f32_16x16x32_bf16 v[18:21], v[168:171], v[210:213], v[18:21]
	v_mfma_f32_16x16x32_bf16 v[6:9], v[146:149], v[236:239], v[6:9]
	v_mfma_f32_16x16x32_bf16 v[2:5], v[168:171], v[236:239], v[2:5]
	v_mfma_f32_16x16x32_bf16 v[54:57], v[150:153], v[180:183], v[54:57]
	v_mfma_f32_16x16x32_bf16 v[50:53], v[172:175], v[180:183], v[50:53]
	v_mfma_f32_16x16x32_bf16 v[38:41], v[150:153], v[206:209], v[38:41]
	v_mfma_f32_16x16x32_bf16 v[34:37], v[172:175], v[206:209], v[34:37]
	v_mfma_f32_16x16x32_bf16 v[22:25], v[150:153], v[232:235], v[22:25]
	v_mfma_f32_16x16x32_bf16 v[18:21], v[172:175], v[232:235], v[18:21]
	v_mfma_f32_16x16x32_bf16 v[6:9], v[150:153], v[240:243], v[6:9]
	v_mfma_f32_16x16x32_bf16 v[2:5], v[172:175], v[240:243], v[2:5]
	s_setprio 0
	s_barrier
	s_add_i32 s51, s51, 2
	s_add_u32 s26, s26, 0x100
	s_addc_u32 s27, s27, 0
	s_add_u32 s49, s49, 0x100
	s_addc_u32 s50, s50, 0
	s_cmp_gt_u32 s51, 13
	s_cbranch_scc0 .LBB0_1270
	s_and_b64 vcc, exec, s[12:13]
	s_cbranch_vccz .LBB0_1273
	s_barrier

; #define PG8_STAGE(bufoff, gbase, voff) do { _Pragma("unroll") for (int _i = 0; _i < 2; ++_i) \
;         __builtin_amdgcn_global_load_lds((const unsigned*)((const char*)(gbase) + (voff)[_i]), (PG8_LAS unsigned*)(lds + (bufoff) + ldsw + _i * 8192), 16, 0, 0); } while (0)
; #define PG8_LDA(dst, b, h) do { _Pragma("unroll") for (int m = 0; m < 4; ++m) _Pragma("unroll") for (int k = 0; k < 2; ++k) dst[m][k] = *(const PG8_LAS bf16x8*)(lds + PG8_SA(b, h) + aoff + m * 2048 + k * 1024); } while (0)
; #define PG8_LDB(dst, b, h) do { _Pragma("unroll") for (int n = 0; n < 2; ++n) _Pragma("unroll") for (int k = 0; k < 2; ++k) dst[n][k] = *(const PG8_LAS bf16x8*)(lds + PG8_SB(b, h) + boff + n * 2048 + k * 1024); } while (0)
; #define PG8_MMA(ai, bj, At, Bt) do { __builtin_amdgcn_s_setprio(1); _Pragma("unroll") for (int m = 0; m < 4; ++m) _Pragma("unroll") for (int n = 0; n < 2; ++n) _Pragma("unroll") for (int k = 0; k < 2; ++k) \
;         acc[ai][bj][m][n] = __builtin_amdgcn_mfma_f32_16x16x32_bf16(Bt[n][k], At[m][k], acc[ai][bj][m][n], 0, 0, 0); __builtin_amdgcn_s_setprio(0); } while (0)
; #define PG8_WAIT_V(n) asm volatile("s_waitcnt vmcnt(" #n ")" ::: "memory")
; #define PG8_WAIT_L(n) asm volatile("s_waitcnt lgkmcnt(" #n ")" ::: "memory")
; #define PG8_BAR __builtin_amdgcn_s_barrier()
; #define PG8_SCHED __builtin_amdgcn_sched_barrier(0)
; template <class Epi, class Sched, bool ALIGN_EPI = false, bool SP2 = false>
; __device__ __forceinline__ void gemm_phase(PG8_LAS unsigned char* lds, const Gemm g, const Sched& S, const Epi& E) {
;     ...
;         for (int t = 0; t < nt; t += 2) {
;             const bool last = (t == nt - 2);
;             const char* a1 = cA + (size_t)(t + 1) * kstep;
;             const char* a2 = last ? nA : cA + (size_t)(t + 2) * kstep; const char* b2 = last ? nB : cB + (size_t)(t + 2) * kstep;
;             const char* a3 = a2 + kstep; const char* b3 = b2 + kstep;
;             if (last && has_next) S.a_ready(nxt);
;             if constexpr (SP2) {
;             PG8_LDB(B0, 0, 0); PG8_LDB(B1, 0, 1); PG8_SCHED; PG8_LDA(At, 0, 0); PG8_STAGE(PG8_SA(1, 1), a1 + hstepA, voffA);
;             PG8_WAIT_V(8); PG8_WAIT_L(0); PG8_BAR; PG8_MMA(0, 0, At, B0); PG8_MMA(0, 1, At, B1); PG8_BAR; PG8_SCHED;
;             PG8_LDA(At, 0, 1); PG8_STAGE(PG8_SB(0, 0), b2, voffB); PG8_STAGE(PG8_SB(0, 1), b2 + hstepB, voffB); PG8_STAGE(PG8_SA(0, 0), a2, voffA);
.LBB0_1354:
	s_add_u32 s24, s22, 0xfffc0080
	s_addc_u32 s25, s23, -1
	s_add_i32 s49, 0, 0x10000
	s_cmp_eq_u32 s48, 12
	s_cselect_b32 s27, s15, s25
	s_cselect_b32 s26, s21, s24
	v_add_u32_e32 v142, s49, v145
	s_cselect_b32 s25, s13, s47
	s_cselect_b32 s24, s45, s46
	s_add_i32 s52, 0, 0x14000
	ds_read_b128 v[150:153], v142
	ds_read_b128 v[154:157], v142 offset:1024
	ds_read_b128 v[158:161], v142 offset:2048
	ds_read_b128 v[162:165], v142 offset:3072
	v_add_u32_e32 v142, s52, v145
	ds_read_b128 v[166:169], v142
	ds_read_b128 v[170:173], v142 offset:1024
	ds_read_b128 v[174:177], v142 offset:2048
	ds_read_b128 v[178:181], v142 offset:3072
	s_add_i32 m0, s36, 0xc000
	ds_read_b128 v[182:185], v148
	ds_read_b128 v[202:205], v148 offset:1024
	ds_read_b128 v[206:209], v148 offset:2048
	ds_read_b128 v[210:213], v148 offset:3072
	ds_read_b128 v[232:235], v148 offset:4096
	ds_read_b128 v[236:239], v148 offset:5120
	ds_read_b128 v[240:243], v148 offset:6144
	ds_read_b128 v[244:247], v148 offset:7168
	global_load_lds_dwordx4 v138, s[22:23]
	s_add_i32 m0, s36, 0xe000
	s_nop 0
	global_load_lds_dwordx4 v140, s[22:23]
	s_waitcnt vmcnt(8)
	s_waitcnt lgkmcnt(0)
	s_barrier
	s_setprio 1
	s_waitcnt lgkmcnt(0)
	v_mfma_f32_16x16x32_bf16 v[126:129], v[150:153], v[182:185], v[126:129]
	v_mfma_f32_16x16x32_bf16 v[122:125], v[158:161], v[182:185], v[122:125]
	v_mfma_f32_16x16x32_bf16 v[114:117], v[150:153], v[206:209], v[114:117]
	v_mfma_f32_16x16x32_bf16 v[106:109], v[158:161], v[206:209], v[106:109]
	v_mfma_f32_16x16x32_bf16 v[98:101], v[150:153], v[232:235], v[98:101]
	v_mfma_f32_16x16x32_bf16 v[90:93], v[158:161], v[232:235], v[90:93]
	v_mfma_f32_16x16x32_bf16 v[78:81], v[150:153], v[240:243], v[78:81]
	v_mfma_f32_16x16x32_bf16 v[74:77], v[158:161], v[240:243], v[74:77]
	v_mfma_f32_16x16x32_bf16 v[126:129], v[154:157], v[202:205], v[126:129]
	v_mfma_f32_16x16x32_bf16 v[122:125], v[162:165], v[202:205], v[122:125]
	v_mfma_f32_16x16x32_bf16 v[114:117], v[154:157], v[210:213], v[114:117]
	v_mfma_f32_16x16x32_bf16 v[106:109], v[162:165], v[210:213], v[106:109]
	v_mfma_f32_16x16x32_bf16 v[98:101], v[154:157], v[236:239], v[98:101]
	v_mfma_f32_16x16x32_bf16 v[90:93], v[162:165], v[236:239], v[90:93]
	v_mfma_f32_16x16x32_bf16 v[78:81], v[154:157], v[244:247], v[78:81]
	v_mfma_f32_16x16x32_bf16 v[74:77], v[162:165], v[244:247], v[74:77]
	s_setprio 0
	s_setprio 1
	v_mfma_f32_16x16x32_bf16 v[118:121], v[166:169], v[182:185], v[118:121]
	v_mfma_f32_16x16x32_bf16 v[110:113], v[174:177], v[182:185], v[110:113]
	v_mfma_f32_16x16x32_bf16 v[102:105], v[166:169], v[206:209], v[102:105]
	v_mfma_f32_16x16x32_bf16 v[94:97], v[174:177], v[206:209], v[94:97]
	v_mfma_f32_16x16x32_bf16 v[86:89], v[166:169], v[232:235], v[86:89]
	v_mfma_f32_16x16x32_bf16 v[82:85], v[174:177], v[232:235], v[82:85]
	v_mfma_f32_16x16x32_bf16 v[70:73], v[166:169], v[240:243], v[70:73]
	v_mfma_f32_16x16x32_bf16 v[66:69], v[174:177], v[240:243], v[66:69]
	v_mfma_f32_16x16x32_bf16 v[118:121], v[170:173], v[202:205], v[118:121]
	v_mfma_f32_16x16x32_bf16 v[110:113], v[178:181], v[202:205], v[110:113]
	v_mfma_f32_16x16x32_bf16 v[102:105], v[170:173], v[210:213], v[102:105]
	v_mfma_f32_16x16x32_bf16 v[94:97], v[178:181], v[210:213], v[94:97]
	v_mfma_f32_16x16x32_bf16 v[86:89], v[170:173], v[236:239], v[86:89]
	v_mfma_f32_16x16x32_bf16 v[82:85], v[178:181], v[236:239], v[82:85]
	v_mfma_f32_16x16x32_bf16 v[70:73], v[170:173], v[244:247], v[70:73]
	v_mfma_f32_16x16x32_bf16 v[66:69], v[178:181], v[244:247], v[66:69]
	s_setprio 0
	s_barrier
	s_add_i32 s49, s49, s34
	s_mov_b32 m0, s49
	ds_read_b128 v[182:185], v148 offset:16384
	ds_read_b128 v[202:205], v148 offset:17408
	ds_read_b128 v[206:209], v148 offset:18432
	ds_read_b128 v[210:213], v148 offset:19456
	ds_read_b128 v[232:235], v148 offset:20480
	ds_read_b128 v[236:239], v148 offset:21504
	ds_read_b128 v[240:243], v148 offset:22528
	ds_read_b128 v[244:247], v148 offset:23552
	s_add_u32 s60, s24, 0x80
	s_addc_u32 s61, s25, 0
	s_add_u32 s62, s26, 0x80
	s_addc_u32 s63, s27, 0
	global_load_lds_dwordx4 v134, s[24:25]
	s_add_i32 m0, s49, 0x2000
	s_add_u32 s50, s24, 0x40000
	s_addc_u32 s51, s25, 0
	s_add_i32 s49, s52, s34
	global_load_lds_dwordx4 v130, s[24:25]
	s_mov_b32 m0, s49
	s_nop 0
	global_load_lds_dwordx4 v134, s[50:51]
	s_add_i32 m0, s49, 0x2000
	s_nop 0
	global_load_lds_dwordx4 v130, s[50:51]
	s_mov_b32 m0, s36
	s_nop 0
	global_load_lds_dwordx4 v136, s[26:27]
	s_mov_b32 m0, s37
	s_nop 0
	global_load_lds_dwordx4 v132, s[26:27]
	s_waitcnt vmcnt(8)
	s_waitcnt lgkmcnt(0)
	s_barrier
; #define PG8_STAGE(bufoff, gbase, voff) do { _Pragma("unroll") for (int _i = 0; _i < 2; ++_i) \
;         __builtin_amdgcn_global_load_lds((const unsigned*)((const char*)(gbase) + (voff)[_i]), (PG8_LAS unsigned*)(lds + (bufoff) + ldsw + _i * 8192), 16, 0, 0); } while (0)
; #define PG8_LDA(dst, b, h) do { _Pragma("unroll") for (int m = 0; m < 4; ++m) _Pragma("unroll") for (int k = 0; k < 2; ++k) dst[m][k] = *(const PG8_LAS bf16x8*)(lds + PG8_SA(b, h) + aoff + m * 2048 + k * 1024); } while (0)
; #define PG8_LDB(dst, b, h) do { _Pragma("unroll") for (int n = 0; n < 2; ++n) _Pragma("unroll") for (int k = 0; k < 2; ++k) dst[n][k] = *(const PG8_LAS bf16x8*)(lds + PG8_SB(b, h) + boff + n * 2048 + k * 1024); } while (0)
; #define PG8_MMA(ai, bj, At, Bt) do { __builtin_amdgcn_s_setprio(1); _Pragma("unroll") for (int m = 0; m < 4; ++m) _Pragma("unroll") for (int n = 0; n < 2; ++n) _Pragma("unroll") for (int k = 0; k < 2; ++k) \
;         acc[ai][bj][m][n] = __builtin_amdgcn_mfma_f32_16x16x32_bf16(Bt[n][k], At[m][k], acc[ai][bj][m][n], 0, 0, 0); __builtin_amdgcn_s_setprio(0); } while (0)
; #define PG8_WAIT_V(n) asm volatile("s_waitcnt vmcnt(" #n ")" ::: "memory")
; #define PG8_WAIT_L(n) asm volatile("s_waitcnt lgkmcnt(" #n ")" ::: "memory")
; #define PG8_BAR __builtin_amdgcn_s_barrier()
; #define PG8_SCHED __builtin_amdgcn_sched_barrier(0)
; template <class Epi, class Sched, bool ALIGN_EPI = false, bool SP2 = false>
; __device__ __forceinline__ void gemm_phase(PG8_LAS unsigned char* lds, const Gemm g, const Sched& S, const Epi& E) {
;     ...
;             PG8_WAIT_V(8); PG8_WAIT_L(0); PG8_BAR; PG8_MMA(1, 0, At, B0); PG8_MMA(1, 1, At, B1); PG8_BAR; PG8_SCHED;
;             PG8_LDB(B0, 1, 0); PG8_LDB(B1, 1, 1); PG8_SCHED; PG8_LDA(At, 1, 0); PG8_STAGE(PG8_SA(0, 1), a2 + hstepA, voffA);
;             PG8_WAIT_V(8); PG8_WAIT_L(0); PG8_BAR; PG8_MMA(0, 0, At, B0); PG8_MMA(0, 1, At, B1); PG8_BAR; PG8_SCHED;
	s_setprio 1
	s_waitcnt lgkmcnt(0)
	v_mfma_f32_16x16x32_bf16 v[62:65], v[150:153], v[182:185], v[62:65]
	v_mfma_f32_16x16x32_bf16 v[58:61], v[158:161], v[182:185], v[58:61]
	v_mfma_f32_16x16x32_bf16 v[46:49], v[150:153], v[206:209], v[46:49]
	v_mfma_f32_16x16x32_bf16 v[42:45], v[158:161], v[206:209], v[42:45]
	v_mfma_f32_16x16x32_bf16 v[30:33], v[150:153], v[232:235], v[30:33]
	v_mfma_f32_16x16x32_bf16 v[26:29], v[158:161], v[232:235], v[26:29]
	v_mfma_f32_16x16x32_bf16 v[14:17], v[150:153], v[240:243], v[14:17]
	v_mfma_f32_16x16x32_bf16 v[10:13], v[158:161], v[240:243], v[10:13]
	v_mfma_f32_16x16x32_bf16 v[62:65], v[154:157], v[202:205], v[62:65]
	v_mfma_f32_16x16x32_bf16 v[58:61], v[162:165], v[202:205], v[58:61]
	v_mfma_f32_16x16x32_bf16 v[46:49], v[154:157], v[210:213], v[46:49]
	v_mfma_f32_16x16x32_bf16 v[42:45], v[162:165], v[210:213], v[42:45]
	v_mfma_f32_16x16x32_bf16 v[30:33], v[154:157], v[236:239], v[30:33]
	v_mfma_f32_16x16x32_bf16 v[26:29], v[162:165], v[236:239], v[26:29]
	v_mfma_f32_16x16x32_bf16 v[14:17], v[154:157], v[244:247], v[14:17]
	v_mfma_f32_16x16x32_bf16 v[10:13], v[162:165], v[244:247], v[10:13]
	s_setprio 0
	s_setprio 1
	v_mfma_f32_16x16x32_bf16 v[54:57], v[166:169], v[182:185], v[54:57]
	v_mfma_f32_16x16x32_bf16 v[50:53], v[174:177], v[182:185], v[50:53]
	v_mfma_f32_16x16x32_bf16 v[38:41], v[166:169], v[206:209], v[38:41]
	v_mfma_f32_16x16x32_bf16 v[34:37], v[174:177], v[206:209], v[34:37]
	v_mfma_f32_16x16x32_bf16 v[22:25], v[166:169], v[232:235], v[22:25]
	v_mfma_f32_16x16x32_bf16 v[18:21], v[174:177], v[232:235], v[18:21]
	v_mfma_f32_16x16x32_bf16 v[6:9], v[166:169], v[240:243], v[6:9]
	v_mfma_f32_16x16x32_bf16 v[2:5], v[174:177], v[240:243], v[2:5]
	v_mfma_f32_16x16x32_bf16 v[54:57], v[170:173], v[202:205], v[54:57]
	v_mfma_f32_16x16x32_bf16 v[50:53], v[178:181], v[202:205], v[50:53]
	v_mfma_f32_16x16x32_bf16 v[38:41], v[170:173], v[210:213], v[38:41]
	v_mfma_f32_16x16x32_bf16 v[34:37], v[178:181], v[210:213], v[34:37]
	v_mfma_f32_16x16x32_bf16 v[22:25], v[170:173], v[236:239], v[22:25]
	v_mfma_f32_16x16x32_bf16 v[18:21], v[178:181], v[236:239], v[18:21]
	v_mfma_f32_16x16x32_bf16 v[6:9], v[170:173], v[244:247], v[6:9]
	v_mfma_f32_16x16x32_bf16 v[2:5], v[178:181], v[244:247], v[2:5]
	s_setprio 0
	s_barrier
	s_add_i32 s49, 0, 0x18000
	v_add_u32_e32 v144, s49, v145
	s_add_i32 s50, 0, 0x1c000
	ds_read_b128 v[150:153], v144
	ds_read_b128 v[154:157], v144 offset:1024
	ds_read_b128 v[158:161], v144 offset:2048
	ds_read_b128 v[162:165], v144 offset:3072
	v_add_u32_e32 v144, s50, v145
	ds_read_b128 v[166:169], v144
	ds_read_b128 v[170:173], v144 offset:1024
	ds_read_b128 v[174:177], v144 offset:2048
	ds_read_b128 v[178:181], v144 offset:3072
	s_add_u32 s26, s26, 0x40000
	s_addc_u32 s27, s27, 0
	s_mov_b32 m0, s38
	ds_read_b128 v[182:185], v148 offset:32768
	ds_read_b128 v[202:205], v148 offset:33792
	ds_read_b128 v[206:209], v148 offset:34816
	ds_read_b128 v[210:213], v148 offset:35840
	ds_read_b128 v[232:235], v148 offset:36864
	ds_read_b128 v[236:239], v148 offset:37888
	ds_read_b128 v[240:243], v148 offset:38912
	ds_read_b128 v[244:247], v148 offset:39936
	global_load_lds_dwordx4 v136, s[26:27]
	s_mov_b32 m0, s39
	s_nop 0
	global_load_lds_dwordx4 v132, s[26:27]
	s_waitcnt vmcnt(8)
	s_waitcnt lgkmcnt(0)
	s_barrier
	s_setprio 1
	s_waitcnt lgkmcnt(0)
	v_mfma_f32_16x16x32_bf16 v[126:129], v[150:153], v[182:185], v[126:129]
	v_mfma_f32_16x16x32_bf16 v[122:125], v[158:161], v[182:185], v[122:125]
	v_mfma_f32_16x16x32_bf16 v[114:117], v[150:153], v[206:209], v[114:117]
	v_mfma_f32_16x16x32_bf16 v[106:109], v[158:161], v[206:209], v[106:109]
	v_mfma_f32_16x16x32_bf16 v[98:101], v[150:153], v[232:235], v[98:101]
	v_mfma_f32_16x16x32_bf16 v[90:93], v[158:161], v[232:235], v[90:93]
	v_mfma_f32_16x16x32_bf16 v[78:81], v[150:153], v[240:243], v[78:81]
	v_mfma_f32_16x16x32_bf16 v[74:77], v[158:161], v[240:243], v[74:77]
	v_mfma_f32_16x16x32_bf16 v[126:129], v[154:157], v[202:205], v[126:129]
	v_mfma_f32_16x16x32_bf16 v[122:125], v[162:165], v[202:205], v[122:125]
	v_mfma_f32_16x16x32_bf16 v[114:117], v[154:157], v[210:213], v[114:117]
	v_mfma_f32_16x16x32_bf16 v[106:109], v[162:165], v[210:213], v[106:109]
	v_mfma_f32_16x16x32_bf16 v[98:101], v[154:157], v[236:239], v[98:101]
	v_mfma_f32_16x16x32_bf16 v[90:93], v[162:165], v[236:239], v[90:93]
	v_mfma_f32_16x16x32_bf16 v[78:81], v[154:157], v[244:247], v[78:81]
	v_mfma_f32_16x16x32_bf16 v[74:77], v[162:165], v[244:247], v[74:77]
	s_setprio 0
	s_setprio 1
	v_mfma_f32_16x16x32_bf16 v[118:121], v[166:169], v[182:185], v[118:121]
	v_mfma_f32_16x16x32_bf16 v[110:113], v[174:177], v[182:185], v[110:113]
	v_mfma_f32_16x16x32_bf16 v[102:105], v[166:169], v[206:209], v[102:105]
	v_mfma_f32_16x16x32_bf16 v[94:97], v[174:177], v[206:209], v[94:97]
	v_mfma_f32_16x16x32_bf16 v[86:89], v[166:169], v[232:235], v[86:89]
	v_mfma_f32_16x16x32_bf16 v[82:85], v[174:177], v[232:235], v[82:85]
	v_mfma_f32_16x16x32_bf16 v[70:73], v[166:169], v[240:243], v[70:73]
	v_mfma_f32_16x16x32_bf16 v[66:69], v[174:177], v[240:243], v[66:69]
	v_mfma_f32_16x16x32_bf16 v[118:121], v[170:173], v[202:205], v[118:121]
	v_mfma_f32_16x16x32_bf16 v[110:113], v[178:181], v[202:205], v[110:113]
	v_mfma_f32_16x16x32_bf16 v[102:105], v[170:173], v[210:213], v[102:105]
	v_mfma_f32_16x16x32_bf16 v[94:97], v[178:181], v[210:213], v[94:97]
	v_mfma_f32_16x16x32_bf16 v[86:89], v[170:173], v[236:239], v[86:89]
	v_mfma_f32_16x16x32_bf16 v[82:85], v[178:181], v[236:239], v[82:85]
	v_mfma_f32_16x16x32_bf16 v[70:73], v[170:173], v[244:247], v[70:73]
	v_mfma_f32_16x16x32_bf16 v[66:69], v[178:181], v[244:247], v[66:69]
	s_setprio 0
	s_barrier
; #define PG8_STAGE(bufoff, gbase, voff) do { _Pragma("unroll") for (int _i = 0; _i < 2; ++_i) \
;         __builtin_amdgcn_global_load_lds((const unsigned*)((const char*)(gbase) + (voff)[_i]), (PG8_LAS unsigned*)(lds + (bufoff) + ldsw + _i * 8192), 16, 0, 0); } while (0)
; #define PG8_LDA(dst, b, h) do { _Pragma("unroll") for (int m = 0; m < 4; ++m) _Pragma("unroll") for (int k = 0; k < 2; ++k) dst[m][k] = *(const PG8_LAS bf16x8*)(lds + PG8_SA(b, h) + aoff + m * 2048 + k * 1024); } while (0)
; #define PG8_MMA(ai, bj, At, Bt) do { __builtin_amdgcn_s_setprio(1); _Pragma("unroll") for (int m = 0; m < 4; ++m) _Pragma("unroll") for (int n = 0; n < 2; ++n) _Pragma("unroll") for (int k = 0; k < 2; ++k) \
;         acc[ai][bj][m][n] = __builtin_amdgcn_mfma_f32_16x16x32_bf16(Bt[n][k], At[m][k], acc[ai][bj][m][n], 0, 0, 0); __builtin_amdgcn_s_setprio(0); } while (0)
; #define PG8_WAIT_V(n) asm volatile("s_waitcnt vmcnt(" #n ")" ::: "memory")
; #define PG8_WAIT_L(n) asm volatile("s_waitcnt lgkmcnt(" #n ")" ::: "memory")
; #define PG8_BAR __builtin_amdgcn_s_barrier()
; #define PG8_SCHED __builtin_amdgcn_sched_barrier(0)
; template <class Epi, class Sched, bool ALIGN_EPI = false, bool SP2 = false>
; __device__ __forceinline__ void gemm_phase(PG8_LAS unsigned char* lds, const Gemm g, const Sched& S, const Epi& E) {
;     ...
;             PG8_LDA(At, 1, 1); PG8_STAGE(PG8_SB(1, 0), b3, voffB); PG8_STAGE(PG8_SB(1, 1), b3 + hstepB, voffB); PG8_STAGE(PG8_SA(1, 0), a3, voffA);
;             PG8_WAIT_V(8); PG8_WAIT_L(0); PG8_BAR; PG8_MMA(1, 0, At, B0); PG8_MMA(1, 1, At, B1); PG8_BAR; PG8_SCHED;
	s_add_i32 s26, s49, s34
	s_mov_b32 m0, s26
	ds_read_b128 v[182:185], v148 offset:49152
	ds_read_b128 v[202:205], v148 offset:50176
	ds_read_b128 v[206:209], v148 offset:51200
	ds_read_b128 v[210:213], v148 offset:52224
	ds_read_b128 v[232:235], v148 offset:53248
	ds_read_b128 v[236:239], v148 offset:54272
	ds_read_b128 v[240:243], v148 offset:55296
	ds_read_b128 v[244:247], v148 offset:56320
	global_load_lds_dwordx4 v134, s[60:61]
	s_add_i32 m0, s26, 0x2000
	s_add_u32 s24, s24, 0x40080
	s_addc_u32 s25, s25, 0
	s_add_i32 s26, s50, s34
	global_load_lds_dwordx4 v130, s[60:61]
	s_mov_b32 m0, s26
	s_nop 0
	global_load_lds_dwordx4 v134, s[24:25]
	s_add_i32 m0, s26, 0x2000
	s_nop 0
	global_load_lds_dwordx4 v130, s[24:25]
	s_mov_b32 m0, s40
	s_nop 0
	global_load_lds_dwordx4 v136, s[62:63]
	s_mov_b32 m0, s41
	s_nop 0
	global_load_lds_dwordx4 v132, s[62:63]
	s_waitcnt vmcnt(8)
	s_waitcnt lgkmcnt(0)
	s_barrier
	s_setprio 1
	s_waitcnt lgkmcnt(0)
	v_mfma_f32_16x16x32_bf16 v[62:65], v[150:153], v[182:185], v[62:65]
	v_mfma_f32_16x16x32_bf16 v[58:61], v[158:161], v[182:185], v[58:61]
	v_mfma_f32_16x16x32_bf16 v[46:49], v[150:153], v[206:209], v[46:49]
	v_mfma_f32_16x16x32_bf16 v[42:45], v[158:161], v[206:209], v[42:45]
	v_mfma_f32_16x16x32_bf16 v[30:33], v[150:153], v[232:235], v[30:33]
	v_mfma_f32_16x16x32_bf16 v[26:29], v[158:161], v[232:235], v[26:29]
	v_mfma_f32_16x16x32_bf16 v[14:17], v[150:153], v[240:243], v[14:17]
	v_mfma_f32_16x16x32_bf16 v[10:13], v[158:161], v[240:243], v[10:13]
	v_mfma_f32_16x16x32_bf16 v[62:65], v[154:157], v[202:205], v[62:65]
	v_mfma_f32_16x16x32_bf16 v[58:61], v[162:165], v[202:205], v[58:61]
	v_mfma_f32_16x16x32_bf16 v[46:49], v[154:157], v[210:213], v[46:49]
	v_mfma_f32_16x16x32_bf16 v[42:45], v[162:165], v[210:213], v[42:45]
	v_mfma_f32_16x16x32_bf16 v[30:33], v[154:157], v[236:239], v[30:33]
	v_mfma_f32_16x16x32_bf16 v[26:29], v[162:165], v[236:239], v[26:29]
	v_mfma_f32_16x16x32_bf16 v[14:17], v[154:157], v[244:247], v[14:17]
	v_mfma_f32_16x16x32_bf16 v[10:13], v[162:165], v[244:247], v[10:13]
	s_setprio 0
	s_setprio 1
	v_mfma_f32_16x16x32_bf16 v[54:57], v[166:169], v[182:185], v[54:57]
	v_mfma_f32_16x16x32_bf16 v[50:53], v[174:177], v[182:185], v[50:53]
	v_mfma_f32_16x16x32_bf16 v[38:41], v[166:169], v[206:209], v[38:41]
	v_mfma_f32_16x16x32_bf16 v[34:37], v[174:177], v[206:209], v[34:37]
	v_mfma_f32_16x16x32_bf16 v[22:25], v[166:169], v[232:235], v[22:25]
	v_mfma_f32_16x16x32_bf16 v[18:21], v[174:177], v[232:235], v[18:21]
	v_mfma_f32_16x16x32_bf16 v[6:9], v[166:169], v[240:243], v[6:9]
	v_mfma_f32_16x16x32_bf16 v[2:5], v[174:177], v[240:243], v[2:5]
	v_mfma_f32_16x16x32_bf16 v[54:57], v[170:173], v[202:205], v[54:57]
	v_mfma_f32_16x16x32_bf16 v[50:53], v[178:181], v[202:205], v[50:53]
	v_mfma_f32_16x16x32_bf16 v[38:41], v[170:173], v[210:213], v[38:41]
	v_mfma_f32_16x16x32_bf16 v[34:37], v[178:181], v[210:213], v[34:37]
	v_mfma_f32_16x16x32_bf16 v[22:25], v[170:173], v[236:239], v[22:25]
	v_mfma_f32_16x16x32_bf16 v[18:21], v[178:181], v[236:239], v[18:21]
	v_mfma_f32_16x16x32_bf16 v[6:9], v[170:173], v[244:247], v[6:9]
	v_mfma_f32_16x16x32_bf16 v[2:5], v[178:181], v[244:247], v[2:5]
	s_setprio 0
	s_barrier
	s_add_i32 s48, s48, 2
	s_add_u32 s22, s22, 0x100
	s_addc_u32 s23, s23, 0
	s_add_u32 s46, s46, 0x100
	s_addc_u32 s47, s47, 0
	s_cmp_gt_u32 s48, 13
	s_cbranch_scc0 .LBB0_1354
	s_and_b64 vcc, exec, s[10:11]
	s_cbranch_vccz .LBB0_1357
	s_barrier

; #define PG8_STAGE(bufoff, gbase, voff) do { _Pragma("unroll") for (int _i = 0; _i < 2; ++_i) \
;         __builtin_amdgcn_global_load_lds((const unsigned*)((const char*)(gbase) + (voff)[_i]), (PG8_LAS unsigned*)(lds + (bufoff) + ldsw + _i * 8192), 16, 0, 0); } while (0)
; #define PG8_LDA(dst, b, h) do { _Pragma("unroll") for (int m = 0; m < 4; ++m) _Pragma("unroll") for (int k = 0; k < 2; ++k) dst[m][k] = *(const PG8_LAS bf16x8*)(lds + PG8_SA(b, h) + aoff + m * 2048 + k * 1024); } while (0)
; #define PG8_LDB(dst, b, h) do { _Pragma("unroll") for (int n = 0; n < 2; ++n) _Pragma("unroll") for (int k = 0; k < 2; ++k) dst[n][k] = *(const PG8_LAS bf16x8*)(lds + PG8_SB(b, h) + boff + n * 2048 + k * 1024); } while (0)
; #define PG8_MMA(ai, bj, At, Bt) do { __builtin_amdgcn_s_setprio(1); _Pragma("unroll") for (int m = 0; m < 4; ++m) _Pragma("unroll") for (int n = 0; n < 2; ++n) _Pragma("unroll") for (int k = 0; k < 2; ++k) \
;         acc[ai][bj][m][n] = __builtin_amdgcn_mfma_f32_16x16x32_bf16(Bt[n][k], At[m][k], acc[ai][bj][m][n], 0, 0, 0); __builtin_amdgcn_s_setprio(0); } while (0)
; #define PG8_WAIT_V(n) asm volatile("s_waitcnt vmcnt(" #n ")" ::: "memory")
; #define PG8_WAIT_L(n) asm volatile("s_waitcnt lgkmcnt(" #n ")" ::: "memory")
; #define PG8_BAR __builtin_amdgcn_s_barrier()
; #define PG8_SCHED __builtin_amdgcn_sched_barrier(0)
; template <class Epi, class Sched, bool ALIGN_EPI = false, bool SP2 = false>
; __device__ __forceinline__ void gemm_phase(PG8_LAS unsigned char* lds, const Gemm g, const Sched& S, const Epi& E) {
;     ...
;         for (int t = 0; t < nt; t += 2) {
;             const bool last = (t == nt - 2);
;             const char* a1 = cA + (size_t)(t + 1) * kstep;
;             const char* a2 = last ? nA : cA + (size_t)(t + 2) * kstep; const char* b2 = last ? nB : cB + (size_t)(t + 2) * kstep;
;             const char* a3 = a2 + kstep; const char* b3 = b2 + kstep;
;             if (last && has_next) S.a_ready(nxt);
;             if constexpr (SP2) {
;             PG8_LDB(B0, 0, 0); PG8_LDB(B1, 0, 1); PG8_SCHED; PG8_LDA(At, 0, 0); PG8_STAGE(PG8_SA(1, 1), a1 + hstepA, voffA);
;             PG8_WAIT_V(8); PG8_WAIT_L(0); PG8_BAR; PG8_MMA(0, 0, At, B0); PG8_MMA(0, 1, At, B1); PG8_BAR; PG8_SCHED;
;             PG8_LDA(At, 0, 1); PG8_STAGE(PG8_SB(0, 0), b2, voffB); PG8_STAGE(PG8_SB(0, 1), b2 + hstepB, voffB); PG8_STAGE(PG8_SA(0, 0), a2, voffA);
.LBB0_1438:
	s_add_u32 s20, s18, 0x100
	s_addc_u32 s21, s19, 0
	s_add_i32 s50, 0, 0x10000
	s_cmp_eq_u32 s49, 40
	s_cselect_b32 s25, s9, s21
	s_cselect_b32 s24, s8, s20
	s_cselect_b32 s23, s17, s48
	s_cselect_b32 s22, s16, s47
	s_add_i32 s51, 0, 0x14000
	v_add_u32_e32 v142, s50, v186
	v_add_u32_e32 v172, s51, v186
	ds_read_b128 v[130:133], v142
	ds_read_b128 v[134:137], v142 offset:1024
	ds_read_b128 v[138:141], v142 offset:2048
	ds_read_b128 v[142:145], v142 offset:3072
	ds_read_b128 v[146:149], v172
	ds_read_b128 v[150:153], v172 offset:1024
	ds_read_b128 v[168:171], v172 offset:2048
	ds_read_b128 v[172:175], v172 offset:3072
	s_add_i32 m0, s31, 0xc000
	ds_read_b128 v[176:179], v200
	ds_read_b128 v[180:183], v200 offset:1024
	ds_read_b128 v[202:205], v200 offset:2048
	ds_read_b128 v[206:209], v200 offset:3072
	ds_read_b128 v[210:213], v200 offset:4096
	ds_read_b128 v[232:235], v200 offset:5120
	ds_read_b128 v[236:239], v200 offset:6144
	ds_read_b128 v[240:243], v200 offset:7168
	global_load_lds_dwordx4 v164, s[18:19]
	s_add_i32 m0, s31, 0xe000
	s_nop 0
	global_load_lds_dwordx4 v166, s[18:19]
	s_waitcnt vmcnt(8)
	s_waitcnt lgkmcnt(0)
	s_barrier
	s_setprio 1
	s_waitcnt lgkmcnt(0)
	v_mfma_f32_16x16x32_bf16 v[126:129], v[130:133], v[176:179], v[126:129]
	v_mfma_f32_16x16x32_bf16 v[122:125], v[138:141], v[176:179], v[122:125]
	v_mfma_f32_16x16x32_bf16 v[110:113], v[130:133], v[202:205], v[110:113]
	v_mfma_f32_16x16x32_bf16 v[106:109], v[138:141], v[202:205], v[106:109]
	v_mfma_f32_16x16x32_bf16 v[94:97], v[130:133], v[210:213], v[94:97]
	v_mfma_f32_16x16x32_bf16 v[90:93], v[138:141], v[210:213], v[90:93]
	v_mfma_f32_16x16x32_bf16 v[78:81], v[130:133], v[236:239], v[78:81]
	v_mfma_f32_16x16x32_bf16 v[74:77], v[138:141], v[236:239], v[74:77]
	v_mfma_f32_16x16x32_bf16 v[126:129], v[134:137], v[180:183], v[126:129]
	v_mfma_f32_16x16x32_bf16 v[122:125], v[142:145], v[180:183], v[122:125]
	v_mfma_f32_16x16x32_bf16 v[110:113], v[134:137], v[206:209], v[110:113]
	v_mfma_f32_16x16x32_bf16 v[106:109], v[142:145], v[206:209], v[106:109]
	v_mfma_f32_16x16x32_bf16 v[94:97], v[134:137], v[232:235], v[94:97]
	v_mfma_f32_16x16x32_bf16 v[90:93], v[142:145], v[232:235], v[90:93]
	v_mfma_f32_16x16x32_bf16 v[78:81], v[134:137], v[240:243], v[78:81]
	v_mfma_f32_16x16x32_bf16 v[74:77], v[142:145], v[240:243], v[74:77]
	s_setprio 0
	s_setprio 1
	v_mfma_f32_16x16x32_bf16 v[118:121], v[146:149], v[176:179], v[118:121]
	v_mfma_f32_16x16x32_bf16 v[114:117], v[168:171], v[176:179], v[114:117]
	v_mfma_f32_16x16x32_bf16 v[102:105], v[146:149], v[202:205], v[102:105]
	v_mfma_f32_16x16x32_bf16 v[98:101], v[168:171], v[202:205], v[98:101]
	v_mfma_f32_16x16x32_bf16 v[86:89], v[146:149], v[210:213], v[86:89]
	v_mfma_f32_16x16x32_bf16 v[82:85], v[168:171], v[210:213], v[82:85]
	v_mfma_f32_16x16x32_bf16 v[70:73], v[146:149], v[236:239], v[70:73]
	v_mfma_f32_16x16x32_bf16 v[66:69], v[168:171], v[236:239], v[66:69]
	v_mfma_f32_16x16x32_bf16 v[118:121], v[150:153], v[180:183], v[118:121]
	v_mfma_f32_16x16x32_bf16 v[114:117], v[172:175], v[180:183], v[114:117]
	v_mfma_f32_16x16x32_bf16 v[102:105], v[150:153], v[206:209], v[102:105]
	v_mfma_f32_16x16x32_bf16 v[98:101], v[172:175], v[206:209], v[98:101]
	v_mfma_f32_16x16x32_bf16 v[86:89], v[150:153], v[232:235], v[86:89]
	v_mfma_f32_16x16x32_bf16 v[82:85], v[172:175], v[232:235], v[82:85]
	v_mfma_f32_16x16x32_bf16 v[70:73], v[150:153], v[240:243], v[70:73]
	v_mfma_f32_16x16x32_bf16 v[66:69], v[172:175], v[240:243], v[66:69]
	s_setprio 0
	s_barrier
	s_add_i32 s18, s50, s30
	s_mov_b32 m0, s18
	ds_read_b128 v[176:179], v200 offset:16384
	ds_read_b128 v[180:183], v200 offset:17408
	ds_read_b128 v[202:205], v200 offset:18432
	ds_read_b128 v[206:209], v200 offset:19456
	ds_read_b128 v[210:213], v200 offset:20480
	ds_read_b128 v[232:235], v200 offset:21504
	ds_read_b128 v[236:239], v200 offset:22528
	ds_read_b128 v[240:243], v200 offset:23552
	s_add_u32 s60, s22, 0x80
	s_addc_u32 s61, s23, 0
	s_add_u32 s62, s24, 0x80
	s_addc_u32 s63, s25, 0
	global_load_lds_dwordx4 v156, s[22:23]
	s_add_i32 m0, s18, 0x2000
	s_add_u32 s18, s22, 0xb0000
	s_addc_u32 s19, s23, 0
	s_add_i32 s50, s51, s30
	global_load_lds_dwordx4 v160, s[22:23]
	s_mov_b32 m0, s50
	s_nop 0
	global_load_lds_dwordx4 v156, s[18:19]
	s_add_i32 m0, s50, 0x2000
	s_nop 0
	global_load_lds_dwordx4 v160, s[18:19]
	s_mov_b32 m0, s31
	s_nop 0
	global_load_lds_dwordx4 v154, s[24:25]
	s_mov_b32 m0, s34
	s_nop 0
	global_load_lds_dwordx4 v158, s[24:25]
	s_waitcnt vmcnt(8)
	s_waitcnt lgkmcnt(0)
	s_barrier
; #define PG8_STAGE(bufoff, gbase, voff) do { _Pragma("unroll") for (int _i = 0; _i < 2; ++_i) \
;         __builtin_amdgcn_global_load_lds((const unsigned*)((const char*)(gbase) + (voff)[_i]), (PG8_LAS unsigned*)(lds + (bufoff) + ldsw + _i * 8192), 16, 0, 0); } while (0)
; #define PG8_LDA(dst, b, h) do { _Pragma("unroll") for (int m = 0; m < 4; ++m) _Pragma("unroll") for (int k = 0; k < 2; ++k) dst[m][k] = *(const PG8_LAS bf16x8*)(lds + PG8_SA(b, h) + aoff + m * 2048 + k * 1024); } while (0)
; #define PG8_LDB(dst, b, h) do { _Pragma("unroll") for (int n = 0; n < 2; ++n) _Pragma("unroll") for (int k = 0; k < 2; ++k) dst[n][k] = *(const PG8_LAS bf16x8*)(lds + PG8_SB(b, h) + boff + n * 2048 + k * 1024); } while (0)
; #define PG8_MMA(ai, bj, At, Bt) do { __builtin_amdgcn_s_setprio(1); _Pragma("unroll") for (int m = 0; m < 4; ++m) _Pragma("unroll") for (int n = 0; n < 2; ++n) _Pragma("unroll") for (int k = 0; k < 2; ++k) \
;         acc[ai][bj][m][n] = __builtin_amdgcn_mfma_f32_16x16x32_bf16(Bt[n][k], At[m][k], acc[ai][bj][m][n], 0, 0, 0); __builtin_amdgcn_s_setprio(0); } while (0)
; #define PG8_WAIT_V(n) asm volatile("s_waitcnt vmcnt(" #n ")" ::: "memory")
; #define PG8_WAIT_L(n) asm volatile("s_waitcnt lgkmcnt(" #n ")" ::: "memory")
; #define PG8_BAR __builtin_amdgcn_s_barrier()
; #define PG8_SCHED __builtin_amdgcn_sched_barrier(0)
; template <class Epi, class Sched, bool ALIGN_EPI = false, bool SP2 = false>
; __device__ __forceinline__ void gemm_phase(PG8_LAS unsigned char* lds, const Gemm g, const Sched& S, const Epi& E) {
;     ...
;             PG8_WAIT_V(8); PG8_WAIT_L(0); PG8_BAR; PG8_MMA(1, 0, At, B0); PG8_MMA(1, 1, At, B1); PG8_BAR; PG8_SCHED;
;             PG8_LDB(B0, 1, 0); PG8_LDB(B1, 1, 1); PG8_SCHED; PG8_LDA(At, 1, 0); PG8_STAGE(PG8_SA(0, 1), a2 + hstepA, voffA);
;             PG8_WAIT_V(8); PG8_WAIT_L(0); PG8_BAR; PG8_MMA(0, 0, At, B0); PG8_MMA(0, 1, At, B1); PG8_BAR; PG8_SCHED;
	s_setprio 1
	s_waitcnt lgkmcnt(0)
	v_mfma_f32_16x16x32_bf16 v[62:65], v[130:133], v[176:179], v[62:65]
	v_mfma_f32_16x16x32_bf16 v[58:61], v[138:141], v[176:179], v[58:61]
	v_mfma_f32_16x16x32_bf16 v[46:49], v[130:133], v[202:205], v[46:49]
	v_mfma_f32_16x16x32_bf16 v[42:45], v[138:141], v[202:205], v[42:45]
	v_mfma_f32_16x16x32_bf16 v[30:33], v[130:133], v[210:213], v[30:33]
	v_mfma_f32_16x16x32_bf16 v[26:29], v[138:141], v[210:213], v[26:29]
	v_mfma_f32_16x16x32_bf16 v[14:17], v[130:133], v[236:239], v[14:17]
	v_mfma_f32_16x16x32_bf16 v[10:13], v[138:141], v[236:239], v[10:13]
	v_mfma_f32_16x16x32_bf16 v[62:65], v[134:137], v[180:183], v[62:65]
	v_mfma_f32_16x16x32_bf16 v[58:61], v[142:145], v[180:183], v[58:61]
	v_mfma_f32_16x16x32_bf16 v[46:49], v[134:137], v[206:209], v[46:49]
	v_mfma_f32_16x16x32_bf16 v[42:45], v[142:145], v[206:209], v[42:45]
	v_mfma_f32_16x16x32_bf16 v[30:33], v[134:137], v[232:235], v[30:33]
	v_mfma_f32_16x16x32_bf16 v[26:29], v[142:145], v[232:235], v[26:29]
	v_mfma_f32_16x16x32_bf16 v[14:17], v[134:137], v[240:243], v[14:17]
	v_mfma_f32_16x16x32_bf16 v[10:13], v[142:145], v[240:243], v[10:13]
	s_setprio 0
	s_setprio 1
	v_mfma_f32_16x16x32_bf16 v[54:57], v[146:149], v[176:179], v[54:57]
	v_mfma_f32_16x16x32_bf16 v[50:53], v[168:171], v[176:179], v[50:53]
	v_mfma_f32_16x16x32_bf16 v[38:41], v[146:149], v[202:205], v[38:41]
	v_mfma_f32_16x16x32_bf16 v[34:37], v[168:171], v[202:205], v[34:37]
	v_mfma_f32_16x16x32_bf16 v[22:25], v[146:149], v[210:213], v[22:25]
	v_mfma_f32_16x16x32_bf16 v[18:21], v[168:171], v[210:213], v[18:21]
	v_mfma_f32_16x16x32_bf16 v[6:9], v[146:149], v[236:239], v[6:9]
	v_mfma_f32_16x16x32_bf16 v[2:5], v[168:171], v[236:239], v[2:5]
	v_mfma_f32_16x16x32_bf16 v[54:57], v[150:153], v[180:183], v[54:57]
	v_mfma_f32_16x16x32_bf16 v[50:53], v[172:175], v[180:183], v[50:53]
	v_mfma_f32_16x16x32_bf16 v[38:41], v[150:153], v[206:209], v[38:41]
	v_mfma_f32_16x16x32_bf16 v[34:37], v[172:175], v[206:209], v[34:37]
	v_mfma_f32_16x16x32_bf16 v[22:25], v[150:153], v[232:235], v[22:25]
	v_mfma_f32_16x16x32_bf16 v[18:21], v[172:175], v[232:235], v[18:21]
	v_mfma_f32_16x16x32_bf16 v[6:9], v[150:153], v[240:243], v[6:9]
	v_mfma_f32_16x16x32_bf16 v[2:5], v[172:175], v[240:243], v[2:5]
	s_setprio 0
	s_barrier
	s_add_i32 s50, 0, 0x18000
	s_add_i32 s51, 0, 0x1c000
	v_add_u32_e32 v142, s50, v186
	v_add_u32_e32 v172, s51, v186
	ds_read_b128 v[130:133], v142
	ds_read_b128 v[134:137], v142 offset:1024
	ds_read_b128 v[138:141], v142 offset:2048
	ds_read_b128 v[142:145], v142 offset:3072
	ds_read_b128 v[146:149], v172
	ds_read_b128 v[150:153], v172 offset:1024
	ds_read_b128 v[168:171], v172 offset:2048
	ds_read_b128 v[172:175], v172 offset:3072
	s_add_u32 s18, s24, 0xb0000
	s_addc_u32 s19, s25, 0
	s_mov_b32 m0, s35
	ds_read_b128 v[176:179], v200 offset:32768
	ds_read_b128 v[180:183], v200 offset:33792
	ds_read_b128 v[202:205], v200 offset:34816
	ds_read_b128 v[206:209], v200 offset:35840
	ds_read_b128 v[210:213], v200 offset:36864
	ds_read_b128 v[232:235], v200 offset:37888
	ds_read_b128 v[236:239], v200 offset:38912
	ds_read_b128 v[240:243], v200 offset:39936
	global_load_lds_dwordx4 v154, s[18:19]
	s_mov_b32 m0, s36
	s_nop 0
	global_load_lds_dwordx4 v158, s[18:19]
	s_waitcnt vmcnt(8)
	s_waitcnt lgkmcnt(0)
	s_barrier
	s_setprio 1
	s_waitcnt lgkmcnt(0)
	v_mfma_f32_16x16x32_bf16 v[126:129], v[130:133], v[176:179], v[126:129]
	v_mfma_f32_16x16x32_bf16 v[122:125], v[138:141], v[176:179], v[122:125]
	v_mfma_f32_16x16x32_bf16 v[110:113], v[130:133], v[202:205], v[110:113]
	v_mfma_f32_16x16x32_bf16 v[106:109], v[138:141], v[202:205], v[106:109]
	v_mfma_f32_16x16x32_bf16 v[94:97], v[130:133], v[210:213], v[94:97]
	v_mfma_f32_16x16x32_bf16 v[90:93], v[138:141], v[210:213], v[90:93]
	v_mfma_f32_16x16x32_bf16 v[78:81], v[130:133], v[236:239], v[78:81]
	v_mfma_f32_16x16x32_bf16 v[74:77], v[138:141], v[236:239], v[74:77]
	v_mfma_f32_16x16x32_bf16 v[126:129], v[134:137], v[180:183], v[126:129]
	v_mfma_f32_16x16x32_bf16 v[122:125], v[142:145], v[180:183], v[122:125]
	v_mfma_f32_16x16x32_bf16 v[110:113], v[134:137], v[206:209], v[110:113]
	v_mfma_f32_16x16x32_bf16 v[106:109], v[142:145], v[206:209], v[106:109]
	v_mfma_f32_16x16x32_bf16 v[94:97], v[134:137], v[232:235], v[94:97]
	v_mfma_f32_16x16x32_bf16 v[90:93], v[142:145], v[232:235], v[90:93]
	v_mfma_f32_16x16x32_bf16 v[78:81], v[134:137], v[240:243], v[78:81]
	v_mfma_f32_16x16x32_bf16 v[74:77], v[142:145], v[240:243], v[74:77]
	s_setprio 0
	s_setprio 1
	v_mfma_f32_16x16x32_bf16 v[118:121], v[146:149], v[176:179], v[118:121]
	v_mfma_f32_16x16x32_bf16 v[114:117], v[168:171], v[176:179], v[114:117]
	v_mfma_f32_16x16x32_bf16 v[102:105], v[146:149], v[202:205], v[102:105]
	v_mfma_f32_16x16x32_bf16 v[98:101], v[168:171], v[202:205], v[98:101]
	v_mfma_f32_16x16x32_bf16 v[86:89], v[146:149], v[210:213], v[86:89]
	v_mfma_f32_16x16x32_bf16 v[82:85], v[168:171], v[210:213], v[82:85]
	v_mfma_f32_16x16x32_bf16 v[70:73], v[146:149], v[236:239], v[70:73]
	v_mfma_f32_16x16x32_bf16 v[66:69], v[168:171], v[236:239], v[66:69]
	v_mfma_f32_16x16x32_bf16 v[118:121], v[150:153], v[180:183], v[118:121]
	v_mfma_f32_16x16x32_bf16 v[114:117], v[172:175], v[180:183], v[114:117]
	v_mfma_f32_16x16x32_bf16 v[102:105], v[150:153], v[206:209], v[102:105]
	v_mfma_f32_16x16x32_bf16 v[98:101], v[172:175], v[206:209], v[98:101]
	v_mfma_f32_16x16x32_bf16 v[86:89], v[150:153], v[232:235], v[86:89]
	v_mfma_f32_16x16x32_bf16 v[82:85], v[172:175], v[232:235], v[82:85]
	v_mfma_f32_16x16x32_bf16 v[70:73], v[150:153], v[240:243], v[70:73]
	v_mfma_f32_16x16x32_bf16 v[66:69], v[172:175], v[240:243], v[66:69]
	s_setprio 0
	s_barrier
; #define PG8_STAGE(bufoff, gbase, voff) do { _Pragma("unroll") for (int _i = 0; _i < 2; ++_i) \
;         __builtin_amdgcn_global_load_lds((const unsigned*)((const char*)(gbase) + (voff)[_i]), (PG8_LAS unsigned*)(lds + (bufoff) + ldsw + _i * 8192), 16, 0, 0); } while (0)
; #define PG8_LDA(dst, b, h) do { _Pragma("unroll") for (int m = 0; m < 4; ++m) _Pragma("unroll") for (int k = 0; k < 2; ++k) dst[m][k] = *(const PG8_LAS bf16x8*)(lds + PG8_SA(b, h) + aoff + m * 2048 + k * 1024); } while (0)
; #define PG8_MMA(ai, bj, At, Bt) do { __builtin_amdgcn_s_setprio(1); _Pragma("unroll") for (int m = 0; m < 4; ++m) _Pragma("unroll") for (int n = 0; n < 2; ++n) _Pragma("unroll") for (int k = 0; k < 2; ++k) \
;         acc[ai][bj][m][n] = __builtin_amdgcn_mfma_f32_16x16x32_bf16(Bt[n][k], At[m][k], acc[ai][bj][m][n], 0, 0, 0); __builtin_amdgcn_s_setprio(0); } while (0)
; #define PG8_WAIT_V(n) asm volatile("s_waitcnt vmcnt(" #n ")" ::: "memory")
; #define PG8_WAIT_L(n) asm volatile("s_waitcnt lgkmcnt(" #n ")" ::: "memory")
; #define PG8_BAR __builtin_amdgcn_s_barrier()
; #define PG8_SCHED __builtin_amdgcn_sched_barrier(0)
; template <class Epi, class Sched, bool ALIGN_EPI = false, bool SP2 = false>
; __device__ __forceinline__ void gemm_phase(PG8_LAS unsigned char* lds, const Gemm g, const Sched& S, const Epi& E) {
;     ...
;             PG8_LDA(At, 1, 1); PG8_STAGE(PG8_SB(1, 0), b3, voffB); PG8_STAGE(PG8_SB(1, 1), b3 + hstepB, voffB); PG8_STAGE(PG8_SA(1, 0), a3, voffA);
;             PG8_WAIT_V(8); PG8_WAIT_L(0); PG8_BAR; PG8_MMA(1, 0, At, B0); PG8_MMA(1, 1, At, B1); PG8_BAR; PG8_SCHED;
	s_add_i32 s18, s50, s30
	s_mov_b32 m0, s18
	ds_read_b128 v[176:179], v200 offset:49152
	ds_read_b128 v[180:183], v200 offset:50176
	ds_read_b128 v[202:205], v200 offset:51200
	ds_read_b128 v[206:209], v200 offset:52224
	ds_read_b128 v[210:213], v200 offset:53248
	ds_read_b128 v[232:235], v200 offset:54272
	ds_read_b128 v[236:239], v200 offset:55296
	ds_read_b128 v[240:243], v200 offset:56320
	global_load_lds_dwordx4 v156, s[60:61]
	s_add_i32 m0, s18, 0x2000
	s_add_u32 s18, s22, 0xb0080
	s_addc_u32 s19, s23, 0
	s_add_i32 s22, s51, s30
	global_load_lds_dwordx4 v160, s[60:61]
	s_mov_b32 m0, s22
	s_nop 0
	global_load_lds_dwordx4 v156, s[18:19]
	s_add_i32 m0, s22, 0x2000
	s_nop 0
	global_load_lds_dwordx4 v160, s[18:19]
	s_mov_b32 m0, s38
	s_nop 0
	global_load_lds_dwordx4 v154, s[62:63]
	s_mov_b32 m0, s39
	s_nop 0
	global_load_lds_dwordx4 v158, s[62:63]
	s_waitcnt vmcnt(8)
	s_waitcnt lgkmcnt(0)
	s_barrier
	s_setprio 1
	s_waitcnt lgkmcnt(0)
	v_mfma_f32_16x16x32_bf16 v[62:65], v[130:133], v[176:179], v[62:65]
	v_mfma_f32_16x16x32_bf16 v[58:61], v[138:141], v[176:179], v[58:61]
	v_mfma_f32_16x16x32_bf16 v[46:49], v[130:133], v[202:205], v[46:49]
	v_mfma_f32_16x16x32_bf16 v[42:45], v[138:141], v[202:205], v[42:45]
	v_mfma_f32_16x16x32_bf16 v[30:33], v[130:133], v[210:213], v[30:33]
	v_mfma_f32_16x16x32_bf16 v[26:29], v[138:141], v[210:213], v[26:29]
	v_mfma_f32_16x16x32_bf16 v[14:17], v[130:133], v[236:239], v[14:17]
	v_mfma_f32_16x16x32_bf16 v[10:13], v[138:141], v[236:239], v[10:13]
	v_mfma_f32_16x16x32_bf16 v[62:65], v[134:137], v[180:183], v[62:65]
	v_mfma_f32_16x16x32_bf16 v[58:61], v[142:145], v[180:183], v[58:61]
	v_mfma_f32_16x16x32_bf16 v[46:49], v[134:137], v[206:209], v[46:49]
	v_mfma_f32_16x16x32_bf16 v[42:45], v[142:145], v[206:209], v[42:45]
	v_mfma_f32_16x16x32_bf16 v[30:33], v[134:137], v[232:235], v[30:33]
	v_mfma_f32_16x16x32_bf16 v[26:29], v[142:145], v[232:235], v[26:29]
	v_mfma_f32_16x16x32_bf16 v[14:17], v[134:137], v[240:243], v[14:17]
	v_mfma_f32_16x16x32_bf16 v[10:13], v[142:145], v[240:243], v[10:13]
	s_setprio 0
	s_setprio 1
	v_mfma_f32_16x16x32_bf16 v[54:57], v[146:149], v[176:179], v[54:57]
	v_mfma_f32_16x16x32_bf16 v[50:53], v[168:171], v[176:179], v[50:53]
	v_mfma_f32_16x16x32_bf16 v[38:41], v[146:149], v[202:205], v[38:41]
	v_mfma_f32_16x16x32_bf16 v[34:37], v[168:171], v[202:205], v[34:37]
	v_mfma_f32_16x16x32_bf16 v[22:25], v[146:149], v[210:213], v[22:25]
	v_mfma_f32_16x16x32_bf16 v[18:21], v[168:171], v[210:213], v[18:21]
	v_mfma_f32_16x16x32_bf16 v[6:9], v[146:149], v[236:239], v[6:9]
	v_mfma_f32_16x16x32_bf16 v[2:5], v[168:171], v[236:239], v[2:5]
	v_mfma_f32_16x16x32_bf16 v[54:57], v[150:153], v[180:183], v[54:57]
	v_mfma_f32_16x16x32_bf16 v[50:53], v[172:175], v[180:183], v[50:53]
	v_mfma_f32_16x16x32_bf16 v[38:41], v[150:153], v[206:209], v[38:41]
	v_mfma_f32_16x16x32_bf16 v[34:37], v[172:175], v[206:209], v[34:37]
	v_mfma_f32_16x16x32_bf16 v[22:25], v[150:153], v[232:235], v[22:25]
	v_mfma_f32_16x16x32_bf16 v[18:21], v[172:175], v[232:235], v[18:21]
	v_mfma_f32_16x16x32_bf16 v[6:9], v[150:153], v[240:243], v[6:9]
	v_mfma_f32_16x16x32_bf16 v[2:5], v[172:175], v[240:243], v[2:5]
	s_setprio 0
	s_barrier
	s_add_i32 s49, s49, 2
	s_add_u32 s47, s47, 0x100
	s_addc_u32 s48, s48, 0
	s_cmp_gt_u32 s49, 41
	s_mov_b64 s[18:19], s[20:21]
	s_cbranch_scc0 .LBB0_1438
	s_and_b64 vcc, exec, s[14:15]
	s_cbranch_vccz .LBB0_1441
	s_barrier
